# A/B: hipcc's per-phase s_setprio 1/0 flips around the MFMA clusters of the GEMM K-loops deleted (160 instructions); the one static raise in ATTN kept
# speedup vs baseline: 1.0093x; 1.0093x over previous
.LBB0_191:
	ds_read_b128 v[48:51], v147
	ds_read_b128 v[132:135], v147 offset:1024
	ds_read_b128 v[162:165], v147 offset:2048
	ds_read_b128 v[166:169], v147 offset:3072
	s_add_u32 s34, s8, 0x100
	s_addc_u32 s35, s9, 0
	s_cmp_eq_u32 s70, 12
	s_cselect_b32 s39, s62, s35
	s_cselect_b32 s38, s63, s34
	s_cselect_b32 s37, s15, s69
	s_cselect_b32 s36, s67, s68
	s_mov_b32 m0, s57
	v_lshl_add_u64 v[186:187], s[8:9], 0, v[150:151]
	ds_read_b128 v[170:173], v159
	ds_read_b128 v[174:177], v159 offset:1024
	ds_read_b128 v[178:181], v159 offset:2048
	ds_read_b128 v[182:185], v159 offset:3072
	ds_read_b128 v[190:193], v159 offset:4096
	ds_read_b128 v[194:197], v159 offset:5120
	ds_read_b128 v[198:201], v159 offset:6144
	ds_read_b128 v[202:205], v159 offset:7168
	global_load_lds_dwordx4 v[186:187], off
	v_lshl_add_u64 v[186:187], s[8:9], 0, v[152:153]
	s_mov_b32 m0, s58
	s_nop 0
	global_load_lds_dwordx4 v[186:187], off
	s_waitcnt lgkmcnt(8)
	s_barrier
	s_waitcnt lgkmcnt(0)
	s_waitcnt lgkmcnt(0)
	v_mfma_f32_16x16x32_bf16 v[72:75], v[48:51], v[170:173], v[72:75]
	v_mfma_f32_16x16x32_bf16 v[28:31], v[162:165], v[170:173], v[28:31]
	v_mfma_f32_16x16x32_bf16 v[64:67], v[48:51], v[178:181], v[64:67]
	v_mfma_f32_16x16x32_bf16 v[24:27], v[162:165], v[178:181], v[24:27]
	v_mfma_f32_16x16x32_bf16 v[128:131], v[48:51], v[190:193], v[128:131]
	v_mfma_f32_16x16x32_bf16 v[124:127], v[162:165], v[190:193], v[124:127]
	v_mfma_f32_16x16x32_bf16 v[120:123], v[48:51], v[198:201], v[120:123]
	v_mfma_f32_16x16x32_bf16 v[116:119], v[162:165], v[198:201], v[116:119]
	v_mfma_f32_16x16x32_bf16 v[72:75], v[132:135], v[174:177], v[72:75]
	v_mfma_f32_16x16x32_bf16 v[28:31], v[166:169], v[174:177], v[28:31]
	v_mfma_f32_16x16x32_bf16 v[64:67], v[132:135], v[182:185], v[64:67]
	v_mfma_f32_16x16x32_bf16 v[24:27], v[166:169], v[182:185], v[24:27]
	v_mfma_f32_16x16x32_bf16 v[128:131], v[132:135], v[194:197], v[128:131]
	v_mfma_f32_16x16x32_bf16 v[124:127], v[166:169], v[194:197], v[124:127]
	v_mfma_f32_16x16x32_bf16 v[120:123], v[132:135], v[202:205], v[120:123]
	v_mfma_f32_16x16x32_bf16 v[116:119], v[166:169], v[202:205], v[116:119]
	s_barrier
	s_add_i32 s8, s54, s43
	v_lshl_add_u64 v[186:187], s[36:37], 0, v[138:139]
	s_mov_b32 m0, s8
	ds_read_b128 v[206:209], v160
	ds_read_b128 v[210:213], v160 offset:1024
	ds_read_b128 v[214:217], v160 offset:2048
	ds_read_b128 v[218:221], v160 offset:3072
	global_load_lds_dwordx4 v[186:187], off
	v_lshl_add_u64 v[222:223], s[36:37], 0, v[142:143]
	s_add_i32 m0, s8, 0x2000
	s_nop 0
	global_load_lds_dwordx4 v[222:223], off
	s_barrier
	s_waitcnt lgkmcnt(0)
	s_waitcnt lgkmcnt(0)
	v_mfma_f32_16x16x32_bf16 v[56:59], v[206:209], v[170:173], v[56:59]
	v_mfma_f32_16x16x32_bf16 v[20:23], v[214:217], v[170:173], v[20:23]
	v_mfma_f32_16x16x32_bf16 v[52:55], v[206:209], v[178:181], v[52:55]
	v_mfma_f32_16x16x32_bf16 v[16:19], v[214:217], v[178:181], v[16:19]
	v_mfma_f32_16x16x32_bf16 v[112:115], v[206:209], v[190:193], v[112:115]
	v_mfma_f32_16x16x32_bf16 v[108:111], v[214:217], v[190:193], v[108:111]
	v_mfma_f32_16x16x32_bf16 v[104:107], v[206:209], v[198:201], v[104:107]
	v_mfma_f32_16x16x32_bf16 v[100:103], v[214:217], v[198:201], v[100:103]
	v_mfma_f32_16x16x32_bf16 v[56:59], v[210:213], v[174:177], v[56:59]
	v_mfma_f32_16x16x32_bf16 v[20:23], v[218:221], v[174:177], v[20:23]
	v_mfma_f32_16x16x32_bf16 v[52:55], v[210:213], v[182:185], v[52:55]
	v_mfma_f32_16x16x32_bf16 v[16:19], v[218:221], v[182:185], v[16:19]
	v_mfma_f32_16x16x32_bf16 v[112:115], v[210:213], v[194:197], v[112:115]
	v_mfma_f32_16x16x32_bf16 v[108:111], v[218:221], v[194:197], v[108:111]
	v_mfma_f32_16x16x32_bf16 v[104:107], v[210:213], v[202:205], v[104:107]
	v_mfma_f32_16x16x32_bf16 v[100:103], v[218:221], v[202:205], v[100:103]
	s_mov_b32 m0, s44
	v_lshl_add_u64 v[224:225], s[38:39], 0, v[136:137]
	s_barrier
	ds_read_b128 v[170:173], v159 offset:16384
	ds_read_b128 v[174:177], v159 offset:17408
	ds_read_b128 v[178:181], v159 offset:18432
	ds_read_b128 v[182:185], v159 offset:19456
	ds_read_b128 v[190:193], v159 offset:20480
	ds_read_b128 v[194:197], v159 offset:21504
	ds_read_b128 v[198:201], v159 offset:22528
	ds_read_b128 v[202:205], v159 offset:23552
	global_load_lds_dwordx4 v[224:225], off
	v_lshl_add_u64 v[226:227], s[38:39], 0, v[140:141]
	s_mov_b32 m0, s45
	s_nop 0
	global_load_lds_dwordx4 v[226:227], off
	s_barrier
	s_waitcnt lgkmcnt(0)
	s_waitcnt lgkmcnt(0)
	v_mfma_f32_16x16x32_bf16 v[44:47], v[48:51], v[170:173], v[44:47]
	v_mfma_f32_16x16x32_bf16 v[12:15], v[162:165], v[170:173], v[12:15]
	v_mfma_f32_16x16x32_bf16 v[40:43], v[48:51], v[178:181], v[40:43]
	v_mfma_f32_16x16x32_bf16 v[8:11], v[162:165], v[178:181], v[8:11]
	v_mfma_f32_16x16x32_bf16 v[96:99], v[48:51], v[190:193], v[96:99]
	v_mfma_f32_16x16x32_bf16 v[92:95], v[162:165], v[190:193], v[92:95]
	v_mfma_f32_16x16x32_bf16 v[76:79], v[162:165], v[198:201], v[76:79]
	v_mfma_f32_16x16x32_bf16 v[44:47], v[132:135], v[174:177], v[44:47]
	v_mfma_f32_16x16x32_bf16 v[12:15], v[166:169], v[174:177], v[12:15]
	v_mfma_f32_16x16x32_bf16 v[40:43], v[132:135], v[182:185], v[40:43]
	v_mfma_f32_16x16x32_bf16 v[8:11], v[166:169], v[182:185], v[8:11]
	v_mfma_f32_16x16x32_bf16 v[96:99], v[132:135], v[194:197], v[96:99]
	v_mfma_f32_16x16x32_bf16 v[92:95], v[166:169], v[194:197], v[92:95]
	v_mfma_f32_16x16x32_bf16 v[48:51], v[48:51], v[198:201], v[84:87]
	v_mfma_f32_16x16x32_bf16 v[76:79], v[166:169], v[202:205], v[76:79]
	v_mfma_f32_16x16x32_bf16 v[48:51], v[132:135], v[202:205], v[48:51]
	s_barrier
	s_add_u32 s8, s36, 0x40000
	s_addc_u32 s9, s37, 0
	s_add_i32 s71, s55, s43
	v_lshl_add_u64 v[84:85], s[8:9], 0, v[138:139]
	s_mov_b32 m0, s71
	s_nop 0
	global_load_lds_dwordx4 v[84:85], off
	v_lshl_add_u64 v[84:85], s[8:9], 0, v[142:143]
	s_add_i32 m0, s71, 0x2000
	s_nop 0
	global_load_lds_dwordx4 v[84:85], off
	s_waitcnt vmcnt(6)
	s_barrier
	v_mfma_f32_16x16x32_bf16 v[36:39], v[206:209], v[170:173], v[36:39]
	v_mfma_f32_16x16x32_bf16 v[4:7], v[214:217], v[170:173], v[4:7]
	v_mfma_f32_16x16x32_bf16 v[32:35], v[206:209], v[178:181], v[32:35]
	v_mfma_f32_16x16x32_bf16 v[0:3], v[214:217], v[178:181], v[0:3]
	v_mfma_f32_16x16x32_bf16 v[84:87], v[206:209], v[190:193], v[88:91]
	v_mfma_f32_16x16x32_bf16 v[80:83], v[214:217], v[190:193], v[80:83]
	v_mfma_f32_16x16x32_bf16 v[68:71], v[206:209], v[198:201], v[68:71]
	v_mfma_f32_16x16x32_bf16 v[60:63], v[214:217], v[198:201], v[60:63]
	v_mfma_f32_16x16x32_bf16 v[36:39], v[210:213], v[174:177], v[36:39]
	v_mfma_f32_16x16x32_bf16 v[4:7], v[218:221], v[174:177], v[4:7]
	v_mfma_f32_16x16x32_bf16 v[32:35], v[210:213], v[182:185], v[32:35]
	v_mfma_f32_16x16x32_bf16 v[0:3], v[218:221], v[182:185], v[0:3]
	v_mfma_f32_16x16x32_bf16 v[88:91], v[210:213], v[194:197], v[84:87]
	v_mfma_f32_16x16x32_bf16 v[80:83], v[218:221], v[194:197], v[80:83]
	v_mfma_f32_16x16x32_bf16 v[68:71], v[210:213], v[202:205], v[68:71]
	v_mfma_f32_16x16x32_bf16 v[60:63], v[218:221], v[202:205], v[60:63]
	s_add_i32 s71, 0, 0x18000
	v_add_u32_e32 v166, s71, v156
	s_barrier
	ds_read_b128 v[84:87], v166
	ds_read_b128 v[132:135], v166 offset:1024
	ds_read_b128 v[162:165], v166 offset:2048
	ds_read_b128 v[166:169], v166 offset:3072
	s_add_u32 s8, s38, 0x40000
	s_addc_u32 s9, s39, 0
	s_mov_b32 m0, s46
	v_lshl_add_u64 v[206:207], s[8:9], 0, v[136:137]
	ds_read_b128 v[170:173], v159 offset:32768
	ds_read_b128 v[174:177], v159 offset:33792
	ds_read_b128 v[178:181], v159 offset:34816
	ds_read_b128 v[182:185], v159 offset:35840
	ds_read_b128 v[190:193], v159 offset:36864
	ds_read_b128 v[194:197], v159 offset:37888
	ds_read_b128 v[198:201], v159 offset:38912
	ds_read_b128 v[202:205], v159 offset:39936
	global_load_lds_dwordx4 v[206:207], off
	v_lshl_add_u64 v[206:207], s[8:9], 0, v[140:141]
	s_mov_b32 m0, s47
	s_nop 0
	global_load_lds_dwordx4 v[206:207], off
	s_waitcnt lgkmcnt(8)
	s_barrier
	s_waitcnt lgkmcnt(0)
	s_waitcnt lgkmcnt(0)
	v_mfma_f32_16x16x32_bf16 v[72:75], v[84:87], v[170:173], v[72:75]
	v_mfma_f32_16x16x32_bf16 v[28:31], v[162:165], v[170:173], v[28:31]
	v_mfma_f32_16x16x32_bf16 v[64:67], v[84:87], v[178:181], v[64:67]
	v_mfma_f32_16x16x32_bf16 v[24:27], v[162:165], v[178:181], v[24:27]
	v_mfma_f32_16x16x32_bf16 v[128:131], v[84:87], v[190:193], v[128:131]
	v_mfma_f32_16x16x32_bf16 v[124:127], v[162:165], v[190:193], v[124:127]
	v_mfma_f32_16x16x32_bf16 v[120:123], v[84:87], v[198:201], v[120:123]
	v_mfma_f32_16x16x32_bf16 v[116:119], v[162:165], v[198:201], v[116:119]
	v_mfma_f32_16x16x32_bf16 v[72:75], v[132:135], v[174:177], v[72:75]
	v_mfma_f32_16x16x32_bf16 v[28:31], v[166:169], v[174:177], v[28:31]
	v_mfma_f32_16x16x32_bf16 v[64:67], v[132:135], v[182:185], v[64:67]
	v_mfma_f32_16x16x32_bf16 v[24:27], v[166:169], v[182:185], v[24:27]
	v_mfma_f32_16x16x32_bf16 v[128:131], v[132:135], v[194:197], v[128:131]
	v_mfma_f32_16x16x32_bf16 v[124:127], v[166:169], v[194:197], v[124:127]
	v_mfma_f32_16x16x32_bf16 v[120:123], v[132:135], v[202:205], v[120:123]
	v_mfma_f32_16x16x32_bf16 v[116:119], v[166:169], v[202:205], v[116:119]
	s_barrier
	s_add_i32 s38, 0, 0x1c000
	s_add_i32 s8, s71, s43
	v_add_u32_e32 v189, s38, v156
	v_lshl_add_u64 v[186:187], v[186:187], 0, s[24:25]
	s_mov_b32 m0, s8
	ds_read_b128 v[206:209], v189
	ds_read_b128 v[210:213], v189 offset:1024
	ds_read_b128 v[214:217], v189 offset:2048
	ds_read_b128 v[218:221], v189 offset:3072
	global_load_lds_dwordx4 v[186:187], off
	v_lshl_add_u64 v[186:187], v[222:223], 0, s[24:25]
	s_add_i32 m0, s8, 0x2000
	s_nop 0
	global_load_lds_dwordx4 v[186:187], off
	s_barrier
	s_waitcnt lgkmcnt(0)
	s_waitcnt lgkmcnt(0)
	v_mfma_f32_16x16x32_bf16 v[56:59], v[206:209], v[170:173], v[56:59]
	v_mfma_f32_16x16x32_bf16 v[20:23], v[214:217], v[170:173], v[20:23]
	v_mfma_f32_16x16x32_bf16 v[52:55], v[206:209], v[178:181], v[52:55]
	v_mfma_f32_16x16x32_bf16 v[16:19], v[214:217], v[178:181], v[16:19]
	v_mfma_f32_16x16x32_bf16 v[112:115], v[206:209], v[190:193], v[112:115]
	v_mfma_f32_16x16x32_bf16 v[108:111], v[214:217], v[190:193], v[108:111]
	v_mfma_f32_16x16x32_bf16 v[104:107], v[206:209], v[198:201], v[104:107]
	v_mfma_f32_16x16x32_bf16 v[100:103], v[214:217], v[198:201], v[100:103]
	v_mfma_f32_16x16x32_bf16 v[56:59], v[210:213], v[174:177], v[56:59]
	v_mfma_f32_16x16x32_bf16 v[20:23], v[218:221], v[174:177], v[20:23]
	v_mfma_f32_16x16x32_bf16 v[52:55], v[210:213], v[182:185], v[52:55]
	v_mfma_f32_16x16x32_bf16 v[16:19], v[218:221], v[182:185], v[16:19]
	v_mfma_f32_16x16x32_bf16 v[112:115], v[210:213], v[194:197], v[112:115]
	v_mfma_f32_16x16x32_bf16 v[108:111], v[218:221], v[194:197], v[108:111]
	v_mfma_f32_16x16x32_bf16 v[104:107], v[210:213], v[202:205], v[104:107]
	v_mfma_f32_16x16x32_bf16 v[100:103], v[218:221], v[202:205], v[100:103]
	s_mov_b32 m0, s50
	v_lshl_add_u64 v[186:187], v[224:225], 0, s[24:25]
	s_barrier
	ds_read_b128 v[170:173], v159 offset:49152
	ds_read_b128 v[174:177], v159 offset:50176
	ds_read_b128 v[178:181], v159 offset:51200
	ds_read_b128 v[182:185], v159 offset:52224
	ds_read_b128 v[190:193], v159 offset:53248
	ds_read_b128 v[194:197], v159 offset:54272
	ds_read_b128 v[198:201], v159 offset:55296
	ds_read_b128 v[202:205], v159 offset:56320
	global_load_lds_dwordx4 v[186:187], off
	v_lshl_add_u64 v[186:187], v[226:227], 0, s[24:25]
	s_mov_b32 m0, s51
	s_nop 0
	global_load_lds_dwordx4 v[186:187], off
	s_barrier
	s_waitcnt lgkmcnt(0)
	s_waitcnt lgkmcnt(0)
	v_mfma_f32_16x16x32_bf16 v[48:51], v[84:87], v[198:201], v[48:51]
	v_mfma_f32_16x16x32_bf16 v[44:47], v[84:87], v[170:173], v[44:47]
	v_mfma_f32_16x16x32_bf16 v[12:15], v[162:165], v[170:173], v[12:15]
	v_mfma_f32_16x16x32_bf16 v[40:43], v[84:87], v[178:181], v[40:43]
	v_mfma_f32_16x16x32_bf16 v[8:11], v[162:165], v[178:181], v[8:11]
	v_mfma_f32_16x16x32_bf16 v[96:99], v[84:87], v[190:193], v[96:99]
	v_mfma_f32_16x16x32_bf16 v[92:95], v[162:165], v[190:193], v[92:95]
	v_mfma_f32_16x16x32_bf16 v[84:87], v[132:135], v[202:205], v[48:51]
	v_mfma_f32_16x16x32_bf16 v[48:51], v[162:165], v[198:201], v[76:79]
	v_mfma_f32_16x16x32_bf16 v[44:47], v[132:135], v[174:177], v[44:47]
	v_mfma_f32_16x16x32_bf16 v[12:15], v[166:169], v[174:177], v[12:15]
	v_mfma_f32_16x16x32_bf16 v[40:43], v[132:135], v[182:185], v[40:43]
	v_mfma_f32_16x16x32_bf16 v[8:11], v[166:169], v[182:185], v[8:11]
	v_mfma_f32_16x16x32_bf16 v[96:99], v[132:135], v[194:197], v[96:99]
	v_mfma_f32_16x16x32_bf16 v[92:95], v[166:169], v[194:197], v[92:95]
	v_mfma_f32_16x16x32_bf16 v[76:79], v[166:169], v[202:205], v[48:51]
	s_barrier
	s_add_u32 s8, s36, 0x40080
	s_addc_u32 s9, s37, 0
	s_add_i32 s36, s38, s43
	v_lshl_add_u64 v[48:49], s[8:9], 0, v[138:139]
	s_mov_b32 m0, s36
	s_nop 0
	global_load_lds_dwordx4 v[48:49], off
	v_lshl_add_u64 v[48:49], s[8:9], 0, v[142:143]
	s_add_i32 m0, s36, 0x2000
	s_nop 0
	global_load_lds_dwordx4 v[48:49], off
	s_waitcnt vmcnt(6)
	s_barrier
	v_mfma_f32_16x16x32_bf16 v[48:51], v[206:209], v[190:193], v[88:91]
	v_mfma_f32_16x16x32_bf16 v[88:91], v[210:213], v[194:197], v[48:51]
	v_mfma_f32_16x16x32_bf16 v[48:51], v[214:217], v[190:193], v[80:83]
	v_mfma_f32_16x16x32_bf16 v[80:83], v[218:221], v[194:197], v[48:51]
	v_mfma_f32_16x16x32_bf16 v[48:51], v[206:209], v[198:201], v[68:71]
	v_mfma_f32_16x16x32_bf16 v[36:39], v[206:209], v[170:173], v[36:39]
	v_mfma_f32_16x16x32_bf16 v[4:7], v[214:217], v[170:173], v[4:7]
	v_mfma_f32_16x16x32_bf16 v[32:35], v[206:209], v[178:181], v[32:35]
	v_mfma_f32_16x16x32_bf16 v[0:3], v[214:217], v[178:181], v[0:3]
	v_mfma_f32_16x16x32_bf16 v[68:71], v[210:213], v[202:205], v[48:51]
	v_mfma_f32_16x16x32_bf16 v[48:51], v[214:217], v[198:201], v[60:63]
	v_mfma_f32_16x16x32_bf16 v[36:39], v[210:213], v[174:177], v[36:39]
	v_mfma_f32_16x16x32_bf16 v[4:7], v[218:221], v[174:177], v[4:7]
	v_mfma_f32_16x16x32_bf16 v[32:35], v[210:213], v[182:185], v[32:35]
	v_mfma_f32_16x16x32_bf16 v[0:3], v[218:221], v[182:185], v[0:3]
	v_mfma_f32_16x16x32_bf16 v[60:63], v[218:221], v[202:205], v[48:51]
	s_add_i32 s70, s70, 2
	s_add_u32 s68, s68, 0x100
	s_addc_u32 s69, s69, 0
	s_cmp_gt_u32 s70, 13
	s_mov_b64 s[8:9], s[34:35]
	s_barrier
	s_cbranch_scc0 .LBB0_191
	v_cndmask_b32_e64 v48, 0, 1, s[30:31]
	v_cmp_ne_u32_e64 s[8:9], 1, v48
	s_andn2_b64 vcc, exec, s[30:31]
	s_cbranch_vccnz .LBB0_196
	v_mov_b32_e32 v48, 0
	v_mov_b32_e32 v49, 0
	v_mov_b32_e32 v50, 0
	v_mov_b32_e32 v51, 0
	s_and_saveexec_b64 s[30:31], s[2:3]
	s_cbranch_execz .LBB0_195
	s_lshl_b32 s34, s14, 7
	s_ashr_i32 s35, s34, 31
	v_lshl_add_u64 v[48:49], s[34:35], 2, v[148:149]
	global_load_dwordx4 v[48:51], v[48:49], off

.LBB0_286:
	ds_read_b128 v[128:131], v162
	ds_read_b128 v[148:151], v162 offset:1024
	ds_read_b128 v[152:155], v162 offset:2048
	ds_read_b128 v[166:169], v162 offset:3072
	s_add_u32 s36, s34, 0xfffc0080
	s_addc_u32 s37, s35, -1
	s_cmp_eq_u32 s59, 12
	s_cselect_b32 s39, s23, s37
	s_cselect_b32 s38, s55, s36
	s_cselect_b32 s37, s21, s58
	s_cselect_b32 s36, s56, s57
	v_lshl_add_u64 v[156:157], s[34:35], 0, v[140:141]
	s_add_i32 m0, s31, 0xc000
	ds_read_b128 v[170:173], v163
	ds_read_b128 v[174:177], v163 offset:1024
	ds_read_b128 v[178:181], v163 offset:2048
	ds_read_b128 v[182:185], v163 offset:3072
	ds_read_b128 v[190:193], v163 offset:4096
	ds_read_b128 v[194:197], v163 offset:5120
	ds_read_b128 v[198:201], v163 offset:6144
	ds_read_b128 v[202:205], v163 offset:7168
	global_load_lds_dwordx4 v[156:157], off
	v_lshl_add_u64 v[156:157], s[34:35], 0, v[142:143]
	s_add_i32 m0, s31, 0xe000
	s_nop 0
	global_load_lds_dwordx4 v[156:157], off
	s_waitcnt lgkmcnt(8)
	s_barrier
	s_waitcnt lgkmcnt(0)
	s_waitcnt lgkmcnt(0)
	v_mfma_f32_16x16x32_bf16 v[124:127], v[128:131], v[170:173], v[124:127]
	v_mfma_f32_16x16x32_bf16 v[120:123], v[152:155], v[170:173], v[120:123]
	v_mfma_f32_16x16x32_bf16 v[108:111], v[128:131], v[178:181], v[108:111]
	v_mfma_f32_16x16x32_bf16 v[104:107], v[152:155], v[178:181], v[104:107]
	v_mfma_f32_16x16x32_bf16 v[92:95], v[128:131], v[190:193], v[92:95]
	v_mfma_f32_16x16x32_bf16 v[88:91], v[152:155], v[190:193], v[88:91]
	v_mfma_f32_16x16x32_bf16 v[76:79], v[128:131], v[198:201], v[76:79]
	v_mfma_f32_16x16x32_bf16 v[72:75], v[152:155], v[198:201], v[72:75]
	v_mfma_f32_16x16x32_bf16 v[124:127], v[148:151], v[174:177], v[124:127]
	v_mfma_f32_16x16x32_bf16 v[120:123], v[166:169], v[174:177], v[120:123]
	v_mfma_f32_16x16x32_bf16 v[108:111], v[148:151], v[182:185], v[108:111]
	v_mfma_f32_16x16x32_bf16 v[104:107], v[166:169], v[182:185], v[104:107]
	v_mfma_f32_16x16x32_bf16 v[92:95], v[148:151], v[194:197], v[92:95]
	v_mfma_f32_16x16x32_bf16 v[88:91], v[166:169], v[194:197], v[88:91]
	v_mfma_f32_16x16x32_bf16 v[76:79], v[148:151], v[202:205], v[76:79]
	v_mfma_f32_16x16x32_bf16 v[72:75], v[166:169], v[202:205], v[72:75]
	s_barrier
	s_add_i32 s60, s52, s44
	v_lshl_add_u64 v[156:157], s[36:37], 0, v[134:135]
	s_mov_b32 m0, s60
	ds_read_b128 v[206:209], v164
	ds_read_b128 v[210:213], v164 offset:1024
	ds_read_b128 v[214:217], v164 offset:2048
	ds_read_b128 v[218:221], v164 offset:3072
	global_load_lds_dwordx4 v[156:157], off
	v_lshl_add_u64 v[186:187], s[36:37], 0, v[138:139]
	s_add_i32 m0, s60, 0x2000
	s_nop 0
	global_load_lds_dwordx4 v[186:187], off
	s_barrier
	s_waitcnt lgkmcnt(0)
	s_waitcnt lgkmcnt(0)
	v_mfma_f32_16x16x32_bf16 v[116:119], v[206:209], v[170:173], v[116:119]
	v_mfma_f32_16x16x32_bf16 v[112:115], v[214:217], v[170:173], v[112:115]
	v_mfma_f32_16x16x32_bf16 v[100:103], v[206:209], v[178:181], v[100:103]
	v_mfma_f32_16x16x32_bf16 v[96:99], v[214:217], v[178:181], v[96:99]
	v_mfma_f32_16x16x32_bf16 v[84:87], v[206:209], v[190:193], v[84:87]
	v_mfma_f32_16x16x32_bf16 v[80:83], v[214:217], v[190:193], v[80:83]
	v_mfma_f32_16x16x32_bf16 v[68:71], v[206:209], v[198:201], v[68:71]
	v_mfma_f32_16x16x32_bf16 v[64:67], v[214:217], v[198:201], v[64:67]
	v_mfma_f32_16x16x32_bf16 v[116:119], v[210:213], v[174:177], v[116:119]
	v_mfma_f32_16x16x32_bf16 v[112:115], v[218:221], v[174:177], v[112:115]
	v_mfma_f32_16x16x32_bf16 v[100:103], v[210:213], v[182:185], v[100:103]
	v_mfma_f32_16x16x32_bf16 v[96:99], v[218:221], v[182:185], v[96:99]
	v_mfma_f32_16x16x32_bf16 v[84:87], v[210:213], v[194:197], v[84:87]
	v_mfma_f32_16x16x32_bf16 v[80:83], v[218:221], v[194:197], v[80:83]
	v_mfma_f32_16x16x32_bf16 v[68:71], v[210:213], v[202:205], v[68:71]
	v_mfma_f32_16x16x32_bf16 v[64:67], v[218:221], v[202:205], v[64:67]
	s_mov_b32 m0, s31
	v_lshl_add_u64 v[222:223], s[38:39], 0, v[132:133]
	s_barrier
	ds_read_b128 v[170:173], v163 offset:16384
	ds_read_b128 v[174:177], v163 offset:17408
	ds_read_b128 v[178:181], v163 offset:18432
	ds_read_b128 v[182:185], v163 offset:19456
	ds_read_b128 v[190:193], v163 offset:20480
	ds_read_b128 v[194:197], v163 offset:21504
	ds_read_b128 v[198:201], v163 offset:22528
	ds_read_b128 v[202:205], v163 offset:23552
	global_load_lds_dwordx4 v[222:223], off
	v_lshl_add_u64 v[224:225], s[38:39], 0, v[136:137]
	s_mov_b32 m0, s45
	s_nop 0
	global_load_lds_dwordx4 v[224:225], off
	s_barrier
	s_waitcnt lgkmcnt(0)
	s_waitcnt lgkmcnt(0)
	v_mfma_f32_16x16x32_bf16 v[60:63], v[128:131], v[170:173], v[60:63]
	v_mfma_f32_16x16x32_bf16 v[56:59], v[152:155], v[170:173], v[56:59]
	v_mfma_f32_16x16x32_bf16 v[44:47], v[128:131], v[178:181], v[44:47]
	v_mfma_f32_16x16x32_bf16 v[40:43], v[152:155], v[178:181], v[40:43]
	v_mfma_f32_16x16x32_bf16 v[28:31], v[128:131], v[190:193], v[28:31]
	v_mfma_f32_16x16x32_bf16 v[24:27], v[152:155], v[190:193], v[24:27]
	v_mfma_f32_16x16x32_bf16 v[12:15], v[128:131], v[198:201], v[12:15]
	v_mfma_f32_16x16x32_bf16 v[8:11], v[152:155], v[198:201], v[8:11]
	v_mfma_f32_16x16x32_bf16 v[60:63], v[148:151], v[174:177], v[60:63]
	v_mfma_f32_16x16x32_bf16 v[56:59], v[166:169], v[174:177], v[56:59]
	v_mfma_f32_16x16x32_bf16 v[44:47], v[148:151], v[182:185], v[44:47]
	v_mfma_f32_16x16x32_bf16 v[40:43], v[166:169], v[182:185], v[40:43]
	v_mfma_f32_16x16x32_bf16 v[28:31], v[148:151], v[194:197], v[28:31]
	v_mfma_f32_16x16x32_bf16 v[24:27], v[166:169], v[194:197], v[24:27]
	v_mfma_f32_16x16x32_bf16 v[12:15], v[148:151], v[202:205], v[12:15]
	v_mfma_f32_16x16x32_bf16 v[8:11], v[166:169], v[202:205], v[8:11]
	s_barrier
	s_add_u32 s60, s36, 0x40000
	s_addc_u32 s61, s37, 0
	s_add_i32 s62, s53, s44
	v_lshl_add_u64 v[128:129], s[60:61], 0, v[134:135]
	s_mov_b32 m0, s62
	s_nop 0
	global_load_lds_dwordx4 v[128:129], off
	v_lshl_add_u64 v[128:129], s[60:61], 0, v[138:139]
	s_add_i32 m0, s62, 0x2000
	s_nop 0
	global_load_lds_dwordx4 v[128:129], off
	s_waitcnt vmcnt(6)
	s_barrier
	v_mfma_f32_16x16x32_bf16 v[52:55], v[206:209], v[170:173], v[52:55]
	v_mfma_f32_16x16x32_bf16 v[48:51], v[214:217], v[170:173], v[48:51]
	v_mfma_f32_16x16x32_bf16 v[36:39], v[206:209], v[178:181], v[36:39]
	v_mfma_f32_16x16x32_bf16 v[32:35], v[214:217], v[178:181], v[32:35]
	v_mfma_f32_16x16x32_bf16 v[20:23], v[206:209], v[190:193], v[20:23]
	v_mfma_f32_16x16x32_bf16 v[16:19], v[214:217], v[190:193], v[16:19]
	v_mfma_f32_16x16x32_bf16 v[4:7], v[206:209], v[198:201], v[4:7]
	v_mfma_f32_16x16x32_bf16 v[0:3], v[214:217], v[198:201], v[0:3]
	v_mfma_f32_16x16x32_bf16 v[52:55], v[210:213], v[174:177], v[52:55]
	v_mfma_f32_16x16x32_bf16 v[48:51], v[218:221], v[174:177], v[48:51]
	v_mfma_f32_16x16x32_bf16 v[36:39], v[210:213], v[182:185], v[36:39]
	v_mfma_f32_16x16x32_bf16 v[32:35], v[218:221], v[182:185], v[32:35]
	v_mfma_f32_16x16x32_bf16 v[20:23], v[210:213], v[194:197], v[20:23]
	v_mfma_f32_16x16x32_bf16 v[16:19], v[218:221], v[194:197], v[16:19]
	v_mfma_f32_16x16x32_bf16 v[4:7], v[210:213], v[202:205], v[4:7]
	v_mfma_f32_16x16x32_bf16 v[0:3], v[218:221], v[202:205], v[0:3]
	s_add_i32 s60, 0, 0x18000
	v_add_u32_e32 v158, s60, v160
	s_barrier
	ds_read_b128 v[128:131], v158
	ds_read_b128 v[148:151], v158 offset:1024
	ds_read_b128 v[152:155], v158 offset:2048
	ds_read_b128 v[166:169], v158 offset:3072
	s_add_u32 s38, s38, 0x40000
	s_addc_u32 s39, s39, 0
	s_mov_b32 m0, s46
	v_lshl_add_u64 v[206:207], s[38:39], 0, v[132:133]
	ds_read_b128 v[170:173], v163 offset:32768
	ds_read_b128 v[174:177], v163 offset:33792
	ds_read_b128 v[178:181], v163 offset:34816
	ds_read_b128 v[182:185], v163 offset:35840
	ds_read_b128 v[190:193], v163 offset:36864
	ds_read_b128 v[194:197], v163 offset:37888
	ds_read_b128 v[198:201], v163 offset:38912
	ds_read_b128 v[202:205], v163 offset:39936
	global_load_lds_dwordx4 v[206:207], off
	v_lshl_add_u64 v[206:207], s[38:39], 0, v[136:137]
	s_mov_b32 m0, s47
	s_nop 0
	global_load_lds_dwordx4 v[206:207], off
	s_waitcnt lgkmcnt(8)
	s_barrier
	s_waitcnt lgkmcnt(0)
	s_waitcnt lgkmcnt(0)
	v_mfma_f32_16x16x32_bf16 v[124:127], v[128:131], v[170:173], v[124:127]
	v_mfma_f32_16x16x32_bf16 v[120:123], v[152:155], v[170:173], v[120:123]
	v_mfma_f32_16x16x32_bf16 v[108:111], v[128:131], v[178:181], v[108:111]
	v_mfma_f32_16x16x32_bf16 v[104:107], v[152:155], v[178:181], v[104:107]
	v_mfma_f32_16x16x32_bf16 v[92:95], v[128:131], v[190:193], v[92:95]
	v_mfma_f32_16x16x32_bf16 v[88:91], v[152:155], v[190:193], v[88:91]
	v_mfma_f32_16x16x32_bf16 v[76:79], v[128:131], v[198:201], v[76:79]
	v_mfma_f32_16x16x32_bf16 v[72:75], v[152:155], v[198:201], v[72:75]
	v_mfma_f32_16x16x32_bf16 v[124:127], v[148:151], v[174:177], v[124:127]
	v_mfma_f32_16x16x32_bf16 v[120:123], v[166:169], v[174:177], v[120:123]
	v_mfma_f32_16x16x32_bf16 v[108:111], v[148:151], v[182:185], v[108:111]
	v_mfma_f32_16x16x32_bf16 v[104:107], v[166:169], v[182:185], v[104:107]
	v_mfma_f32_16x16x32_bf16 v[92:95], v[148:151], v[194:197], v[92:95]
	v_mfma_f32_16x16x32_bf16 v[88:91], v[166:169], v[194:197], v[88:91]
	v_mfma_f32_16x16x32_bf16 v[76:79], v[148:151], v[202:205], v[76:79]
	v_mfma_f32_16x16x32_bf16 v[72:75], v[166:169], v[202:205], v[72:75]
	s_barrier
	s_add_i32 s38, 0, 0x1c000
	s_add_i32 s39, s60, s44
	v_add_u32_e32 v158, s38, v160
	v_lshl_add_u64 v[156:157], v[156:157], 0, s[8:9]
	s_mov_b32 m0, s39
	ds_read_b128 v[206:209], v158
	ds_read_b128 v[210:213], v158 offset:1024
	ds_read_b128 v[214:217], v158 offset:2048
	ds_read_b128 v[218:221], v158 offset:3072
	global_load_lds_dwordx4 v[156:157], off
	v_lshl_add_u64 v[156:157], v[186:187], 0, s[8:9]
	s_add_i32 m0, s39, 0x2000
	s_nop 0
	global_load_lds_dwordx4 v[156:157], off
	s_barrier
	s_waitcnt lgkmcnt(0)
	s_waitcnt lgkmcnt(0)
	v_mfma_f32_16x16x32_bf16 v[116:119], v[206:209], v[170:173], v[116:119]
	v_mfma_f32_16x16x32_bf16 v[112:115], v[214:217], v[170:173], v[112:115]
	v_mfma_f32_16x16x32_bf16 v[100:103], v[206:209], v[178:181], v[100:103]
	v_mfma_f32_16x16x32_bf16 v[96:99], v[214:217], v[178:181], v[96:99]
	v_mfma_f32_16x16x32_bf16 v[84:87], v[206:209], v[190:193], v[84:87]
	v_mfma_f32_16x16x32_bf16 v[80:83], v[214:217], v[190:193], v[80:83]
	v_mfma_f32_16x16x32_bf16 v[68:71], v[206:209], v[198:201], v[68:71]
	v_mfma_f32_16x16x32_bf16 v[64:67], v[214:217], v[198:201], v[64:67]
	v_mfma_f32_16x16x32_bf16 v[116:119], v[210:213], v[174:177], v[116:119]
	v_mfma_f32_16x16x32_bf16 v[112:115], v[218:221], v[174:177], v[112:115]
	v_mfma_f32_16x16x32_bf16 v[100:103], v[210:213], v[182:185], v[100:103]
	v_mfma_f32_16x16x32_bf16 v[96:99], v[218:221], v[182:185], v[96:99]
	v_mfma_f32_16x16x32_bf16 v[84:87], v[210:213], v[194:197], v[84:87]
	v_mfma_f32_16x16x32_bf16 v[80:83], v[218:221], v[194:197], v[80:83]
	v_mfma_f32_16x16x32_bf16 v[68:71], v[210:213], v[202:205], v[68:71]
	v_mfma_f32_16x16x32_bf16 v[64:67], v[218:221], v[202:205], v[64:67]
	s_mov_b32 m0, s49
	v_lshl_add_u64 v[156:157], v[222:223], 0, s[8:9]
	s_barrier
	ds_read_b128 v[170:173], v163 offset:49152
	ds_read_b128 v[174:177], v163 offset:50176
	ds_read_b128 v[178:181], v163 offset:51200
	ds_read_b128 v[182:185], v163 offset:52224
	ds_read_b128 v[190:193], v163 offset:53248
	ds_read_b128 v[194:197], v163 offset:54272
	ds_read_b128 v[198:201], v163 offset:55296
	ds_read_b128 v[202:205], v163 offset:56320
	global_load_lds_dwordx4 v[156:157], off
	v_lshl_add_u64 v[156:157], v[224:225], 0, s[8:9]
	s_mov_b32 m0, s50
	s_nop 0
	global_load_lds_dwordx4 v[156:157], off
	s_barrier
	s_waitcnt lgkmcnt(0)
	s_waitcnt lgkmcnt(0)
	v_mfma_f32_16x16x32_bf16 v[60:63], v[128:131], v[170:173], v[60:63]
	v_mfma_f32_16x16x32_bf16 v[56:59], v[152:155], v[170:173], v[56:59]
	v_mfma_f32_16x16x32_bf16 v[44:47], v[128:131], v[178:181], v[44:47]
	v_mfma_f32_16x16x32_bf16 v[40:43], v[152:155], v[178:181], v[40:43]
	v_mfma_f32_16x16x32_bf16 v[28:31], v[128:131], v[190:193], v[28:31]
	v_mfma_f32_16x16x32_bf16 v[24:27], v[152:155], v[190:193], v[24:27]
	v_mfma_f32_16x16x32_bf16 v[12:15], v[128:131], v[198:201], v[12:15]
	v_mfma_f32_16x16x32_bf16 v[8:11], v[152:155], v[198:201], v[8:11]
	v_mfma_f32_16x16x32_bf16 v[60:63], v[148:151], v[174:177], v[60:63]
	v_mfma_f32_16x16x32_bf16 v[56:59], v[166:169], v[174:177], v[56:59]
	v_mfma_f32_16x16x32_bf16 v[44:47], v[148:151], v[182:185], v[44:47]
	v_mfma_f32_16x16x32_bf16 v[40:43], v[166:169], v[182:185], v[40:43]
	v_mfma_f32_16x16x32_bf16 v[28:31], v[148:151], v[194:197], v[28:31]
	v_mfma_f32_16x16x32_bf16 v[24:27], v[166:169], v[194:197], v[24:27]
	v_mfma_f32_16x16x32_bf16 v[12:15], v[148:151], v[202:205], v[12:15]
	v_mfma_f32_16x16x32_bf16 v[8:11], v[166:169], v[202:205], v[8:11]
	s_barrier
	s_add_u32 s36, s36, 0x40080
	s_addc_u32 s37, s37, 0
	s_add_i32 s38, s38, s44
	v_lshl_add_u64 v[128:129], s[36:37], 0, v[134:135]
	s_mov_b32 m0, s38
	s_nop 0
	global_load_lds_dwordx4 v[128:129], off
	v_lshl_add_u64 v[128:129], s[36:37], 0, v[138:139]
	s_add_i32 m0, s38, 0x2000
	s_nop 0
	global_load_lds_dwordx4 v[128:129], off
	s_waitcnt vmcnt(6)
	s_barrier
	v_mfma_f32_16x16x32_bf16 v[52:55], v[206:209], v[170:173], v[52:55]
	v_mfma_f32_16x16x32_bf16 v[48:51], v[214:217], v[170:173], v[48:51]
	v_mfma_f32_16x16x32_bf16 v[36:39], v[206:209], v[178:181], v[36:39]
	v_mfma_f32_16x16x32_bf16 v[32:35], v[214:217], v[178:181], v[32:35]
	v_mfma_f32_16x16x32_bf16 v[20:23], v[206:209], v[190:193], v[20:23]
	v_mfma_f32_16x16x32_bf16 v[16:19], v[214:217], v[190:193], v[16:19]
	v_mfma_f32_16x16x32_bf16 v[4:7], v[206:209], v[198:201], v[4:7]
	v_mfma_f32_16x16x32_bf16 v[0:3], v[214:217], v[198:201], v[0:3]
	v_mfma_f32_16x16x32_bf16 v[52:55], v[210:213], v[174:177], v[52:55]
	v_mfma_f32_16x16x32_bf16 v[48:51], v[218:221], v[174:177], v[48:51]
	v_mfma_f32_16x16x32_bf16 v[36:39], v[210:213], v[182:185], v[36:39]
	v_mfma_f32_16x16x32_bf16 v[32:35], v[218:221], v[182:185], v[32:35]
	v_mfma_f32_16x16x32_bf16 v[20:23], v[210:213], v[194:197], v[20:23]
	v_mfma_f32_16x16x32_bf16 v[16:19], v[218:221], v[194:197], v[16:19]
	v_mfma_f32_16x16x32_bf16 v[4:7], v[210:213], v[202:205], v[4:7]
	v_mfma_f32_16x16x32_bf16 v[0:3], v[218:221], v[202:205], v[0:3]
	s_add_i32 s59, s59, 2
	s_add_u32 s34, s34, 0x100
	s_addc_u32 s35, s35, 0
	s_add_u32 s57, s57, 0x100
	s_addc_u32 s58, s58, 0
	s_cmp_gt_u32 s59, 13
	s_barrier
	s_cbranch_scc0 .LBB0_286
	v_lshl_add_u32 v128, s30, 8, v159
	v_or_b32_e32 v156, 16, v128
	v_lshl_or_b32 v130, s54, 8, v161
	v_ashrrev_i32_e32 v129, 31, v128
	v_ashrrev_i32_e32 v157, 31, v156
	v_ashrrev_i32_e32 v131, 31, v130
	v_lshl_add_u64 v[152:153], v[128:129], 2, s[10:11]
	v_lshlrev_b64 v[154:155], 11, v[128:129]
	v_lshl_add_u64 v[170:171], v[156:157], 2, s[10:11]
	v_lshlrev_b64 v[186:187], 11, v[156:157]
	v_or_b32_e32 v156, 32, v128
	v_or_b32_e32 v128, 48, v128
	v_lshlrev_b64 v[148:149], 1, v[130:131]
	v_ashrrev_i32_e32 v157, 31, v156
	v_ashrrev_i32_e32 v129, 31, v128
	v_lshl_add_u64 v[150:151], s[0:1], 0, v[148:149]
	v_lshl_add_u64 v[182:183], v[156:157], 2, s[10:11]
	v_lshlrev_b64 v[198:199], 11, v[156:157]
	v_lshlrev_b64 v[156:157], 11, v[128:129]
	v_lshl_add_u64 v[130:131], v[150:151], 0, v[154:155]
	v_lshl_add_u64 v[178:179], v[150:151], 0, v[186:187]
	v_lshl_add_u64 v[190:191], v[150:151], 0, v[198:199]
	v_lshl_add_u64 v[192:193], v[128:129], 2, s[10:11]
	v_lshl_add_u64 v[128:129], v[150:151], 0, v[156:157]
	global_load_dword v200, v[152:153], off
	global_load_dwordx4 v[166:169], v[130:131], off
	global_load_dword v202, v[170:171], off
	s_nop 0
	global_load_dwordx4 v[170:173], v[130:131], off offset:256
	global_load_dwordx4 v[174:177], v[178:179], off
	s_nop 0
	global_load_dwordx4 v[178:181], v[178:179], off offset:256
	s_nop 0
	global_load_dword v204, v[182:183], off
	s_nop 0
	global_load_dwordx4 v[182:185], v[190:191], off
	global_load_dword v158, v[192:193], off
	s_nop 0
	global_load_dwordx4 v[190:193], v[190:191], off offset:256
	s_nop 0
	global_load_dwordx4 v[194:197], v[128:129], off
	s_nop 0
	global_load_dwordx4 v[128:131], v[128:129], off offset:256
	global_load_dword v216, v[152:153], off offset:512
	global_load_dword v218, v[152:153], off offset:576
	global_load_dword v220, v[152:153], off offset:640
	v_lshl_add_u64 v[252:253], v[154:155], 0, s[6:7]
	v_lshl_add_u64 v[252:253], v[150:151], 0, v[252:253]
	global_load_dwordx4 v[236:239], v[252:253], off
	global_load_dwordx4 v[240:243], v[252:253], off offset:256
	v_lshl_add_u64 v[252:253], v[154:155], 0, s[12:13]
	v_lshl_add_u64 v[252:253], v[150:151], 0, v[252:253]
	global_load_dwordx4 v[244:247], v[252:253], off
	global_load_dwordx4 v[248:251], v[252:253], off offset:256
	v_lshl_add_u64 v[252:253], v[154:155], 0, s[14:15]
	v_lshl_add_u64 v[252:253], v[150:151], 0, v[252:253]
	global_load_dwordx4 v[208:211], v[252:253], off
	global_load_dwordx4 v[212:215], v[252:253], off offset:256
	global_load_dword v252, v[152:153], off offset:704
	s_waitcnt vmcnt(10)
	v_pk_mul_f32 v[124:125], v[124:125], v[200:201] op_sel_hi:[1,0]
	v_pk_mul_f32 v[206:207], v[122:123], v[200:201] op_sel_hi:[1,0]
	v_pk_mul_f32 v[122:123], v[120:121], v[200:201] op_sel_hi:[1,0]
	v_lshlrev_b32_e32 v120, 16, v166
	v_and_b32_e32 v121, 0xffff0000, v166
	v_mul_f32_e32 v120, v124, v120
	v_mul_f32_e32 v121, v125, v121
	v_pk_mul_f32 v[126:127], v[126:127], v[200:201] op_sel_hi:[1,0]
	v_cvt_pk_bf16_f32 v120, v120, v121
	v_lshlrev_b32_e32 v121, 16, v167
	v_and_b32_e32 v124, 0xffff0000, v167
	v_mul_f32_e32 v121, v126, v121
	v_mul_f32_e32 v124, v127, v124
	v_cvt_pk_bf16_f32 v121, v121, v124
	v_lshlrev_b32_e32 v124, 16, v168
	v_mul_f32_e32 v122, v122, v124
	v_and_b32_e32 v124, 0xffff0000, v168
	v_mul_f32_e32 v123, v123, v124
	v_cvt_pk_bf16_f32 v122, v122, v123
	v_lshlrev_b32_e32 v123, 16, v169
	v_and_b32_e32 v124, 0xffff0000, v169
	v_mul_f32_e32 v123, v206, v123
	v_mul_f32_e32 v124, v207, v124
	v_cvt_pk_bf16_f32 v123, v123, v124
	v_lshl_add_u64 v[124:125], s[26:27], 0, v[154:155]
	v_lshl_add_u64 v[124:125], v[124:125], 0, v[148:149]
	global_store_dwordx4 v[124:125], v[120:123], off
	v_pk_mul_f32 v[116:117], v[116:117], v[200:201] op_sel_hi:[1,0]
	v_pk_mul_f32 v[118:119], v[118:119], v[200:201] op_sel_hi:[1,0]
	v_pk_mul_f32 v[120:121], v[114:115], v[200:201] op_sel_hi:[1,0]
	v_pk_mul_f32 v[114:115], v[112:113], v[200:201] op_sel_hi:[1,0]
	v_lshlrev_b32_e32 v112, 16, v170
	v_and_b32_e32 v113, 0xffff0000, v170
	v_mul_f32_e32 v112, v116, v112
	v_mul_f32_e32 v113, v117, v113
	v_cvt_pk_bf16_f32 v112, v112, v113
	v_lshlrev_b32_e32 v113, 16, v171
	v_and_b32_e32 v116, 0xffff0000, v171
	v_mul_f32_e32 v113, v118, v113
	v_mul_f32_e32 v116, v119, v116
	v_cvt_pk_bf16_f32 v113, v113, v116
	v_lshlrev_b32_e32 v116, 16, v172
	v_mul_f32_e32 v114, v114, v116
	v_and_b32_e32 v116, 0xffff0000, v172
	v_mul_f32_e32 v115, v115, v116
	v_cvt_pk_bf16_f32 v114, v114, v115
	v_lshlrev_b32_e32 v115, 16, v173
	v_mul_f32_e32 v115, v120, v115
	v_and_b32_e32 v116, 0xffff0000, v173
	v_mul_f32_e32 v116, v121, v116
	v_cvt_pk_bf16_f32 v115, v115, v116
	global_store_dwordx4 v[124:125], v[112:115], off offset:256
	v_pk_mul_f32 v[108:109], v[108:109], v[202:203] op_sel_hi:[1,0]
	v_pk_mul_f32 v[110:111], v[110:111], v[202:203] op_sel_hi:[1,0]
	v_pk_mul_f32 v[112:113], v[106:107], v[202:203] op_sel_hi:[1,0]
	v_pk_mul_f32 v[106:107], v[104:105], v[202:203] op_sel_hi:[1,0]
	v_lshlrev_b32_e32 v104, 16, v174
	v_and_b32_e32 v105, 0xffff0000, v174
	v_mul_f32_e32 v104, v108, v104
	v_mul_f32_e32 v105, v109, v105
	v_cvt_pk_bf16_f32 v104, v104, v105
	v_lshlrev_b32_e32 v105, 16, v175
	v_and_b32_e32 v108, 0xffff0000, v175
	v_mul_f32_e32 v105, v110, v105
	v_mul_f32_e32 v108, v111, v108
	v_cvt_pk_bf16_f32 v105, v105, v108
	v_lshlrev_b32_e32 v108, 16, v176
	v_mul_f32_e32 v106, v106, v108
	v_and_b32_e32 v108, 0xffff0000, v176
	v_mul_f32_e32 v107, v107, v108
	v_cvt_pk_bf16_f32 v106, v106, v107
	v_lshlrev_b32_e32 v107, 16, v177
	v_and_b32_e32 v108, 0xffff0000, v177
	v_mul_f32_e32 v107, v112, v107
	v_mul_f32_e32 v108, v113, v108
	v_cvt_pk_bf16_f32 v107, v107, v108
	v_lshl_add_u64 v[108:109], s[26:27], 0, v[186:187]
	v_lshl_add_u64 v[108:109], v[108:109], 0, v[148:149]
	global_store_dwordx4 v[108:109], v[104:107], off
	v_pk_mul_f32 v[100:101], v[100:101], v[202:203] op_sel_hi:[1,0]
	v_pk_mul_f32 v[102:103], v[102:103], v[202:203] op_sel_hi:[1,0]
	v_pk_mul_f32 v[104:105], v[98:99], v[202:203] op_sel_hi:[1,0]
	v_pk_mul_f32 v[98:99], v[96:97], v[202:203] op_sel_hi:[1,0]
	v_lshlrev_b32_e32 v96, 16, v178
	v_and_b32_e32 v97, 0xffff0000, v178
	v_mul_f32_e32 v96, v100, v96
	v_mul_f32_e32 v97, v101, v97
	v_cvt_pk_bf16_f32 v96, v96, v97
	v_lshlrev_b32_e32 v97, 16, v179
	v_and_b32_e32 v100, 0xffff0000, v179
	v_mul_f32_e32 v97, v102, v97
	v_mul_f32_e32 v100, v103, v100
	v_cvt_pk_bf16_f32 v97, v97, v100
	v_lshlrev_b32_e32 v100, 16, v180
	v_mul_f32_e32 v98, v98, v100
	v_and_b32_e32 v100, 0xffff0000, v180
	v_mul_f32_e32 v99, v99, v100
	v_cvt_pk_bf16_f32 v98, v98, v99
	v_lshlrev_b32_e32 v99, 16, v181
	v_mul_f32_e32 v99, v104, v99
	v_and_b32_e32 v100, 0xffff0000, v181
	v_mul_f32_e32 v100, v105, v100
	v_cvt_pk_bf16_f32 v99, v99, v100
	global_store_dwordx4 v[108:109], v[96:99], off offset:256
	v_pk_mul_f32 v[92:93], v[92:93], v[204:205] op_sel_hi:[1,0]
	v_pk_mul_f32 v[94:95], v[94:95], v[204:205] op_sel_hi:[1,0]
	v_pk_mul_f32 v[96:97], v[90:91], v[204:205] op_sel_hi:[1,0]
	v_pk_mul_f32 v[90:91], v[88:89], v[204:205] op_sel_hi:[1,0]
	v_lshlrev_b32_e32 v88, 16, v182
	v_and_b32_e32 v89, 0xffff0000, v182
	v_mul_f32_e32 v88, v92, v88
	v_mul_f32_e32 v89, v93, v89
	v_cvt_pk_bf16_f32 v88, v88, v89
	v_lshlrev_b32_e32 v89, 16, v183
	v_and_b32_e32 v92, 0xffff0000, v183
	v_mul_f32_e32 v89, v94, v89
	v_mul_f32_e32 v92, v95, v92
	v_cvt_pk_bf16_f32 v89, v89, v92
	v_lshlrev_b32_e32 v92, 16, v184
	v_mul_f32_e32 v90, v90, v92
	v_and_b32_e32 v92, 0xffff0000, v184
	v_mul_f32_e32 v91, v91, v92
	v_cvt_pk_bf16_f32 v90, v90, v91
	v_lshlrev_b32_e32 v91, 16, v185
	v_and_b32_e32 v92, 0xffff0000, v185
	v_mul_f32_e32 v91, v96, v91
	v_mul_f32_e32 v92, v97, v92
	v_cvt_pk_bf16_f32 v91, v91, v92
	v_lshl_add_u64 v[92:93], s[26:27], 0, v[198:199]
	v_lshl_add_u64 v[92:93], v[92:93], 0, v[148:149]
	global_store_dwordx4 v[92:93], v[88:91], off
	v_pk_mul_f32 v[84:85], v[84:85], v[204:205] op_sel_hi:[1,0]
	v_pk_mul_f32 v[86:87], v[86:87], v[204:205] op_sel_hi:[1,0]
	v_pk_mul_f32 v[88:89], v[82:83], v[204:205] op_sel_hi:[1,0]
	v_pk_mul_f32 v[82:83], v[80:81], v[204:205] op_sel_hi:[1,0]
	v_lshlrev_b32_e32 v80, 16, v190
	v_and_b32_e32 v81, 0xffff0000, v190
	v_mul_f32_e32 v80, v84, v80
	v_mul_f32_e32 v81, v85, v81
	v_cvt_pk_bf16_f32 v80, v80, v81
	v_lshlrev_b32_e32 v81, 16, v191
	v_and_b32_e32 v84, 0xffff0000, v191
	v_mul_f32_e32 v81, v86, v81
	v_mul_f32_e32 v84, v87, v84
	v_cvt_pk_bf16_f32 v81, v81, v84
	v_lshlrev_b32_e32 v84, 16, v192
	v_mul_f32_e32 v82, v82, v84
	v_and_b32_e32 v84, 0xffff0000, v192
	v_mul_f32_e32 v83, v83, v84
	v_cvt_pk_bf16_f32 v82, v82, v83
	v_lshlrev_b32_e32 v83, 16, v193
	v_mul_f32_e32 v83, v88, v83
	v_and_b32_e32 v84, 0xffff0000, v193
	v_mul_f32_e32 v84, v89, v84
	v_cvt_pk_bf16_f32 v83, v83, v84
	global_store_dwordx4 v[92:93], v[80:83], off offset:256
	v_pk_mul_f32 v[76:77], v[76:77], v[158:159] op_sel_hi:[1,0]
	v_pk_mul_f32 v[78:79], v[78:79], v[158:159] op_sel_hi:[1,0]
	v_pk_mul_f32 v[80:81], v[74:75], v[158:159] op_sel_hi:[1,0]
	v_pk_mul_f32 v[74:75], v[72:73], v[158:159] op_sel_hi:[1,0]
	v_lshlrev_b32_e32 v72, 16, v194
	v_and_b32_e32 v73, 0xffff0000, v194
	v_mul_f32_e32 v72, v76, v72
	v_mul_f32_e32 v73, v77, v73
	v_cvt_pk_bf16_f32 v72, v72, v73
	v_lshlrev_b32_e32 v73, 16, v195
	v_and_b32_e32 v76, 0xffff0000, v195
	v_mul_f32_e32 v73, v78, v73
	v_mul_f32_e32 v76, v79, v76
	v_cvt_pk_bf16_f32 v73, v73, v76
	v_lshlrev_b32_e32 v76, 16, v196
	v_mul_f32_e32 v74, v74, v76
	v_and_b32_e32 v76, 0xffff0000, v196
	v_mul_f32_e32 v75, v75, v76
	v_cvt_pk_bf16_f32 v74, v74, v75
	v_lshlrev_b32_e32 v75, 16, v197
	v_and_b32_e32 v76, 0xffff0000, v197
	v_mul_f32_e32 v75, v80, v75
	v_mul_f32_e32 v76, v81, v76
	v_cvt_pk_bf16_f32 v75, v75, v76
	v_lshl_add_u64 v[76:77], s[26:27], 0, v[156:157]
	v_lshl_add_u64 v[76:77], v[76:77], 0, v[148:149]
	global_store_dwordx4 v[76:77], v[72:75], off
	v_pk_mul_f32 v[68:69], v[68:69], v[158:159] op_sel_hi:[1,0]
	v_pk_mul_f32 v[70:71], v[70:71], v[158:159] op_sel_hi:[1,0]
	v_pk_mul_f32 v[72:73], v[66:67], v[158:159] op_sel_hi:[1,0]
	v_pk_mul_f32 v[66:67], v[64:65], v[158:159] op_sel_hi:[1,0]
	v_lshlrev_b32_e32 v64, 16, v128
	v_and_b32_e32 v65, 0xffff0000, v128
	v_mul_f32_e32 v64, v68, v64
	v_mul_f32_e32 v65, v69, v65
	v_cvt_pk_bf16_f32 v64, v64, v65
	v_lshlrev_b32_e32 v65, 16, v129
	v_and_b32_e32 v68, 0xffff0000, v129
	v_mul_f32_e32 v65, v70, v65
	v_mul_f32_e32 v68, v71, v68
	v_cvt_pk_bf16_f32 v65, v65, v68
	v_lshlrev_b32_e32 v68, 16, v130
	v_mul_f32_e32 v66, v66, v68
	v_and_b32_e32 v68, 0xffff0000, v130
	v_mul_f32_e32 v67, v67, v68
	v_cvt_pk_bf16_f32 v66, v66, v67
	v_lshlrev_b32_e32 v67, 16, v131
	v_mul_f32_e32 v67, v72, v67
	v_and_b32_e32 v68, 0xffff0000, v131
	v_mul_f32_e32 v68, v73, v68
	v_cvt_pk_bf16_f32 v67, v67, v68
	v_lshl_add_u64 v[100:101], v[154:155], 0, s[6:7]
	v_lshl_add_u64 v[102:103], v[154:155], 0, s[12:13]
	v_lshl_add_u64 v[104:105], v[154:155], 0, s[14:15]
	global_store_dwordx4 v[76:77], v[64:67], off offset:256
	v_lshl_add_u64 v[92:93], v[150:151], 0, v[104:105]
	v_lshl_add_u64 v[70:71], v[154:155], 0, s[18:19]
	v_lshl_add_u64 v[64:65], v[150:151], 0, v[100:101]
	v_lshl_add_u64 v[66:67], v[150:151], 0, v[102:103]
	v_lshl_add_u64 v[112:113], v[150:151], 0, v[70:71]
	s_nop 0
	s_nop 0
	global_load_dwordx4 v[96:99], v[112:113], off
	global_load_dwordx4 v[64:67], v[112:113], off offset:256
	s_waitcnt vmcnt(10)
	v_pk_mul_f32 v[60:61], v[60:61], v[216:217] op_sel_hi:[1,0]
	v_pk_mul_f32 v[112:113], v[58:59], v[216:217] op_sel_hi:[1,0]
	v_pk_mul_f32 v[58:59], v[56:57], v[216:217] op_sel_hi:[1,0]
	v_lshlrev_b32_e32 v56, 16, v236
	v_and_b32_e32 v57, 0xffff0000, v236
	v_mul_f32_e32 v56, v60, v56
	v_mul_f32_e32 v57, v61, v57
	v_pk_mul_f32 v[62:63], v[62:63], v[216:217] op_sel_hi:[1,0]
	v_cvt_pk_bf16_f32 v56, v56, v57
	v_lshlrev_b32_e32 v57, 16, v237
	v_and_b32_e32 v60, 0xffff0000, v237
	v_mul_f32_e32 v57, v62, v57
	v_mul_f32_e32 v60, v63, v60
	v_cvt_pk_bf16_f32 v57, v57, v60
	v_lshlrev_b32_e32 v60, 16, v238
	v_mul_f32_e32 v58, v58, v60
	v_and_b32_e32 v60, 0xffff0000, v238
	v_mul_f32_e32 v59, v59, v60
	v_cvt_pk_bf16_f32 v58, v58, v59
	v_lshlrev_b32_e32 v59, 16, v239
	v_and_b32_e32 v60, 0xffff0000, v239
	v_mul_f32_e32 v59, v112, v59
	v_mul_f32_e32 v60, v113, v60
	v_cvt_pk_bf16_f32 v59, v59, v60
	v_lshl_add_u64 v[60:61], s[26:27], 0, v[100:101]
	v_lshl_add_u64 v[60:61], v[60:61], 0, v[148:149]
	global_store_dwordx4 v[60:61], v[56:59], off
	v_pk_mul_f32 v[52:53], v[52:53], v[216:217] op_sel_hi:[1,0]
	v_pk_mul_f32 v[54:55], v[54:55], v[216:217] op_sel_hi:[1,0]
	v_pk_mul_f32 v[56:57], v[50:51], v[216:217] op_sel_hi:[1,0]
	v_pk_mul_f32 v[50:51], v[48:49], v[216:217] op_sel_hi:[1,0]
	v_lshlrev_b32_e32 v48, 16, v240
	v_and_b32_e32 v49, 0xffff0000, v240
	v_mul_f32_e32 v48, v52, v48
	v_mul_f32_e32 v49, v53, v49
	v_cvt_pk_bf16_f32 v48, v48, v49
	v_lshlrev_b32_e32 v49, 16, v241
	v_and_b32_e32 v52, 0xffff0000, v241
	v_mul_f32_e32 v49, v54, v49
	v_mul_f32_e32 v52, v55, v52
	v_cvt_pk_bf16_f32 v49, v49, v52
	v_lshlrev_b32_e32 v52, 16, v242
	v_mul_f32_e32 v50, v50, v52
	v_and_b32_e32 v52, 0xffff0000, v242
	v_mul_f32_e32 v51, v51, v52
	v_cvt_pk_bf16_f32 v50, v50, v51
	v_lshlrev_b32_e32 v51, 16, v243
	v_mul_f32_e32 v51, v56, v51
	v_and_b32_e32 v52, 0xffff0000, v243
	v_mul_f32_e32 v52, v57, v52
	v_cvt_pk_bf16_f32 v51, v51, v52
	global_store_dwordx4 v[60:61], v[48:51], off offset:256
	v_pk_mul_f32 v[44:45], v[44:45], v[218:219] op_sel_hi:[1,0]
	v_pk_mul_f32 v[46:47], v[46:47], v[218:219] op_sel_hi:[1,0]
	v_pk_mul_f32 v[48:49], v[42:43], v[218:219] op_sel_hi:[1,0]
	v_pk_mul_f32 v[42:43], v[40:41], v[218:219] op_sel_hi:[1,0]
	v_lshlrev_b32_e32 v40, 16, v244
	v_and_b32_e32 v41, 0xffff0000, v244
	v_mul_f32_e32 v40, v44, v40
	v_mul_f32_e32 v41, v45, v41
	v_cvt_pk_bf16_f32 v40, v40, v41
	v_lshlrev_b32_e32 v41, 16, v245
	v_and_b32_e32 v44, 0xffff0000, v245
	v_mul_f32_e32 v41, v46, v41
	v_mul_f32_e32 v44, v47, v44
	v_cvt_pk_bf16_f32 v41, v41, v44
	v_lshlrev_b32_e32 v44, 16, v246
	v_mul_f32_e32 v42, v42, v44
	v_and_b32_e32 v44, 0xffff0000, v246
	v_mul_f32_e32 v43, v43, v44
	v_cvt_pk_bf16_f32 v42, v42, v43
	v_lshlrev_b32_e32 v43, 16, v247
	v_and_b32_e32 v44, 0xffff0000, v247
	v_mul_f32_e32 v43, v48, v43
	v_mul_f32_e32 v44, v49, v44
	v_cvt_pk_bf16_f32 v43, v43, v44
	v_lshl_add_u64 v[44:45], s[26:27], 0, v[102:103]
	v_lshl_add_u64 v[44:45], v[44:45], 0, v[148:149]
	global_store_dwordx4 v[44:45], v[40:43], off
	v_pk_mul_f32 v[36:37], v[36:37], v[218:219] op_sel_hi:[1,0]
	v_pk_mul_f32 v[38:39], v[38:39], v[218:219] op_sel_hi:[1,0]
	v_pk_mul_f32 v[40:41], v[34:35], v[218:219] op_sel_hi:[1,0]
	v_pk_mul_f32 v[34:35], v[32:33], v[218:219] op_sel_hi:[1,0]
	v_lshlrev_b32_e32 v32, 16, v248
	v_and_b32_e32 v33, 0xffff0000, v248
	v_mul_f32_e32 v32, v36, v32
	v_mul_f32_e32 v33, v37, v33
	v_cvt_pk_bf16_f32 v32, v32, v33
	v_lshlrev_b32_e32 v33, 16, v249
	v_and_b32_e32 v36, 0xffff0000, v249
	v_mul_f32_e32 v33, v38, v33
	v_mul_f32_e32 v36, v39, v36
	v_cvt_pk_bf16_f32 v33, v33, v36
	v_lshlrev_b32_e32 v36, 16, v250
	v_mul_f32_e32 v34, v34, v36
	v_and_b32_e32 v36, 0xffff0000, v250
	v_mul_f32_e32 v35, v35, v36
	v_cvt_pk_bf16_f32 v34, v34, v35
	v_lshlrev_b32_e32 v35, 16, v251
	v_mul_f32_e32 v35, v40, v35
	v_and_b32_e32 v36, 0xffff0000, v251
	v_mul_f32_e32 v36, v41, v36
	v_cvt_pk_bf16_f32 v35, v35, v36
	global_store_dwordx4 v[44:45], v[32:35], off offset:256
	v_pk_mul_f32 v[28:29], v[28:29], v[220:221] op_sel_hi:[1,0]
	v_pk_mul_f32 v[30:31], v[30:31], v[220:221] op_sel_hi:[1,0]
	v_pk_mul_f32 v[32:33], v[26:27], v[220:221] op_sel_hi:[1,0]
	v_pk_mul_f32 v[26:27], v[24:25], v[220:221] op_sel_hi:[1,0]
	v_lshlrev_b32_e32 v24, 16, v208
	v_and_b32_e32 v25, 0xffff0000, v208
	v_mul_f32_e32 v24, v28, v24
	v_mul_f32_e32 v25, v29, v25
	v_cvt_pk_bf16_f32 v24, v24, v25
	v_lshlrev_b32_e32 v25, 16, v209
	v_and_b32_e32 v28, 0xffff0000, v209
	v_mul_f32_e32 v25, v30, v25
	v_mul_f32_e32 v28, v31, v28
	v_cvt_pk_bf16_f32 v25, v25, v28
	v_lshlrev_b32_e32 v28, 16, v210
	v_mul_f32_e32 v26, v26, v28
	v_and_b32_e32 v28, 0xffff0000, v210
	v_mul_f32_e32 v27, v27, v28
	v_cvt_pk_bf16_f32 v26, v26, v27
	v_lshlrev_b32_e32 v27, 16, v211
	v_and_b32_e32 v28, 0xffff0000, v211
	v_mul_f32_e32 v27, v32, v27
	v_mul_f32_e32 v28, v33, v28
	v_cvt_pk_bf16_f32 v27, v27, v28
	v_lshl_add_u64 v[28:29], s[26:27], 0, v[104:105]
	v_lshl_add_u64 v[28:29], v[28:29], 0, v[148:149]
	global_store_dwordx4 v[28:29], v[24:27], off
	v_pk_mul_f32 v[20:21], v[20:21], v[220:221] op_sel_hi:[1,0]
	v_pk_mul_f32 v[22:23], v[22:23], v[220:221] op_sel_hi:[1,0]
	v_pk_mul_f32 v[24:25], v[18:19], v[220:221] op_sel_hi:[1,0]
	v_pk_mul_f32 v[18:19], v[16:17], v[220:221] op_sel_hi:[1,0]
	v_lshlrev_b32_e32 v16, 16, v212
	v_and_b32_e32 v17, 0xffff0000, v212
	v_mul_f32_e32 v16, v20, v16
	v_mul_f32_e32 v17, v21, v17
	v_cvt_pk_bf16_f32 v16, v16, v17
	v_lshlrev_b32_e32 v17, 16, v213
	v_and_b32_e32 v20, 0xffff0000, v213
	v_mul_f32_e32 v17, v22, v17
	v_mul_f32_e32 v20, v23, v20
	v_cvt_pk_bf16_f32 v17, v17, v20
	v_lshlrev_b32_e32 v20, 16, v214
	v_mul_f32_e32 v18, v18, v20
	v_and_b32_e32 v20, 0xffff0000, v214
	v_mul_f32_e32 v19, v19, v20
	v_cvt_pk_bf16_f32 v18, v18, v19
	v_lshlrev_b32_e32 v19, 16, v215
	v_mul_f32_e32 v19, v24, v19
	v_and_b32_e32 v20, 0xffff0000, v215
	v_mul_f32_e32 v20, v25, v20
	v_cvt_pk_bf16_f32 v19, v19, v20
	global_store_dwordx4 v[28:29], v[16:19], off offset:256
	s_waitcnt vmcnt(6)
	v_pk_mul_f32 v[12:13], v[12:13], v[252:253] op_sel_hi:[1,0]
	v_pk_mul_f32 v[14:15], v[14:15], v[252:253] op_sel_hi:[1,0]
	v_pk_mul_f32 v[16:17], v[10:11], v[252:253] op_sel_hi:[1,0]
	v_pk_mul_f32 v[10:11], v[8:9], v[252:253] op_sel_hi:[1,0]
	v_lshlrev_b32_e32 v8, 16, v96
	v_and_b32_e32 v9, 0xffff0000, v96
	v_mul_f32_e32 v8, v12, v8
	v_mul_f32_e32 v9, v13, v9
	v_cvt_pk_bf16_f32 v8, v8, v9
	v_lshlrev_b32_e32 v9, 16, v97
	v_and_b32_e32 v12, 0xffff0000, v97
	v_mul_f32_e32 v9, v14, v9
	v_mul_f32_e32 v12, v15, v12
	v_cvt_pk_bf16_f32 v9, v9, v12
	v_lshlrev_b32_e32 v12, 16, v98
	v_mul_f32_e32 v10, v10, v12
	v_and_b32_e32 v12, 0xffff0000, v98
	v_mul_f32_e32 v11, v11, v12
	v_cvt_pk_bf16_f32 v10, v10, v11
	v_lshlrev_b32_e32 v11, 16, v99
	v_and_b32_e32 v12, 0xffff0000, v99
	v_mul_f32_e32 v11, v16, v11
	v_mul_f32_e32 v12, v17, v12
	v_cvt_pk_bf16_f32 v11, v11, v12
	v_lshl_add_u64 v[12:13], s[26:27], 0, v[70:71]
	v_lshl_add_u64 v[12:13], v[12:13], 0, v[148:149]
	global_store_dwordx4 v[12:13], v[8:11], off
	v_pk_mul_f32 v[4:5], v[4:5], v[252:253] op_sel_hi:[1,0]
	v_pk_mul_f32 v[6:7], v[6:7], v[252:253] op_sel_hi:[1,0]
	v_pk_mul_f32 v[8:9], v[2:3], v[252:253] op_sel_hi:[1,0]
	v_pk_mul_f32 v[2:3], v[0:1], v[252:253] op_sel_hi:[1,0]
	v_lshlrev_b32_e32 v0, 16, v64
	v_and_b32_e32 v1, 0xffff0000, v64
	v_mul_f32_e32 v0, v4, v0
	v_mul_f32_e32 v1, v5, v1
	v_cvt_pk_bf16_f32 v0, v0, v1
	v_lshlrev_b32_e32 v1, 16, v65
	v_and_b32_e32 v4, 0xffff0000, v65
	v_mul_f32_e32 v1, v6, v1
	v_mul_f32_e32 v4, v7, v4
	v_cvt_pk_bf16_f32 v1, v1, v4
	v_lshlrev_b32_e32 v4, 16, v66
	v_mul_f32_e32 v2, v2, v4
	v_and_b32_e32 v4, 0xffff0000, v66
	v_mul_f32_e32 v3, v3, v4
	v_cvt_pk_bf16_f32 v2, v2, v3
	v_lshlrev_b32_e32 v3, 16, v67
	v_mul_f32_e32 v3, v8, v3
	v_and_b32_e32 v4, 0xffff0000, v67
	s_and_b64 vcc, exec, s[2:3]
	s_mov_b32 s54, s20
	s_mov_b32 s30, s22
	s_mov_b64 s[36:37], s[28:29]
	s_mov_b64 s[34:35], s[24:25]
	v_mul_f32_e32 v4, v9, v4
	v_cvt_pk_bf16_f32 v3, v3, v4
	global_store_dwordx4 v[12:13], v[0:3], off offset:256
	s_cbranch_vccz .LBB0_279
	s_waitcnt vmcnt(0)
	s_cmpk_gt_u32 s40, 0xff
	s_cbranch_scc1 .LBB0_290
	s_barrier

.LBB0_364:
	ds_read_b128 v[128:131], v208
	ds_read_b128 v[132:135], v208 offset:1024
	ds_read_b128 v[136:139], v208 offset:2048
	ds_read_b128 v[140:143], v208 offset:3072
	s_add_u32 s24, s22, 0xfffc0080
	s_addc_u32 s25, s23, -1
	s_cmp_eq_u32 s51, 12
	s_cselect_b32 s29, s13, s25
	s_cselect_b32 s28, s21, s24
	s_cselect_b32 s25, s11, s50
	s_cselect_b32 s24, s48, s49
	v_lshl_add_u64 v[194:195], s[22:23], 0, v[184:185]
	s_add_i32 m0, s36, 0xc000
	ds_read_b128 v[144:147], v209
	ds_read_b128 v[148:151], v209 offset:1024
	ds_read_b128 v[152:155], v209 offset:2048
	ds_read_b128 v[156:159], v209 offset:3072
	ds_read_b128 v[160:163], v209 offset:4096
	ds_read_b128 v[164:167], v209 offset:5120
	ds_read_b128 v[168:171], v209 offset:6144
	ds_read_b128 v[172:175], v209 offset:7168
	global_load_lds_dwordx4 v[194:195], off
	v_lshl_add_u64 v[194:195], s[22:23], 0, v[186:187]
	s_add_i32 m0, s36, 0xe000
	s_nop 0
	global_load_lds_dwordx4 v[194:195], off
	s_waitcnt lgkmcnt(8)
	s_barrier
	s_waitcnt lgkmcnt(0)
	s_waitcnt lgkmcnt(0)
	v_mfma_f32_16x16x32_bf16 v[124:127], v[128:131], v[144:147], v[124:127]
	v_mfma_f32_16x16x32_bf16 v[120:123], v[136:139], v[144:147], v[120:123]
	v_mfma_f32_16x16x32_bf16 v[108:111], v[128:131], v[152:155], v[108:111]
	v_mfma_f32_16x16x32_bf16 v[104:107], v[136:139], v[152:155], v[104:107]
	v_mfma_f32_16x16x32_bf16 v[92:95], v[128:131], v[160:163], v[92:95]
	v_mfma_f32_16x16x32_bf16 v[88:91], v[136:139], v[160:163], v[88:91]
	v_mfma_f32_16x16x32_bf16 v[76:79], v[128:131], v[168:171], v[76:79]
	v_mfma_f32_16x16x32_bf16 v[72:75], v[136:139], v[168:171], v[72:75]
	v_mfma_f32_16x16x32_bf16 v[124:127], v[132:135], v[148:151], v[124:127]
	v_mfma_f32_16x16x32_bf16 v[120:123], v[140:143], v[148:151], v[120:123]
	v_mfma_f32_16x16x32_bf16 v[108:111], v[132:135], v[156:159], v[108:111]
	v_mfma_f32_16x16x32_bf16 v[104:107], v[140:143], v[156:159], v[104:107]
	v_mfma_f32_16x16x32_bf16 v[92:95], v[132:135], v[164:167], v[92:95]
	v_mfma_f32_16x16x32_bf16 v[88:91], v[140:143], v[164:167], v[88:91]
	v_mfma_f32_16x16x32_bf16 v[76:79], v[132:135], v[172:175], v[76:79]
	v_mfma_f32_16x16x32_bf16 v[72:75], v[140:143], v[172:175], v[72:75]
	s_barrier
	s_add_i32 s52, s45, s35
	v_lshl_add_u64 v[216:217], s[24:25], 0, v[178:179]
	s_mov_b32 m0, s52
	ds_read_b128 v[194:197], v210
	ds_read_b128 v[198:201], v210 offset:1024
	ds_read_b128 v[202:205], v210 offset:2048
	ds_read_b128 v[212:215], v210 offset:3072
	global_load_lds_dwordx4 v[216:217], off
	v_lshl_add_u64 v[218:219], s[24:25], 0, v[182:183]
	s_add_i32 m0, s52, 0x2000
	s_nop 0
	global_load_lds_dwordx4 v[218:219], off
	s_barrier
	s_waitcnt lgkmcnt(0)
	s_waitcnt lgkmcnt(0)
	v_mfma_f32_16x16x32_bf16 v[116:119], v[194:197], v[144:147], v[116:119]
	v_mfma_f32_16x16x32_bf16 v[112:115], v[202:205], v[144:147], v[112:115]
	v_mfma_f32_16x16x32_bf16 v[100:103], v[194:197], v[152:155], v[100:103]
	v_mfma_f32_16x16x32_bf16 v[96:99], v[202:205], v[152:155], v[96:99]
	v_mfma_f32_16x16x32_bf16 v[84:87], v[194:197], v[160:163], v[84:87]
	v_mfma_f32_16x16x32_bf16 v[80:83], v[202:205], v[160:163], v[80:83]
	v_mfma_f32_16x16x32_bf16 v[68:71], v[194:197], v[168:171], v[68:71]
	v_mfma_f32_16x16x32_bf16 v[64:67], v[202:205], v[168:171], v[64:67]
	v_mfma_f32_16x16x32_bf16 v[116:119], v[198:201], v[148:151], v[116:119]
	v_mfma_f32_16x16x32_bf16 v[112:115], v[212:215], v[148:151], v[112:115]
	v_mfma_f32_16x16x32_bf16 v[100:103], v[198:201], v[156:159], v[100:103]
	v_mfma_f32_16x16x32_bf16 v[96:99], v[212:215], v[156:159], v[96:99]
	v_mfma_f32_16x16x32_bf16 v[84:87], v[198:201], v[164:167], v[84:87]
	v_mfma_f32_16x16x32_bf16 v[80:83], v[212:215], v[164:167], v[80:83]
	v_mfma_f32_16x16x32_bf16 v[68:71], v[198:201], v[172:175], v[68:71]
	v_mfma_f32_16x16x32_bf16 v[64:67], v[212:215], v[172:175], v[64:67]
	s_mov_b32 m0, s36
	v_lshl_add_u64 v[220:221], s[28:29], 0, v[176:177]
	s_barrier
	ds_read_b128 v[144:147], v209 offset:16384
	ds_read_b128 v[148:151], v209 offset:17408
	ds_read_b128 v[152:155], v209 offset:18432
	ds_read_b128 v[156:159], v209 offset:19456
	ds_read_b128 v[160:163], v209 offset:20480
	ds_read_b128 v[164:167], v209 offset:21504
	ds_read_b128 v[168:171], v209 offset:22528
	ds_read_b128 v[172:175], v209 offset:23552
	global_load_lds_dwordx4 v[220:221], off
	v_lshl_add_u64 v[222:223], s[28:29], 0, v[180:181]
	s_mov_b32 m0, s37
	s_nop 0
	global_load_lds_dwordx4 v[222:223], off
	s_barrier
	s_waitcnt lgkmcnt(0)
	s_waitcnt lgkmcnt(0)
	v_mfma_f32_16x16x32_bf16 v[60:63], v[128:131], v[144:147], v[60:63]
	v_mfma_f32_16x16x32_bf16 v[56:59], v[136:139], v[144:147], v[56:59]
	v_mfma_f32_16x16x32_bf16 v[44:47], v[128:131], v[152:155], v[44:47]
	v_mfma_f32_16x16x32_bf16 v[40:43], v[136:139], v[152:155], v[40:43]
	v_mfma_f32_16x16x32_bf16 v[28:31], v[128:131], v[160:163], v[28:31]
	v_mfma_f32_16x16x32_bf16 v[24:27], v[136:139], v[160:163], v[24:27]
	v_mfma_f32_16x16x32_bf16 v[12:15], v[128:131], v[168:171], v[12:15]
	v_mfma_f32_16x16x32_bf16 v[8:11], v[136:139], v[168:171], v[8:11]
	v_mfma_f32_16x16x32_bf16 v[60:63], v[132:135], v[148:151], v[60:63]
	v_mfma_f32_16x16x32_bf16 v[56:59], v[140:143], v[148:151], v[56:59]
	v_mfma_f32_16x16x32_bf16 v[44:47], v[132:135], v[156:159], v[44:47]
	v_mfma_f32_16x16x32_bf16 v[40:43], v[140:143], v[156:159], v[40:43]
	v_mfma_f32_16x16x32_bf16 v[28:31], v[132:135], v[164:167], v[28:31]
	v_mfma_f32_16x16x32_bf16 v[24:27], v[140:143], v[164:167], v[24:27]
	v_mfma_f32_16x16x32_bf16 v[12:15], v[132:135], v[172:175], v[12:15]
	v_mfma_f32_16x16x32_bf16 v[8:11], v[140:143], v[172:175], v[8:11]
	s_barrier
	s_add_u32 s52, s24, 0x40000
	s_addc_u32 s53, s25, 0
	s_add_i32 s54, s46, s35
	v_lshl_add_u64 v[128:129], s[52:53], 0, v[178:179]
	s_mov_b32 m0, s54
	s_nop 0
	global_load_lds_dwordx4 v[128:129], off
	v_lshl_add_u64 v[128:129], s[52:53], 0, v[182:183]
	s_add_i32 m0, s54, 0x2000
	s_nop 0
	global_load_lds_dwordx4 v[128:129], off
	s_waitcnt vmcnt(6)
	s_barrier
	v_mfma_f32_16x16x32_bf16 v[52:55], v[194:197], v[144:147], v[52:55]
	v_mfma_f32_16x16x32_bf16 v[48:51], v[202:205], v[144:147], v[48:51]
	v_mfma_f32_16x16x32_bf16 v[36:39], v[194:197], v[152:155], v[36:39]
	v_mfma_f32_16x16x32_bf16 v[32:35], v[202:205], v[152:155], v[32:35]
	v_mfma_f32_16x16x32_bf16 v[20:23], v[194:197], v[160:163], v[20:23]
	v_mfma_f32_16x16x32_bf16 v[16:19], v[202:205], v[160:163], v[16:19]
	v_mfma_f32_16x16x32_bf16 v[4:7], v[194:197], v[168:171], v[4:7]
	v_mfma_f32_16x16x32_bf16 v[0:3], v[202:205], v[168:171], v[0:3]
	v_mfma_f32_16x16x32_bf16 v[52:55], v[198:201], v[148:151], v[52:55]
	v_mfma_f32_16x16x32_bf16 v[48:51], v[212:215], v[148:151], v[48:51]
	v_mfma_f32_16x16x32_bf16 v[36:39], v[198:201], v[156:159], v[36:39]
	v_mfma_f32_16x16x32_bf16 v[32:35], v[212:215], v[156:159], v[32:35]
	v_mfma_f32_16x16x32_bf16 v[20:23], v[198:201], v[164:167], v[20:23]
	v_mfma_f32_16x16x32_bf16 v[16:19], v[212:215], v[164:167], v[16:19]
	v_mfma_f32_16x16x32_bf16 v[4:7], v[198:201], v[172:175], v[4:7]
	v_mfma_f32_16x16x32_bf16 v[0:3], v[212:215], v[172:175], v[0:3]
	s_add_i32 s52, 0, 0x18000
	v_add_u32_e32 v140, s52, v206
	s_barrier
	ds_read_b128 v[128:131], v140
	ds_read_b128 v[132:135], v140 offset:1024
	ds_read_b128 v[136:139], v140 offset:2048
	ds_read_b128 v[140:143], v140 offset:3072
	s_add_u32 s28, s28, 0x40000
	s_addc_u32 s29, s29, 0
	s_mov_b32 m0, s38
	v_lshl_add_u64 v[194:195], s[28:29], 0, v[176:177]
	ds_read_b128 v[144:147], v209 offset:32768
	ds_read_b128 v[148:151], v209 offset:33792
	ds_read_b128 v[152:155], v209 offset:34816
	ds_read_b128 v[156:159], v209 offset:35840
	ds_read_b128 v[160:163], v209 offset:36864
	ds_read_b128 v[164:167], v209 offset:37888
	ds_read_b128 v[168:171], v209 offset:38912
	ds_read_b128 v[172:175], v209 offset:39936
	global_load_lds_dwordx4 v[194:195], off
	v_lshl_add_u64 v[194:195], s[28:29], 0, v[180:181]
	s_mov_b32 m0, s39
	s_nop 0
	global_load_lds_dwordx4 v[194:195], off
	s_waitcnt lgkmcnt(8)
	s_barrier
	s_waitcnt lgkmcnt(0)
	s_waitcnt lgkmcnt(0)
	v_mfma_f32_16x16x32_bf16 v[124:127], v[128:131], v[144:147], v[124:127]
	v_mfma_f32_16x16x32_bf16 v[120:123], v[136:139], v[144:147], v[120:123]
	v_mfma_f32_16x16x32_bf16 v[108:111], v[128:131], v[152:155], v[108:111]
	v_mfma_f32_16x16x32_bf16 v[104:107], v[136:139], v[152:155], v[104:107]
	v_mfma_f32_16x16x32_bf16 v[92:95], v[128:131], v[160:163], v[92:95]
	v_mfma_f32_16x16x32_bf16 v[88:91], v[136:139], v[160:163], v[88:91]
	v_mfma_f32_16x16x32_bf16 v[76:79], v[128:131], v[168:171], v[76:79]
	v_mfma_f32_16x16x32_bf16 v[72:75], v[136:139], v[168:171], v[72:75]
	v_mfma_f32_16x16x32_bf16 v[124:127], v[132:135], v[148:151], v[124:127]
	v_mfma_f32_16x16x32_bf16 v[120:123], v[140:143], v[148:151], v[120:123]
	v_mfma_f32_16x16x32_bf16 v[108:111], v[132:135], v[156:159], v[108:111]
	v_mfma_f32_16x16x32_bf16 v[104:107], v[140:143], v[156:159], v[104:107]
	v_mfma_f32_16x16x32_bf16 v[92:95], v[132:135], v[164:167], v[92:95]
	v_mfma_f32_16x16x32_bf16 v[88:91], v[140:143], v[164:167], v[88:91]
	v_mfma_f32_16x16x32_bf16 v[76:79], v[132:135], v[172:175], v[76:79]
	v_mfma_f32_16x16x32_bf16 v[72:75], v[140:143], v[172:175], v[72:75]
	s_barrier
	s_add_i32 s28, 0, 0x1c000
	s_add_i32 s29, s52, s35
	v_add_u32_e32 v212, s28, v206
	v_lshl_add_u64 v[216:217], v[216:217], 0, s[8:9]
	s_mov_b32 m0, s29
	ds_read_b128 v[194:197], v212
	ds_read_b128 v[198:201], v212 offset:1024
	ds_read_b128 v[202:205], v212 offset:2048
	ds_read_b128 v[212:215], v212 offset:3072
	global_load_lds_dwordx4 v[216:217], off
	v_lshl_add_u64 v[216:217], v[218:219], 0, s[8:9]
	s_add_i32 m0, s29, 0x2000
	s_nop 0
	global_load_lds_dwordx4 v[216:217], off
	s_barrier
	s_waitcnt lgkmcnt(0)
	s_waitcnt lgkmcnt(0)
	v_mfma_f32_16x16x32_bf16 v[116:119], v[194:197], v[144:147], v[116:119]
	v_mfma_f32_16x16x32_bf16 v[112:115], v[202:205], v[144:147], v[112:115]
	v_mfma_f32_16x16x32_bf16 v[100:103], v[194:197], v[152:155], v[100:103]
	v_mfma_f32_16x16x32_bf16 v[96:99], v[202:205], v[152:155], v[96:99]
	v_mfma_f32_16x16x32_bf16 v[84:87], v[194:197], v[160:163], v[84:87]
	v_mfma_f32_16x16x32_bf16 v[80:83], v[202:205], v[160:163], v[80:83]
	v_mfma_f32_16x16x32_bf16 v[68:71], v[194:197], v[168:171], v[68:71]
	v_mfma_f32_16x16x32_bf16 v[64:67], v[202:205], v[168:171], v[64:67]
	v_mfma_f32_16x16x32_bf16 v[116:119], v[198:201], v[148:151], v[116:119]
	v_mfma_f32_16x16x32_bf16 v[112:115], v[212:215], v[148:151], v[112:115]
	v_mfma_f32_16x16x32_bf16 v[100:103], v[198:201], v[156:159], v[100:103]
	v_mfma_f32_16x16x32_bf16 v[96:99], v[212:215], v[156:159], v[96:99]
	v_mfma_f32_16x16x32_bf16 v[84:87], v[198:201], v[164:167], v[84:87]
	v_mfma_f32_16x16x32_bf16 v[80:83], v[212:215], v[164:167], v[80:83]
	v_mfma_f32_16x16x32_bf16 v[68:71], v[198:201], v[172:175], v[68:71]
	v_mfma_f32_16x16x32_bf16 v[64:67], v[212:215], v[172:175], v[64:67]
	s_mov_b32 m0, s41
	v_lshl_add_u64 v[216:217], v[220:221], 0, s[8:9]
	s_barrier
	ds_read_b128 v[144:147], v209 offset:49152
	ds_read_b128 v[148:151], v209 offset:50176
	ds_read_b128 v[152:155], v209 offset:51200
	ds_read_b128 v[156:159], v209 offset:52224
	ds_read_b128 v[160:163], v209 offset:53248
	ds_read_b128 v[164:167], v209 offset:54272
	ds_read_b128 v[168:171], v209 offset:55296
	ds_read_b128 v[172:175], v209 offset:56320
	global_load_lds_dwordx4 v[216:217], off
	v_lshl_add_u64 v[216:217], v[222:223], 0, s[8:9]
	s_mov_b32 m0, s42
	s_nop 0
	global_load_lds_dwordx4 v[216:217], off
	s_barrier
	s_waitcnt lgkmcnt(0)
	s_waitcnt lgkmcnt(0)
	v_mfma_f32_16x16x32_bf16 v[60:63], v[128:131], v[144:147], v[60:63]
	v_mfma_f32_16x16x32_bf16 v[56:59], v[136:139], v[144:147], v[56:59]
	v_mfma_f32_16x16x32_bf16 v[44:47], v[128:131], v[152:155], v[44:47]
	v_mfma_f32_16x16x32_bf16 v[40:43], v[136:139], v[152:155], v[40:43]
	v_mfma_f32_16x16x32_bf16 v[28:31], v[128:131], v[160:163], v[28:31]
	v_mfma_f32_16x16x32_bf16 v[24:27], v[136:139], v[160:163], v[24:27]
	v_mfma_f32_16x16x32_bf16 v[12:15], v[128:131], v[168:171], v[12:15]
	v_mfma_f32_16x16x32_bf16 v[8:11], v[136:139], v[168:171], v[8:11]
	v_mfma_f32_16x16x32_bf16 v[60:63], v[132:135], v[148:151], v[60:63]
	v_mfma_f32_16x16x32_bf16 v[56:59], v[140:143], v[148:151], v[56:59]
	v_mfma_f32_16x16x32_bf16 v[44:47], v[132:135], v[156:159], v[44:47]
	v_mfma_f32_16x16x32_bf16 v[40:43], v[140:143], v[156:159], v[40:43]
	v_mfma_f32_16x16x32_bf16 v[28:31], v[132:135], v[164:167], v[28:31]
	v_mfma_f32_16x16x32_bf16 v[24:27], v[140:143], v[164:167], v[24:27]
	v_mfma_f32_16x16x32_bf16 v[12:15], v[132:135], v[172:175], v[12:15]
	v_mfma_f32_16x16x32_bf16 v[8:11], v[140:143], v[172:175], v[8:11]
	s_barrier
	s_add_u32 s24, s24, 0x40080
	s_addc_u32 s25, s25, 0
	s_add_i32 s28, s28, s35
	v_lshl_add_u64 v[128:129], s[24:25], 0, v[178:179]
	s_mov_b32 m0, s28
	s_nop 0
	global_load_lds_dwordx4 v[128:129], off
	v_lshl_add_u64 v[128:129], s[24:25], 0, v[182:183]
	s_add_i32 m0, s28, 0x2000
	s_nop 0
	global_load_lds_dwordx4 v[128:129], off
	s_waitcnt vmcnt(6)
	s_barrier
	v_mfma_f32_16x16x32_bf16 v[52:55], v[194:197], v[144:147], v[52:55]
	v_mfma_f32_16x16x32_bf16 v[48:51], v[202:205], v[144:147], v[48:51]
	v_mfma_f32_16x16x32_bf16 v[36:39], v[194:197], v[152:155], v[36:39]
	v_mfma_f32_16x16x32_bf16 v[32:35], v[202:205], v[152:155], v[32:35]
	v_mfma_f32_16x16x32_bf16 v[20:23], v[194:197], v[160:163], v[20:23]
	v_mfma_f32_16x16x32_bf16 v[16:19], v[202:205], v[160:163], v[16:19]
	v_mfma_f32_16x16x32_bf16 v[4:7], v[194:197], v[168:171], v[4:7]
	v_mfma_f32_16x16x32_bf16 v[0:3], v[202:205], v[168:171], v[0:3]
	v_mfma_f32_16x16x32_bf16 v[52:55], v[198:201], v[148:151], v[52:55]
	v_mfma_f32_16x16x32_bf16 v[48:51], v[212:215], v[148:151], v[48:51]
	v_mfma_f32_16x16x32_bf16 v[36:39], v[198:201], v[156:159], v[36:39]
	v_mfma_f32_16x16x32_bf16 v[32:35], v[212:215], v[156:159], v[32:35]
	v_mfma_f32_16x16x32_bf16 v[20:23], v[198:201], v[164:167], v[20:23]
	v_mfma_f32_16x16x32_bf16 v[16:19], v[212:215], v[164:167], v[16:19]
	v_mfma_f32_16x16x32_bf16 v[4:7], v[198:201], v[172:175], v[4:7]
	v_mfma_f32_16x16x32_bf16 v[0:3], v[212:215], v[172:175], v[0:3]
	s_add_i32 s51, s51, 2
	s_add_u32 s22, s22, 0x100
	s_addc_u32 s23, s23, 0
	s_add_u32 s49, s49, 0x100
	s_addc_u32 s50, s50, 0
	s_cmp_gt_u32 s51, 13
	s_barrier
	s_cbranch_scc0 .LBB0_364
	v_lshl_add_u32 v196, s20, 8, v189
	v_lshl_or_b32 v194, s6, 8, v207
	v_readlane_b32 s48, v235, 5
	v_ashrrev_i32_e32 v195, 31, v194
	v_readlane_b32 s49, v235, 6
	v_ashrrev_i32_e32 v197, 31, v196
	v_lshlrev_b64 v[128:129], 12, v[196:197]
	v_lshl_add_u64 v[198:199], v[194:195], 2, s[48:49]
	v_or_b32_e32 v204, 16, v196
	v_lshl_add_u64 v[128:129], v[198:199], 0, v[128:129]
	v_ashrrev_i32_e32 v205, 31, v204
	global_load_dwordx4 v[212:215], v[128:129], off offset:16 nt
	global_load_dwordx4 v[216:219], v[128:129], off nt
	global_load_dwordx4 v[220:223], v[128:129], off offset:528 nt
	global_load_dwordx4 v[224:227], v[128:129], off offset:512 nt
	v_lshlrev_b64 v[128:129], 12, v[204:205]
	v_or_b32_e32 v202, 32, v196
	v_lshl_add_u64 v[128:129], v[198:199], 0, v[128:129]
	v_ashrrev_i32_e32 v203, 31, v202
	global_load_dwordx4 v[168:171], v[128:129], off offset:16 nt
	global_load_dwordx4 v[172:175], v[128:129], off nt
	global_load_dwordx4 v[160:163], v[128:129], off offset:528 nt
	global_load_dwordx4 v[164:167], v[128:129], off offset:512 nt
	v_lshlrev_b64 v[128:129], 12, v[202:203]
	v_or_b32_e32 v200, 48, v196
	v_lshl_add_u64 v[128:129], v[198:199], 0, v[128:129]
	v_ashrrev_i32_e32 v201, 31, v200
	global_load_dwordx4 v[152:155], v[128:129], off offset:16 nt
	global_load_dwordx4 v[156:159], v[128:129], off nt
	global_load_dwordx4 v[144:147], v[128:129], off offset:528 nt
	global_load_dwordx4 v[148:151], v[128:129], off offset:512 nt
	v_lshlrev_b64 v[128:129], 12, v[200:201]
	v_lshl_add_u64 v[132:133], v[198:199], 0, v[128:129]
	global_load_dwordx4 v[136:139], v[132:133], off offset:16 nt
	global_load_dwordx4 v[140:143], v[132:133], off nt
	global_load_dwordx4 v[128:131], v[132:133], off offset:528 nt
	s_nop 0
	global_load_dwordx4 v[132:135], v[132:133], off offset:512 nt
	s_lshl_b32 s20, s6, 2
	s_ashr_i32 s21, s20, 31
	v_readlane_b32 s50, v235, 7
	v_readlane_b32 s51, v235, 8
	v_readlane_b32 s52, v235, 9
	v_readlane_b32 s53, v235, 10
	v_readlane_b32 s54, v235, 11
	v_readlane_b32 s55, v235, 12
	v_readlane_b32 s56, v235, 13
	v_readlane_b32 s57, v235, 14
	v_readlane_b32 s58, v235, 15
	v_readlane_b32 s59, v235, 16
	v_readlane_b32 s60, v235, 17
	v_readlane_b32 s61, v235, 18
	v_readlane_b32 s62, v235, 19
	v_readlane_b32 s63, v235, 20
	s_waitcnt vmcnt(0)
	v_pk_add_f32 v[126:127], v[126:127], v[218:219]
	v_pk_add_f32 v[124:125], v[124:125], v[216:217]
	v_pk_add_f32 v[214:215], v[122:123], v[214:215]
	v_mul_f32_e32 v122, v125, v125
	v_mul_f32_e32 v123, v127, v127
	v_pk_add_f32 v[120:121], v[120:121], v[212:213]
	v_fmac_f32_e32 v122, v124, v124
	v_fmac_f32_e32 v123, v126, v126
	v_add_f32_e32 v122, v122, v123
	v_mul_f32_e32 v123, v121, v121
	v_mul_f32_e32 v212, v215, v215
	v_fmac_f32_e32 v123, v120, v120
	v_fmac_f32_e32 v212, v214, v214
	v_pk_add_f32 v[118:119], v[118:119], v[226:227]
	v_pk_add_f32 v[116:117], v[116:117], v[224:225]
	v_add_f32_e32 v123, v123, v212
	v_pk_add_f32 v[212:213], v[112:113], v[220:221]
	v_mul_f32_e32 v112, v117, v117
	v_mul_f32_e32 v113, v119, v119
	v_add_f32_e32 v216, v122, v123
	v_cvt_pk_bf16_f32 v122, v124, v125
	v_cvt_pk_bf16_f32 v123, v126, v127
	v_pk_add_f32 v[126:127], v[114:115], v[222:223]
	v_fmac_f32_e32 v112, v116, v116
	v_fmac_f32_e32 v113, v118, v118
	v_add_f32_e32 v112, v112, v113
	v_mul_f32_e32 v113, v213, v213
	v_mul_f32_e32 v114, v127, v127
	v_fmac_f32_e32 v113, v212, v212
	v_fmac_f32_e32 v114, v126, v126
	v_add_f32_e32 v113, v113, v114
	v_add_f32_e32 v112, v112, v113
	v_and_b32_e32 v113, 64, v211
	v_cvt_pk_bf16_f32 v124, v120, v121
	v_add_f32_e32 v115, v216, v112
	v_xor_b32_e32 v112, 16, v211
	v_add_u32_e32 v121, 64, v113
	v_cmp_lt_i32_e32 vcc, v112, v121
	v_lshlrev_b64 v[228:229], 11, v[196:197]
	v_cvt_pk_bf16_f32 v125, v214, v215
	s_nop 0
	v_cndmask_b32_e32 v112, v211, v112, vcc
	v_lshlrev_b32_e32 v120, 2, v112
	ds_bpermute_b32 v216, v120, v115
	v_lshl_add_u64 v[112:113], s[64:65], 0, v[228:229]
	v_lshl_add_u64 v[214:215], v[194:195], 1, v[112:113]
	v_xor_b32_e32 v113, 32, v211
	v_cmp_lt_i32_e32 vcc, v113, v121
	s_waitcnt lgkmcnt(0)
	v_add_f32_e32 v112, v115, v216
	global_store_dwordx4 v[214:215], v[122:125], off
	v_cndmask_b32_e32 v113, v211, v113, vcc
	v_lshlrev_b32_e32 v121, 2, v113
	ds_bpermute_b32 v113, v121, v112
	v_cvt_pk_bf16_f32 v114, v116, v117
	v_cvt_pk_bf16_f32 v115, v118, v119
	v_cvt_pk_bf16_f32 v116, v212, v213
	v_cvt_pk_bf16_f32 v117, v126, v127
	global_store_dwordx4 v[214:215], v[114:117], off offset:256
	s_and_saveexec_b64 s[22:23], s[2:3]
	s_cbranch_execz .LBB0_367
	v_lshlrev_b64 v[114:115], 6, v[196:197]
	v_lshl_add_u64 v[114:115], s[74:75], 0, v[114:115]
	v_lshl_add_u64 v[114:115], s[20:21], 2, v[114:115]
	s_lshl_b32 s6, s40, 2
	v_lshl_add_u64 v[114:115], v[114:115], 0, s[6:7]
	s_waitcnt lgkmcnt(0)
	v_add_f32_e32 v112, v112, v113
	global_store_dword v[114:115], v112, off

.LBB0_452:
	ds_read_b128 v[16:19], v212
	ds_read_b128 v[20:23], v212 offset:1024
	ds_read_b128 v[24:27], v212 offset:2048
	ds_read_b128 v[68:71], v212 offset:3072
	s_add_u32 s34, s8, 0x100
	s_addc_u32 s35, s9, 0
	s_cmp_eq_u32 s71, 12
	s_cselect_b32 s39, s63, s35
	s_cselect_b32 s38, s67, s34
	s_cselect_b32 s37, s11, s70
	s_cselect_b32 s36, s68, s69
	v_lshl_add_u64 v[176:177], s[8:9], 0, v[204:205]
	s_add_i32 m0, s46, 0xc000
	ds_read_b128 v[96:99], v213
	ds_read_b128 v[148:151], v213 offset:1024
	ds_read_b128 v[152:155], v213 offset:2048
	ds_read_b128 v[156:159], v213 offset:3072
	ds_read_b128 v[160:163], v213 offset:4096
	ds_read_b128 v[164:167], v213 offset:5120
	ds_read_b128 v[168:171], v213 offset:6144
	ds_read_b128 v[172:175], v213 offset:7168
	global_load_lds_dwordx4 v[176:177], off
	v_lshl_add_u64 v[176:177], s[8:9], 0, v[206:207]
	s_add_i32 m0, s46, 0xe000
	s_nop 0
	global_load_lds_dwordx4 v[176:177], off
	s_waitcnt lgkmcnt(8)
	s_barrier
	s_waitcnt lgkmcnt(0)
	s_waitcnt lgkmcnt(0)
	v_mfma_f32_16x16x32_bf16 v[112:115], v[16:19], v[96:99], v[112:115]
	v_mfma_f32_16x16x32_bf16 v[40:43], v[24:27], v[96:99], v[40:43]
	v_mfma_f32_16x16x32_bf16 v[108:111], v[16:19], v[152:155], v[108:111]
	v_mfma_f32_16x16x32_bf16 v[36:39], v[24:27], v[152:155], v[36:39]
	v_mfma_f32_16x16x32_bf16 v[144:147], v[16:19], v[160:163], v[144:147]
	v_mfma_f32_16x16x32_bf16 v[140:143], v[24:27], v[160:163], v[140:143]
	v_mfma_f32_16x16x32_bf16 v[136:139], v[16:19], v[168:171], v[136:139]
	v_mfma_f32_16x16x32_bf16 v[132:135], v[24:27], v[168:171], v[132:135]
	v_mfma_f32_16x16x32_bf16 v[112:115], v[20:23], v[148:151], v[112:115]
	v_mfma_f32_16x16x32_bf16 v[40:43], v[68:71], v[148:151], v[40:43]
	v_mfma_f32_16x16x32_bf16 v[108:111], v[20:23], v[156:159], v[108:111]
	v_mfma_f32_16x16x32_bf16 v[36:39], v[68:71], v[156:159], v[36:39]
	v_mfma_f32_16x16x32_bf16 v[144:147], v[20:23], v[164:167], v[144:147]
	v_mfma_f32_16x16x32_bf16 v[140:143], v[68:71], v[164:167], v[140:143]
	v_mfma_f32_16x16x32_bf16 v[136:139], v[20:23], v[172:175], v[136:139]
	v_mfma_f32_16x16x32_bf16 v[132:135], v[68:71], v[172:175], v[132:135]
	s_barrier
	s_add_i32 s8, s56, s45
	v_lshl_add_u64 v[222:223], s[36:37], 0, v[192:193]
	s_mov_b32 m0, s8
	ds_read_b128 v[176:179], v214
	ds_read_b128 v[180:183], v214 offset:1024
	ds_read_b128 v[184:187], v214 offset:2048
	ds_read_b128 v[218:221], v214 offset:3072
	global_load_lds_dwordx4 v[222:223], off
	v_lshl_add_u64 v[224:225], s[36:37], 0, v[198:199]
	s_add_i32 m0, s8, 0x2000
	s_nop 0
	global_load_lds_dwordx4 v[224:225], off
	s_barrier
	s_waitcnt lgkmcnt(0)
	s_waitcnt lgkmcnt(0)
	v_mfma_f32_16x16x32_bf16 v[104:107], v[176:179], v[96:99], v[104:107]
	v_mfma_f32_16x16x32_bf16 v[32:35], v[184:187], v[96:99], v[32:35]
	v_mfma_f32_16x16x32_bf16 v[28:31], v[184:187], v[152:155], v[28:31]
	v_mfma_f32_16x16x32_bf16 v[80:83], v[176:179], v[160:163], v[80:83]
	v_mfma_f32_16x16x32_bf16 v[92:95], v[184:187], v[160:163], v[92:95]
	v_mfma_f32_16x16x32_bf16 v[84:87], v[176:179], v[168:171], v[84:87]
	v_mfma_f32_16x16x32_bf16 v[88:91], v[184:187], v[168:171], v[88:91]
	v_mfma_f32_16x16x32_bf16 v[104:107], v[180:183], v[148:151], v[104:107]
	v_mfma_f32_16x16x32_bf16 v[32:35], v[218:221], v[148:151], v[32:35]
	v_mfma_f32_16x16x32_bf16 v[96:99], v[176:179], v[152:155], v[100:103]
	v_mfma_f32_16x16x32_bf16 v[28:31], v[218:221], v[156:159], v[28:31]
	v_mfma_f32_16x16x32_bf16 v[80:83], v[180:183], v[164:167], v[80:83]
	v_mfma_f32_16x16x32_bf16 v[92:95], v[218:221], v[164:167], v[92:95]
	v_mfma_f32_16x16x32_bf16 v[84:87], v[180:183], v[172:175], v[84:87]
	v_mfma_f32_16x16x32_bf16 v[88:91], v[218:221], v[172:175], v[88:91]
	v_mfma_f32_16x16x32_bf16 v[96:99], v[180:183], v[156:159], v[96:99]
	s_mov_b32 m0, s46
	v_lshl_add_u64 v[226:227], s[38:39], 0, v[194:195]
	s_barrier
	ds_read_b128 v[100:103], v213 offset:16384
	ds_read_b128 v[148:151], v213 offset:17408
	ds_read_b128 v[152:155], v213 offset:18432
	ds_read_b128 v[156:159], v213 offset:19456
	ds_read_b128 v[160:163], v213 offset:20480
	ds_read_b128 v[164:167], v213 offset:21504
	ds_read_b128 v[168:171], v213 offset:22528
	ds_read_b128 v[172:175], v213 offset:23552
	global_load_lds_dwordx4 v[226:227], off
	v_lshl_add_u64 v[228:229], s[38:39], 0, v[196:197]
	s_mov_b32 m0, s47
	s_nop 0
	global_load_lds_dwordx4 v[228:229], off
	s_barrier
	s_waitcnt lgkmcnt(0)
	s_waitcnt lgkmcnt(0)
	v_mfma_f32_16x16x32_bf16 v[76:79], v[16:19], v[100:103], v[76:79]
	v_mfma_f32_16x16x32_bf16 v[12:15], v[24:27], v[100:103], v[12:15]
	v_mfma_f32_16x16x32_bf16 v[72:75], v[16:19], v[152:155], v[72:75]
	v_mfma_f32_16x16x32_bf16 v[8:11], v[24:27], v[152:155], v[8:11]
	v_mfma_f32_16x16x32_bf16 v[128:131], v[16:19], v[160:163], v[128:131]
	v_mfma_f32_16x16x32_bf16 v[124:127], v[24:27], v[160:163], v[124:127]
	v_mfma_f32_16x16x32_bf16 v[16:19], v[16:19], v[168:171], v[120:123]
	v_mfma_f32_16x16x32_bf16 v[76:79], v[20:23], v[148:151], v[76:79]
	v_mfma_f32_16x16x32_bf16 v[12:15], v[68:71], v[148:151], v[12:15]
	v_mfma_f32_16x16x32_bf16 v[72:75], v[20:23], v[156:159], v[72:75]
	v_mfma_f32_16x16x32_bf16 v[8:11], v[68:71], v[156:159], v[8:11]
	v_mfma_f32_16x16x32_bf16 v[128:131], v[20:23], v[164:167], v[128:131]
	v_mfma_f32_16x16x32_bf16 v[124:127], v[68:71], v[164:167], v[124:127]
	v_mfma_f32_16x16x32_bf16 v[16:19], v[20:23], v[172:175], v[16:19]
	v_mfma_f32_16x16x32_bf16 v[20:23], v[24:27], v[168:171], v[116:119]
	v_mfma_f32_16x16x32_bf16 v[20:23], v[68:71], v[172:175], v[20:23]
	s_barrier
	s_add_u32 s8, s36, 0x40000
	s_addc_u32 s9, s37, 0
	s_add_i32 s78, s57, s45
	v_lshl_add_u64 v[24:25], s[8:9], 0, v[192:193]
	s_mov_b32 m0, s78
	s_nop 0
	global_load_lds_dwordx4 v[24:25], off
	v_lshl_add_u64 v[24:25], s[8:9], 0, v[198:199]
	s_add_i32 m0, s78, 0x2000
	s_nop 0
	global_load_lds_dwordx4 v[24:25], off
	s_waitcnt vmcnt(6)
	s_barrier
	v_mfma_f32_16x16x32_bf16 v[4:7], v[184:187], v[100:103], v[4:7]
	v_mfma_f32_16x16x32_bf16 v[60:63], v[176:179], v[152:155], v[60:63]
	v_mfma_f32_16x16x32_bf16 v[0:3], v[184:187], v[152:155], v[0:3]
	v_mfma_f32_16x16x32_bf16 v[44:47], v[176:179], v[160:163], v[44:47]
	v_mfma_f32_16x16x32_bf16 v[48:51], v[184:187], v[160:163], v[48:51]
	v_mfma_f32_16x16x32_bf16 v[52:55], v[176:179], v[168:171], v[52:55]
	v_mfma_f32_16x16x32_bf16 v[56:59], v[184:187], v[168:171], v[56:59]
	v_mfma_f32_16x16x32_bf16 v[24:27], v[176:179], v[100:103], v[64:67]
	v_mfma_f32_16x16x32_bf16 v[4:7], v[218:221], v[148:151], v[4:7]
	v_mfma_f32_16x16x32_bf16 v[60:63], v[180:183], v[156:159], v[60:63]
	v_mfma_f32_16x16x32_bf16 v[0:3], v[218:221], v[156:159], v[0:3]
	v_mfma_f32_16x16x32_bf16 v[44:47], v[180:183], v[164:167], v[44:47]
	v_mfma_f32_16x16x32_bf16 v[48:51], v[218:221], v[164:167], v[48:51]
	v_mfma_f32_16x16x32_bf16 v[52:55], v[180:183], v[172:175], v[52:55]
	v_mfma_f32_16x16x32_bf16 v[56:59], v[218:221], v[172:175], v[56:59]
	v_mfma_f32_16x16x32_bf16 v[24:27], v[180:183], v[148:151], v[24:27]
	s_add_i32 s78, 0, 0x18000
	v_add_u32_e32 v100, s78, v208
	s_barrier
	ds_read_b128 v[64:67], v100
	ds_read_b128 v[68:71], v100 offset:1024
	ds_read_b128 v[116:119], v100 offset:2048
	ds_read_b128 v[148:151], v100 offset:3072
	s_add_u32 s8, s38, 0x40000
	s_addc_u32 s9, s39, 0
	s_mov_b32 m0, s48
	v_lshl_add_u64 v[176:177], s[8:9], 0, v[194:195]
	ds_read_b128 v[100:103], v213 offset:32768
	ds_read_b128 v[120:123], v213 offset:33792
	ds_read_b128 v[152:155], v213 offset:34816
	ds_read_b128 v[156:159], v213 offset:35840
	ds_read_b128 v[160:163], v213 offset:36864
	ds_read_b128 v[164:167], v213 offset:37888
	ds_read_b128 v[168:171], v213 offset:38912
	ds_read_b128 v[172:175], v213 offset:39936
	global_load_lds_dwordx4 v[176:177], off
	v_lshl_add_u64 v[176:177], s[8:9], 0, v[196:197]
	s_mov_b32 m0, s49
	s_nop 0
	global_load_lds_dwordx4 v[176:177], off
	s_waitcnt lgkmcnt(8)
	s_barrier
	s_waitcnt lgkmcnt(0)
	s_waitcnt lgkmcnt(0)
	v_mfma_f32_16x16x32_bf16 v[112:115], v[64:67], v[100:103], v[112:115]
	v_mfma_f32_16x16x32_bf16 v[40:43], v[116:119], v[100:103], v[40:43]
	v_mfma_f32_16x16x32_bf16 v[108:111], v[64:67], v[152:155], v[108:111]
	v_mfma_f32_16x16x32_bf16 v[36:39], v[116:119], v[152:155], v[36:39]
	v_mfma_f32_16x16x32_bf16 v[144:147], v[64:67], v[160:163], v[144:147]
	v_mfma_f32_16x16x32_bf16 v[140:143], v[116:119], v[160:163], v[140:143]
	v_mfma_f32_16x16x32_bf16 v[136:139], v[64:67], v[168:171], v[136:139]
	v_mfma_f32_16x16x32_bf16 v[132:135], v[116:119], v[168:171], v[132:135]
	v_mfma_f32_16x16x32_bf16 v[112:115], v[68:71], v[120:123], v[112:115]
	v_mfma_f32_16x16x32_bf16 v[40:43], v[148:151], v[120:123], v[40:43]
	v_mfma_f32_16x16x32_bf16 v[108:111], v[68:71], v[156:159], v[108:111]
	v_mfma_f32_16x16x32_bf16 v[36:39], v[148:151], v[156:159], v[36:39]
	v_mfma_f32_16x16x32_bf16 v[144:147], v[68:71], v[164:167], v[144:147]
	v_mfma_f32_16x16x32_bf16 v[140:143], v[148:151], v[164:167], v[140:143]
	v_mfma_f32_16x16x32_bf16 v[136:139], v[68:71], v[172:175], v[136:139]
	v_mfma_f32_16x16x32_bf16 v[132:135], v[148:151], v[172:175], v[132:135]
	s_barrier
	s_add_i32 s38, 0, 0x1c000
	s_add_i32 s8, s78, s45
	v_add_u32_e32 v217, s38, v208
	v_lshl_add_u64 v[222:223], v[222:223], 0, s[20:21]
	s_mov_b32 m0, s8
	ds_read_b128 v[176:179], v217
	ds_read_b128 v[180:183], v217 offset:1024
	ds_read_b128 v[184:187], v217 offset:2048
	ds_read_b128 v[218:221], v217 offset:3072
	global_load_lds_dwordx4 v[222:223], off
	v_lshl_add_u64 v[222:223], v[224:225], 0, s[20:21]
	s_add_i32 m0, s8, 0x2000
	s_nop 0
	global_load_lds_dwordx4 v[222:223], off
	s_barrier
	s_waitcnt lgkmcnt(0)
	s_waitcnt lgkmcnt(0)
	v_mfma_f32_16x16x32_bf16 v[104:107], v[176:179], v[100:103], v[104:107]
	v_mfma_f32_16x16x32_bf16 v[32:35], v[184:187], v[100:103], v[32:35]
	v_mfma_f32_16x16x32_bf16 v[96:99], v[176:179], v[152:155], v[96:99]
	v_mfma_f32_16x16x32_bf16 v[28:31], v[184:187], v[152:155], v[28:31]
	v_mfma_f32_16x16x32_bf16 v[80:83], v[176:179], v[160:163], v[80:83]
	v_mfma_f32_16x16x32_bf16 v[92:95], v[184:187], v[160:163], v[92:95]
	v_mfma_f32_16x16x32_bf16 v[84:87], v[176:179], v[168:171], v[84:87]
	v_mfma_f32_16x16x32_bf16 v[88:91], v[184:187], v[168:171], v[88:91]
	v_mfma_f32_16x16x32_bf16 v[104:107], v[180:183], v[120:123], v[104:107]
	v_mfma_f32_16x16x32_bf16 v[32:35], v[218:221], v[120:123], v[32:35]
	v_mfma_f32_16x16x32_bf16 v[100:103], v[180:183], v[156:159], v[96:99]
	v_mfma_f32_16x16x32_bf16 v[28:31], v[218:221], v[156:159], v[28:31]
	v_mfma_f32_16x16x32_bf16 v[80:83], v[180:183], v[164:167], v[80:83]
	v_mfma_f32_16x16x32_bf16 v[92:95], v[218:221], v[164:167], v[92:95]
	v_mfma_f32_16x16x32_bf16 v[84:87], v[180:183], v[172:175], v[84:87]
	v_mfma_f32_16x16x32_bf16 v[88:91], v[218:221], v[172:175], v[88:91]
	s_mov_b32 m0, s53
	v_lshl_add_u64 v[120:121], v[226:227], 0, s[20:21]
	s_barrier
	ds_read_b128 v[96:99], v213 offset:49152
	ds_read_b128 v[152:155], v213 offset:50176
	ds_read_b128 v[156:159], v213 offset:51200
	ds_read_b128 v[160:163], v213 offset:52224
	ds_read_b128 v[164:167], v213 offset:53248
	ds_read_b128 v[168:171], v213 offset:54272
	ds_read_b128 v[172:175], v213 offset:55296
	ds_read_b128 v[222:225], v213 offset:56320
	global_load_lds_dwordx4 v[120:121], off
	v_lshl_add_u64 v[120:121], v[228:229], 0, s[20:21]
	s_mov_b32 m0, s54
	s_nop 0
	global_load_lds_dwordx4 v[120:121], off
	s_barrier
	s_waitcnt lgkmcnt(0)
	s_waitcnt lgkmcnt(0)
	v_mfma_f32_16x16x32_bf16 v[120:123], v[64:67], v[164:167], v[128:131]
	v_mfma_f32_16x16x32_bf16 v[128:131], v[68:71], v[168:171], v[120:123]
	v_mfma_f32_16x16x32_bf16 v[120:123], v[116:119], v[164:167], v[124:127]
	v_mfma_f32_16x16x32_bf16 v[16:19], v[64:67], v[172:175], v[16:19]
	v_mfma_f32_16x16x32_bf16 v[76:79], v[64:67], v[96:99], v[76:79]
	v_mfma_f32_16x16x32_bf16 v[12:15], v[116:119], v[96:99], v[12:15]
	v_mfma_f32_16x16x32_bf16 v[72:75], v[64:67], v[156:159], v[72:75]
	v_mfma_f32_16x16x32_bf16 v[8:11], v[116:119], v[156:159], v[8:11]
	v_mfma_f32_16x16x32_bf16 v[124:127], v[148:151], v[168:171], v[120:123]
	v_mfma_f32_16x16x32_bf16 v[120:123], v[68:71], v[222:225], v[16:19]
	v_mfma_f32_16x16x32_bf16 v[16:19], v[116:119], v[172:175], v[20:23]
	v_mfma_f32_16x16x32_bf16 v[76:79], v[68:71], v[152:155], v[76:79]
	v_mfma_f32_16x16x32_bf16 v[12:15], v[148:151], v[152:155], v[12:15]
	v_mfma_f32_16x16x32_bf16 v[72:75], v[68:71], v[160:163], v[72:75]
	v_mfma_f32_16x16x32_bf16 v[8:11], v[148:151], v[160:163], v[8:11]
	v_mfma_f32_16x16x32_bf16 v[116:119], v[148:151], v[222:225], v[16:19]
	s_barrier
	s_add_u32 s8, s36, 0x40080
	s_addc_u32 s9, s37, 0
	s_add_i32 s36, s38, s45
	v_lshl_add_u64 v[16:17], s[8:9], 0, v[192:193]
	s_mov_b32 m0, s36
	s_nop 0
	global_load_lds_dwordx4 v[16:17], off
	v_lshl_add_u64 v[16:17], s[8:9], 0, v[198:199]
	s_add_i32 m0, s36, 0x2000
	s_nop 0
	global_load_lds_dwordx4 v[16:17], off
	s_waitcnt vmcnt(6)
	s_barrier
	v_mfma_f32_16x16x32_bf16 v[16:19], v[176:179], v[96:99], v[24:27]
	v_mfma_f32_16x16x32_bf16 v[64:67], v[180:183], v[152:155], v[16:19]
	v_mfma_f32_16x16x32_bf16 v[16:19], v[176:179], v[156:159], v[60:63]
	v_mfma_f32_16x16x32_bf16 v[60:63], v[180:183], v[160:163], v[16:19]
	v_mfma_f32_16x16x32_bf16 v[16:19], v[176:179], v[164:167], v[44:47]
	v_mfma_f32_16x16x32_bf16 v[44:47], v[180:183], v[168:171], v[16:19]
	v_mfma_f32_16x16x32_bf16 v[16:19], v[184:187], v[164:167], v[48:51]
	v_mfma_f32_16x16x32_bf16 v[48:51], v[218:221], v[168:171], v[16:19]
	v_mfma_f32_16x16x32_bf16 v[16:19], v[176:179], v[172:175], v[52:55]
	v_mfma_f32_16x16x32_bf16 v[4:7], v[184:187], v[96:99], v[4:7]
	v_mfma_f32_16x16x32_bf16 v[0:3], v[184:187], v[156:159], v[0:3]
	v_mfma_f32_16x16x32_bf16 v[52:55], v[180:183], v[222:225], v[16:19]
	v_mfma_f32_16x16x32_bf16 v[16:19], v[184:187], v[172:175], v[56:59]
	v_mfma_f32_16x16x32_bf16 v[4:7], v[218:221], v[152:155], v[4:7]
	v_mfma_f32_16x16x32_bf16 v[0:3], v[218:221], v[160:163], v[0:3]
	v_mfma_f32_16x16x32_bf16 v[56:59], v[218:221], v[222:225], v[16:19]
	s_add_i32 s71, s71, 2
	s_add_u32 s69, s69, 0x100
	s_addc_u32 s70, s70, 0
	s_cmp_gt_u32 s71, 13
	s_mov_b64 s[8:9], s[34:35]
	s_barrier
	s_cbranch_scc0 .LBB0_452
	v_cndmask_b32_e64 v16, 0, 1, s[30:31]
	v_cmp_ne_u32_e64 s[8:9], 1, v16
	s_andn2_b64 vcc, exec, s[30:31]
	s_cbranch_vccnz .LBB0_457
	v_mov_b32_e32 v16, 0
	v_mov_b32_e32 v17, 0
	v_mov_b32_e32 v18, 0
	v_mov_b32_e32 v19, 0
	s_and_saveexec_b64 s[30:31], s[2:3]
	s_cbranch_execz .LBB0_456
	s_lshl_b32 s34, s10, 7
	s_ashr_i32 s35, s34, 31
	v_lshl_add_u64 v[16:17], s[34:35], 2, v[202:203]
	global_load_dwordx4 v[16:19], v[16:17], off

.LBB0_554:
	ds_read_b128 v[128:131], v190
	ds_read_b128 v[132:135], v190 offset:1024
	ds_read_b128 v[136:139], v190 offset:2048
	ds_read_b128 v[140:143], v190 offset:3072
	s_add_u32 s18, s14, 0x100
	s_addc_u32 s19, s15, 0
	s_cmp_eq_u32 s51, 40
	s_cselect_b32 s23, s1, s19
	s_cselect_b32 s22, s0, s18
	s_cselect_b32 s21, s7, s50
	s_cselect_b32 s20, s6, s49
	v_lshl_add_u64 v[184:185], s[14:15], 0, v[160:161]
	s_add_i32 m0, s34, 0xc000
	ds_read_b128 v[144:147], v191
	ds_read_b128 v[148:151], v191 offset:1024
	ds_read_b128 v[168:171], v191 offset:2048
	ds_read_b128 v[172:175], v191 offset:3072
	ds_read_b128 v[176:179], v191 offset:4096
	ds_read_b128 v[180:183], v191 offset:5120
	ds_read_b128 v[194:197], v191 offset:6144
	ds_read_b128 v[198:201], v191 offset:7168
	global_load_lds_dwordx4 v[184:185], off
	v_lshl_add_u64 v[184:185], s[14:15], 0, v[162:163]
	s_add_i32 m0, s34, 0xe000
	s_nop 0
	global_load_lds_dwordx4 v[184:185], off
	s_waitcnt lgkmcnt(8)
	s_barrier
	s_waitcnt lgkmcnt(0)
	s_waitcnt lgkmcnt(0)
	v_mfma_f32_16x16x32_bf16 v[124:127], v[128:131], v[144:147], v[124:127]
	v_mfma_f32_16x16x32_bf16 v[120:123], v[136:139], v[144:147], v[120:123]
	v_mfma_f32_16x16x32_bf16 v[108:111], v[128:131], v[168:171], v[108:111]
	v_mfma_f32_16x16x32_bf16 v[104:107], v[136:139], v[168:171], v[104:107]
	v_mfma_f32_16x16x32_bf16 v[92:95], v[128:131], v[176:179], v[92:95]
	v_mfma_f32_16x16x32_bf16 v[88:91], v[136:139], v[176:179], v[88:91]
	v_mfma_f32_16x16x32_bf16 v[76:79], v[128:131], v[194:197], v[76:79]
	v_mfma_f32_16x16x32_bf16 v[72:75], v[136:139], v[194:197], v[72:75]
	v_mfma_f32_16x16x32_bf16 v[124:127], v[132:135], v[148:151], v[124:127]
	v_mfma_f32_16x16x32_bf16 v[120:123], v[140:143], v[148:151], v[120:123]
	v_mfma_f32_16x16x32_bf16 v[108:111], v[132:135], v[172:175], v[108:111]
	v_mfma_f32_16x16x32_bf16 v[104:107], v[140:143], v[172:175], v[104:107]
	v_mfma_f32_16x16x32_bf16 v[92:95], v[132:135], v[180:183], v[92:95]
	v_mfma_f32_16x16x32_bf16 v[88:91], v[140:143], v[180:183], v[88:91]
	v_mfma_f32_16x16x32_bf16 v[76:79], v[132:135], v[198:201], v[76:79]
	v_mfma_f32_16x16x32_bf16 v[72:75], v[140:143], v[198:201], v[72:75]
	s_barrier
	s_add_i32 s14, s43, s31
	v_lshl_add_u64 v[184:185], s[20:21], 0, v[154:155]
	s_mov_b32 m0, s14
	ds_read_b128 v[202:205], v192
	ds_read_b128 v[206:209], v192 offset:1024
	ds_read_b128 v[210:213], v192 offset:2048
	ds_read_b128 v[214:217], v192 offset:3072
	global_load_lds_dwordx4 v[184:185], off
	v_lshl_add_u64 v[218:219], s[20:21], 0, v[158:159]
	s_add_i32 m0, s14, 0x2000
	s_nop 0
	global_load_lds_dwordx4 v[218:219], off
	s_barrier
	s_waitcnt lgkmcnt(0)
	s_waitcnt lgkmcnt(0)
	v_mfma_f32_16x16x32_bf16 v[116:119], v[202:205], v[144:147], v[116:119]
	v_mfma_f32_16x16x32_bf16 v[112:115], v[210:213], v[144:147], v[112:115]
	v_mfma_f32_16x16x32_bf16 v[100:103], v[202:205], v[168:171], v[100:103]
	v_mfma_f32_16x16x32_bf16 v[96:99], v[210:213], v[168:171], v[96:99]
	v_mfma_f32_16x16x32_bf16 v[84:87], v[202:205], v[176:179], v[84:87]
	v_mfma_f32_16x16x32_bf16 v[80:83], v[210:213], v[176:179], v[80:83]
	v_mfma_f32_16x16x32_bf16 v[68:71], v[202:205], v[194:197], v[68:71]
	v_mfma_f32_16x16x32_bf16 v[64:67], v[210:213], v[194:197], v[64:67]
	v_mfma_f32_16x16x32_bf16 v[116:119], v[206:209], v[148:151], v[116:119]
	v_mfma_f32_16x16x32_bf16 v[112:115], v[214:217], v[148:151], v[112:115]
	v_mfma_f32_16x16x32_bf16 v[100:103], v[206:209], v[172:175], v[100:103]
	v_mfma_f32_16x16x32_bf16 v[96:99], v[214:217], v[172:175], v[96:99]
	v_mfma_f32_16x16x32_bf16 v[84:87], v[206:209], v[180:183], v[84:87]
	v_mfma_f32_16x16x32_bf16 v[80:83], v[214:217], v[180:183], v[80:83]
	v_mfma_f32_16x16x32_bf16 v[68:71], v[206:209], v[198:201], v[68:71]
	v_mfma_f32_16x16x32_bf16 v[64:67], v[214:217], v[198:201], v[64:67]
	s_mov_b32 m0, s34
	v_lshl_add_u64 v[220:221], s[22:23], 0, v[152:153]
	s_barrier
	ds_read_b128 v[144:147], v191 offset:16384
	ds_read_b128 v[148:151], v191 offset:17408
	ds_read_b128 v[168:171], v191 offset:18432
	ds_read_b128 v[172:175], v191 offset:19456
	ds_read_b128 v[176:179], v191 offset:20480
	ds_read_b128 v[180:183], v191 offset:21504
	ds_read_b128 v[194:197], v191 offset:22528
	ds_read_b128 v[198:201], v191 offset:23552
	global_load_lds_dwordx4 v[220:221], off
	v_lshl_add_u64 v[222:223], s[22:23], 0, v[156:157]
	s_mov_b32 m0, s35
	s_nop 0
	global_load_lds_dwordx4 v[222:223], off
	s_barrier
	s_waitcnt lgkmcnt(0)
	s_waitcnt lgkmcnt(0)
	v_mfma_f32_16x16x32_bf16 v[60:63], v[128:131], v[144:147], v[60:63]
	v_mfma_f32_16x16x32_bf16 v[56:59], v[136:139], v[144:147], v[56:59]
	v_mfma_f32_16x16x32_bf16 v[44:47], v[128:131], v[168:171], v[44:47]
	v_mfma_f32_16x16x32_bf16 v[40:43], v[136:139], v[168:171], v[40:43]
	v_mfma_f32_16x16x32_bf16 v[28:31], v[128:131], v[176:179], v[28:31]
	v_mfma_f32_16x16x32_bf16 v[24:27], v[136:139], v[176:179], v[24:27]
	v_mfma_f32_16x16x32_bf16 v[12:15], v[128:131], v[194:197], v[12:15]
	v_mfma_f32_16x16x32_bf16 v[8:11], v[136:139], v[194:197], v[8:11]
	v_mfma_f32_16x16x32_bf16 v[60:63], v[132:135], v[148:151], v[60:63]
	v_mfma_f32_16x16x32_bf16 v[56:59], v[140:143], v[148:151], v[56:59]
	v_mfma_f32_16x16x32_bf16 v[44:47], v[132:135], v[172:175], v[44:47]
	v_mfma_f32_16x16x32_bf16 v[40:43], v[140:143], v[172:175], v[40:43]
	v_mfma_f32_16x16x32_bf16 v[28:31], v[132:135], v[180:183], v[28:31]
	v_mfma_f32_16x16x32_bf16 v[24:27], v[140:143], v[180:183], v[24:27]
	v_mfma_f32_16x16x32_bf16 v[12:15], v[132:135], v[198:201], v[12:15]
	v_mfma_f32_16x16x32_bf16 v[8:11], v[140:143], v[198:201], v[8:11]
	s_barrier
	s_add_u32 s14, s20, 0xb0000
	s_addc_u32 s15, s21, 0
	s_add_i32 s52, s44, s31
	v_lshl_add_u64 v[128:129], s[14:15], 0, v[154:155]
	s_mov_b32 m0, s52
	s_nop 0
	global_load_lds_dwordx4 v[128:129], off
	v_lshl_add_u64 v[128:129], s[14:15], 0, v[158:159]
	s_add_i32 m0, s52, 0x2000
	s_nop 0
	global_load_lds_dwordx4 v[128:129], off
	s_waitcnt vmcnt(6)
	s_barrier
	v_mfma_f32_16x16x32_bf16 v[52:55], v[202:205], v[144:147], v[52:55]
	v_mfma_f32_16x16x32_bf16 v[48:51], v[210:213], v[144:147], v[48:51]
	v_mfma_f32_16x16x32_bf16 v[36:39], v[202:205], v[168:171], v[36:39]
	v_mfma_f32_16x16x32_bf16 v[32:35], v[210:213], v[168:171], v[32:35]
	v_mfma_f32_16x16x32_bf16 v[20:23], v[202:205], v[176:179], v[20:23]
	v_mfma_f32_16x16x32_bf16 v[16:19], v[210:213], v[176:179], v[16:19]
	v_mfma_f32_16x16x32_bf16 v[4:7], v[202:205], v[194:197], v[4:7]
	v_mfma_f32_16x16x32_bf16 v[0:3], v[210:213], v[194:197], v[0:3]
	v_mfma_f32_16x16x32_bf16 v[52:55], v[206:209], v[148:151], v[52:55]
	v_mfma_f32_16x16x32_bf16 v[48:51], v[214:217], v[148:151], v[48:51]
	v_mfma_f32_16x16x32_bf16 v[36:39], v[206:209], v[172:175], v[36:39]
	v_mfma_f32_16x16x32_bf16 v[32:35], v[214:217], v[172:175], v[32:35]
	v_mfma_f32_16x16x32_bf16 v[20:23], v[206:209], v[180:183], v[20:23]
	v_mfma_f32_16x16x32_bf16 v[16:19], v[214:217], v[180:183], v[16:19]
	v_mfma_f32_16x16x32_bf16 v[4:7], v[206:209], v[198:201], v[4:7]
	v_mfma_f32_16x16x32_bf16 v[0:3], v[214:217], v[198:201], v[0:3]
	s_add_i32 s52, 0, 0x18000
	v_add_u32_e32 v140, s52, v187
	s_barrier
	ds_read_b128 v[128:131], v140
	ds_read_b128 v[132:135], v140 offset:1024
	ds_read_b128 v[136:139], v140 offset:2048
	ds_read_b128 v[140:143], v140 offset:3072
	s_add_u32 s14, s22, 0xb0000
	s_addc_u32 s15, s23, 0
	s_mov_b32 m0, s36
	v_lshl_add_u64 v[202:203], s[14:15], 0, v[152:153]
	ds_read_b128 v[144:147], v191 offset:32768
	ds_read_b128 v[148:151], v191 offset:33792
	ds_read_b128 v[168:171], v191 offset:34816
	ds_read_b128 v[172:175], v191 offset:35840
	ds_read_b128 v[176:179], v191 offset:36864
	ds_read_b128 v[180:183], v191 offset:37888
	ds_read_b128 v[194:197], v191 offset:38912
	ds_read_b128 v[198:201], v191 offset:39936
	global_load_lds_dwordx4 v[202:203], off
	v_lshl_add_u64 v[202:203], s[14:15], 0, v[156:157]
	s_mov_b32 m0, s37
	s_nop 0
	global_load_lds_dwordx4 v[202:203], off
	s_waitcnt lgkmcnt(8)
	s_barrier
	s_waitcnt lgkmcnt(0)
	s_waitcnt lgkmcnt(0)
	v_mfma_f32_16x16x32_bf16 v[124:127], v[128:131], v[144:147], v[124:127]
	v_mfma_f32_16x16x32_bf16 v[120:123], v[136:139], v[144:147], v[120:123]
	v_mfma_f32_16x16x32_bf16 v[108:111], v[128:131], v[168:171], v[108:111]
	v_mfma_f32_16x16x32_bf16 v[104:107], v[136:139], v[168:171], v[104:107]
	v_mfma_f32_16x16x32_bf16 v[92:95], v[128:131], v[176:179], v[92:95]
	v_mfma_f32_16x16x32_bf16 v[88:91], v[136:139], v[176:179], v[88:91]
	v_mfma_f32_16x16x32_bf16 v[76:79], v[128:131], v[194:197], v[76:79]
	v_mfma_f32_16x16x32_bf16 v[72:75], v[136:139], v[194:197], v[72:75]
	v_mfma_f32_16x16x32_bf16 v[124:127], v[132:135], v[148:151], v[124:127]
	v_mfma_f32_16x16x32_bf16 v[120:123], v[140:143], v[148:151], v[120:123]
	v_mfma_f32_16x16x32_bf16 v[108:111], v[132:135], v[172:175], v[108:111]
	v_mfma_f32_16x16x32_bf16 v[104:107], v[140:143], v[172:175], v[104:107]
	v_mfma_f32_16x16x32_bf16 v[92:95], v[132:135], v[180:183], v[92:95]
	v_mfma_f32_16x16x32_bf16 v[88:91], v[140:143], v[180:183], v[88:91]
	v_mfma_f32_16x16x32_bf16 v[76:79], v[132:135], v[198:201], v[76:79]
	v_mfma_f32_16x16x32_bf16 v[72:75], v[140:143], v[198:201], v[72:75]
	s_barrier
	s_add_i32 s22, 0, 0x1c000
	s_add_i32 s14, s52, s31
	v_add_u32_e32 v214, s22, v187
	v_lshl_add_u64 v[184:185], v[184:185], 0, s[12:13]
	s_mov_b32 m0, s14
	ds_read_b128 v[202:205], v214
	ds_read_b128 v[206:209], v214 offset:1024
	ds_read_b128 v[210:213], v214 offset:2048
	ds_read_b128 v[214:217], v214 offset:3072
	global_load_lds_dwordx4 v[184:185], off
	v_lshl_add_u64 v[184:185], v[218:219], 0, s[12:13]
	s_add_i32 m0, s14, 0x2000
	s_nop 0
	global_load_lds_dwordx4 v[184:185], off
	s_barrier
	s_waitcnt lgkmcnt(0)
	s_waitcnt lgkmcnt(0)
	v_mfma_f32_16x16x32_bf16 v[116:119], v[202:205], v[144:147], v[116:119]
	v_mfma_f32_16x16x32_bf16 v[112:115], v[210:213], v[144:147], v[112:115]
	v_mfma_f32_16x16x32_bf16 v[100:103], v[202:205], v[168:171], v[100:103]
	v_mfma_f32_16x16x32_bf16 v[96:99], v[210:213], v[168:171], v[96:99]
	v_mfma_f32_16x16x32_bf16 v[84:87], v[202:205], v[176:179], v[84:87]
	v_mfma_f32_16x16x32_bf16 v[80:83], v[210:213], v[176:179], v[80:83]
	v_mfma_f32_16x16x32_bf16 v[68:71], v[202:205], v[194:197], v[68:71]
	v_mfma_f32_16x16x32_bf16 v[64:67], v[210:213], v[194:197], v[64:67]
	v_mfma_f32_16x16x32_bf16 v[116:119], v[206:209], v[148:151], v[116:119]
	v_mfma_f32_16x16x32_bf16 v[112:115], v[214:217], v[148:151], v[112:115]
	v_mfma_f32_16x16x32_bf16 v[100:103], v[206:209], v[172:175], v[100:103]
	v_mfma_f32_16x16x32_bf16 v[96:99], v[214:217], v[172:175], v[96:99]
	v_mfma_f32_16x16x32_bf16 v[84:87], v[206:209], v[180:183], v[84:87]
	v_mfma_f32_16x16x32_bf16 v[80:83], v[214:217], v[180:183], v[80:83]
	v_mfma_f32_16x16x32_bf16 v[68:71], v[206:209], v[198:201], v[68:71]
	v_mfma_f32_16x16x32_bf16 v[64:67], v[214:217], v[198:201], v[64:67]
	s_mov_b32 m0, s39
	v_lshl_add_u64 v[184:185], v[220:221], 0, s[12:13]
	s_barrier
	ds_read_b128 v[144:147], v191 offset:49152
	ds_read_b128 v[148:151], v191 offset:50176
	ds_read_b128 v[168:171], v191 offset:51200
	ds_read_b128 v[172:175], v191 offset:52224
	ds_read_b128 v[176:179], v191 offset:53248
	ds_read_b128 v[180:183], v191 offset:54272
	ds_read_b128 v[194:197], v191 offset:55296
	ds_read_b128 v[198:201], v191 offset:56320
	global_load_lds_dwordx4 v[184:185], off
	v_lshl_add_u64 v[184:185], v[222:223], 0, s[12:13]
	s_mov_b32 m0, s40
	s_nop 0
	global_load_lds_dwordx4 v[184:185], off
	s_barrier
	s_waitcnt lgkmcnt(0)
	s_waitcnt lgkmcnt(0)
	v_mfma_f32_16x16x32_bf16 v[60:63], v[128:131], v[144:147], v[60:63]
	v_mfma_f32_16x16x32_bf16 v[56:59], v[136:139], v[144:147], v[56:59]
	v_mfma_f32_16x16x32_bf16 v[44:47], v[128:131], v[168:171], v[44:47]
	v_mfma_f32_16x16x32_bf16 v[40:43], v[136:139], v[168:171], v[40:43]
	v_mfma_f32_16x16x32_bf16 v[28:31], v[128:131], v[176:179], v[28:31]
	v_mfma_f32_16x16x32_bf16 v[24:27], v[136:139], v[176:179], v[24:27]
	v_mfma_f32_16x16x32_bf16 v[12:15], v[128:131], v[194:197], v[12:15]
	v_mfma_f32_16x16x32_bf16 v[8:11], v[136:139], v[194:197], v[8:11]
	v_mfma_f32_16x16x32_bf16 v[60:63], v[132:135], v[148:151], v[60:63]
	v_mfma_f32_16x16x32_bf16 v[56:59], v[140:143], v[148:151], v[56:59]
	v_mfma_f32_16x16x32_bf16 v[44:47], v[132:135], v[172:175], v[44:47]
	v_mfma_f32_16x16x32_bf16 v[40:43], v[140:143], v[172:175], v[40:43]
	v_mfma_f32_16x16x32_bf16 v[28:31], v[132:135], v[180:183], v[28:31]
	v_mfma_f32_16x16x32_bf16 v[24:27], v[140:143], v[180:183], v[24:27]
	v_mfma_f32_16x16x32_bf16 v[12:15], v[132:135], v[198:201], v[12:15]
	v_mfma_f32_16x16x32_bf16 v[8:11], v[140:143], v[198:201], v[8:11]
	s_barrier
	s_add_u32 s14, s20, 0xb0080
	s_addc_u32 s15, s21, 0
	s_add_i32 s20, s22, s31
	v_lshl_add_u64 v[128:129], s[14:15], 0, v[154:155]
	s_mov_b32 m0, s20
	s_nop 0
	global_load_lds_dwordx4 v[128:129], off
	v_lshl_add_u64 v[128:129], s[14:15], 0, v[158:159]
	s_add_i32 m0, s20, 0x2000
	s_nop 0
	global_load_lds_dwordx4 v[128:129], off
	s_waitcnt vmcnt(6)
	s_barrier
	v_mfma_f32_16x16x32_bf16 v[52:55], v[202:205], v[144:147], v[52:55]
	v_mfma_f32_16x16x32_bf16 v[48:51], v[210:213], v[144:147], v[48:51]
	v_mfma_f32_16x16x32_bf16 v[36:39], v[202:205], v[168:171], v[36:39]
	v_mfma_f32_16x16x32_bf16 v[32:35], v[210:213], v[168:171], v[32:35]
	v_mfma_f32_16x16x32_bf16 v[20:23], v[202:205], v[176:179], v[20:23]
	v_mfma_f32_16x16x32_bf16 v[16:19], v[210:213], v[176:179], v[16:19]
	v_mfma_f32_16x16x32_bf16 v[4:7], v[202:205], v[194:197], v[4:7]
	v_mfma_f32_16x16x32_bf16 v[0:3], v[210:213], v[194:197], v[0:3]
	v_mfma_f32_16x16x32_bf16 v[52:55], v[206:209], v[148:151], v[52:55]
	v_mfma_f32_16x16x32_bf16 v[48:51], v[214:217], v[148:151], v[48:51]
	v_mfma_f32_16x16x32_bf16 v[36:39], v[206:209], v[172:175], v[36:39]
	v_mfma_f32_16x16x32_bf16 v[32:35], v[214:217], v[172:175], v[32:35]
	v_mfma_f32_16x16x32_bf16 v[20:23], v[206:209], v[180:183], v[20:23]
	v_mfma_f32_16x16x32_bf16 v[16:19], v[214:217], v[180:183], v[16:19]
	v_mfma_f32_16x16x32_bf16 v[4:7], v[206:209], v[198:201], v[4:7]
	v_mfma_f32_16x16x32_bf16 v[0:3], v[214:217], v[198:201], v[0:3]
	s_add_i32 s51, s51, 2
	s_add_u32 s49, s49, 0x100
	s_addc_u32 s50, s50, 0
	s_cmp_gt_u32 s51, 41
	s_mov_b64 s[14:15], s[18:19]
	s_barrier
	s_cbranch_scc0 .LBB0_554
	v_lshl_or_b32 v168, s10, 8, v189
	v_lshl_add_u32 v170, s48, 8, v186
	v_ashrrev_i32_e32 v169, 31, v168
	v_lshlrev_b64 v[202:203], 1, v[168:169]
	v_ashrrev_i32_e32 v171, 31, v170
	v_or_b32_e32 v182, 16, v170
	v_lshl_add_u64 v[172:173], s[64:65], 0, v[202:203]
	v_lshlrev_b64 v[204:205], 11, v[170:171]
	v_ashrrev_i32_e32 v183, 31, v182
	v_or_b32_e32 v178, 32, v170
	v_lshl_add_u64 v[128:129], v[172:173], 0, v[204:205]
	v_lshlrev_b64 v[184:185], 11, v[182:183]
	v_ashrrev_i32_e32 v179, 31, v178
	v_or_b32_e32 v174, 48, v170
	global_load_dwordx4 v[194:197], v[128:129], off
	global_load_dwordx4 v[198:201], v[128:129], off offset:256
	v_lshl_add_u64 v[128:129], v[172:173], 0, v[184:185]
	v_lshlrev_b64 v[180:181], 11, v[178:179]
	v_ashrrev_i32_e32 v175, 31, v174
	global_load_dwordx4 v[148:151], v[128:129], off
	global_load_dwordx4 v[144:147], v[128:129], off offset:256
	v_lshl_add_u64 v[128:129], v[172:173], 0, v[180:181]
	v_lshlrev_b64 v[176:177], 11, v[174:175]
	global_load_dwordx4 v[140:143], v[128:129], off
	global_load_dwordx4 v[136:139], v[128:129], off offset:256
	v_lshl_add_u64 v[128:129], v[172:173], 0, v[176:177]
	global_load_dwordx4 v[132:135], v[128:129], off
	s_nop 0
	global_load_dwordx4 v[128:131], v[128:129], off offset:256
	s_lshl_b32 s14, s10, 2
	s_ashr_i32 s15, s14, 31
	v_add_u32_e32 v252, 0x80, v170
	v_ashrrev_i32_e32 v253, 31, v252
	v_lshlrev_b64 v[252:253], 11, v[252:253]
	v_lshl_add_u64 v[252:253], v[172:173], 0, v[252:253]
	global_load_dwordx4 v[236:239], v[252:253], off
	global_load_dwordx4 v[240:243], v[252:253], off offset:256
	v_add_u32_e32 v252, 0x90, v170
	v_ashrrev_i32_e32 v253, 31, v252
	v_lshlrev_b64 v[252:253], 11, v[252:253]
	v_lshl_add_u64 v[252:253], v[172:173], 0, v[252:253]
	global_load_dwordx4 v[244:247], v[252:253], off
	global_load_dwordx4 v[248:251], v[252:253], off offset:256
	v_add_u32_e32 v252, 0xa0, v170
	v_ashrrev_i32_e32 v253, 31, v252
	v_lshlrev_b64 v[252:253], 11, v[252:253]
	v_lshl_add_u64 v[252:253], v[172:173], 0, v[252:253]
	global_load_dwordx4 v[210:213], v[252:253], off
	global_load_dwordx4 v[214:217], v[252:253], off offset:256
	s_waitcnt vmcnt(6)
	v_lshlrev_b32_e32 v206, 16, v194
	v_and_b32_e32 v207, 0xffff0000, v194
	v_lshlrev_b32_e32 v194, 16, v195
	v_and_b32_e32 v195, 0xffff0000, v195
	v_lshlrev_b32_e32 v208, 16, v196
	v_and_b32_e32 v209, 0xffff0000, v196
	v_lshlrev_b32_e32 v196, 16, v197
	v_and_b32_e32 v197, 0xffff0000, v197
	v_pk_add_f32 v[126:127], v[126:127], v[194:195]
	v_pk_add_f32 v[124:125], v[124:125], v[206:207]
	v_pk_add_f32 v[194:195], v[122:123], v[196:197]
	v_pk_add_f32 v[122:123], v[120:121], v[208:209]
	v_mul_f32_e32 v120, v125, v125
	v_mul_f32_e32 v121, v127, v127
	v_fmac_f32_e32 v120, v124, v124
	v_fmac_f32_e32 v121, v126, v126
	v_add_f32_e32 v120, v120, v121
	v_mul_f32_e32 v121, v123, v123
	v_mul_f32_e32 v196, v195, v195
	v_fmac_f32_e32 v121, v122, v122
	v_fmac_f32_e32 v196, v194, v194
	v_add_f32_e32 v121, v121, v196
	v_add_f32_e32 v206, v120, v121
	v_cvt_pk_bf16_f32 v120, v124, v125
	v_cvt_pk_bf16_f32 v121, v126, v127
	v_lshlrev_b32_e32 v124, 16, v198
	v_and_b32_e32 v125, 0xffff0000, v198
	v_lshlrev_b32_e32 v126, 16, v199
	v_and_b32_e32 v127, 0xffff0000, v199
	v_cvt_pk_bf16_f32 v122, v122, v123
	v_cvt_pk_bf16_f32 v123, v194, v195
	v_lshlrev_b32_e32 v194, 16, v200
	v_and_b32_e32 v195, 0xffff0000, v200
	v_pk_add_f32 v[118:119], v[118:119], v[126:127]
	v_pk_add_f32 v[116:117], v[116:117], v[124:125]
	v_lshlrev_b32_e32 v196, 16, v201
	v_and_b32_e32 v197, 0xffff0000, v201
	v_pk_add_f32 v[126:127], v[112:113], v[194:195]
	v_mul_f32_e32 v112, v117, v117
	v_mul_f32_e32 v113, v119, v119
	v_pk_add_f32 v[124:125], v[114:115], v[196:197]
	v_fmac_f32_e32 v112, v116, v116
	v_fmac_f32_e32 v113, v118, v118
	v_add_f32_e32 v112, v112, v113
	v_mul_f32_e32 v113, v127, v127
	v_mul_f32_e32 v114, v125, v125
	v_fmac_f32_e32 v113, v126, v126
	v_fmac_f32_e32 v114, v124, v124
	v_add_f32_e32 v113, v113, v114
	v_add_f32_e32 v112, v112, v113
	v_and_b32_e32 v114, 64, v193
	v_add_f32_e32 v113, v206, v112
	v_xor_b32_e32 v112, 16, v193
	v_add_u32_e32 v196, 64, v114
	v_cmp_lt_i32_e32 vcc, v112, v196
	v_lshl_add_u64 v[114:115], s[64:65], 0, v[204:205]
	v_lshl_add_u64 v[194:195], v[114:115], 0, v[202:203]
	v_cndmask_b32_e32 v112, v193, v112, vcc
	v_lshlrev_b32_e32 v112, 2, v112
	ds_bpermute_b32 v197, v112, v113
	global_store_dwordx4 v[194:195], v[120:123], off
	v_cvt_pk_bf16_f32 v116, v116, v117
	v_cvt_pk_bf16_f32 v117, v118, v119
	v_cvt_pk_bf16_f32 v118, v126, v127
	s_waitcnt lgkmcnt(0)
	v_add_f32_e32 v114, v113, v197
	v_xor_b32_e32 v113, 32, v193
	v_cmp_lt_i32_e32 vcc, v113, v196
	v_cvt_pk_bf16_f32 v119, v124, v125
	global_store_dwordx4 v[194:195], v[116:119], off offset:256
	s_nop 0
	v_cndmask_b32_e32 v113, v193, v113, vcc
	v_lshlrev_b32_e32 v113, 2, v113
	ds_bpermute_b32 v115, v113, v114
	s_and_saveexec_b64 s[18:19], s[2:3]
	s_cbranch_execz .LBB0_557
	s_waitcnt lgkmcnt(0)
	v_add_f32_e32 v116, v114, v115
	v_lshlrev_b64 v[114:115], 6, v[170:171]
	v_lshl_add_u64 v[114:115], s[74:75], 0, v[114:115]
	v_lshl_add_u64 v[114:115], s[14:15], 2, v[114:115]
	s_lshl_b32 s10, s38, 2
	v_lshl_add_u64 v[114:115], v[114:115], 0, s[10:11]
	global_store_dword v[114:115], v116, off

.LBB0_642:
	ds_read_b128 v[24:27], v178
	ds_read_b128 v[28:31], v178 offset:1024
	ds_read_b128 v[160:163], v178 offset:2048
	ds_read_b128 v[164:167], v178 offset:3072
	s_add_u32 s38, s6, 0xfffc0080
	s_addc_u32 s39, s7, -1
	s_cmp_eq_u32 s68, 12
	s_cselect_b32 s41, s42, s39
	s_cselect_b32 s40, s43, s38
	s_cselect_b32 s39, s23, s67
	s_cselect_b32 s38, s44, s45
	v_lshl_add_u64 v[172:173], s[6:7], 0, v[152:153]
	s_add_i32 m0, s49, 0xc000
	ds_read_b128 v[168:171], v179
	ds_read_b128 v[182:185], v179 offset:1024
	ds_read_b128 v[190:193], v179 offset:2048
	ds_read_b128 v[194:197], v179 offset:3072
	ds_read_b128 v[198:201], v179 offset:4096
	ds_read_b128 v[202:205], v179 offset:5120
	ds_read_b128 v[206:209], v179 offset:6144
	ds_read_b128 v[210:213], v179 offset:7168
	global_load_lds_dwordx4 v[172:173], off
	v_lshl_add_u64 v[172:173], s[6:7], 0, v[154:155]
	s_add_i32 m0, s49, 0xe000
	s_nop 0
	global_load_lds_dwordx4 v[172:173], off
	s_waitcnt lgkmcnt(8)
	s_barrier
	s_waitcnt lgkmcnt(0)
	s_waitcnt lgkmcnt(0)
	v_mfma_f32_16x16x32_bf16 v[132:135], v[24:27], v[168:171], v[132:135]
	v_mfma_f32_16x16x32_bf16 v[128:131], v[160:163], v[168:171], v[128:131]
	v_mfma_f32_16x16x32_bf16 v[116:119], v[24:27], v[190:193], v[116:119]
	v_mfma_f32_16x16x32_bf16 v[112:115], v[160:163], v[190:193], v[112:115]
	v_mfma_f32_16x16x32_bf16 v[100:103], v[24:27], v[198:201], v[100:103]
	v_mfma_f32_16x16x32_bf16 v[96:99], v[160:163], v[198:201], v[96:99]
	v_mfma_f32_16x16x32_bf16 v[84:87], v[24:27], v[206:209], v[84:87]
	v_mfma_f32_16x16x32_bf16 v[80:83], v[160:163], v[206:209], v[80:83]
	v_mfma_f32_16x16x32_bf16 v[132:135], v[28:31], v[182:185], v[132:135]
	v_mfma_f32_16x16x32_bf16 v[128:131], v[164:167], v[182:185], v[128:131]
	v_mfma_f32_16x16x32_bf16 v[116:119], v[28:31], v[194:197], v[116:119]
	v_mfma_f32_16x16x32_bf16 v[112:115], v[164:167], v[194:197], v[112:115]
	v_mfma_f32_16x16x32_bf16 v[100:103], v[28:31], v[202:205], v[100:103]
	v_mfma_f32_16x16x32_bf16 v[96:99], v[164:167], v[202:205], v[96:99]
	v_mfma_f32_16x16x32_bf16 v[84:87], v[28:31], v[210:213], v[84:87]
	v_mfma_f32_16x16x32_bf16 v[80:83], v[164:167], v[210:213], v[80:83]
	s_barrier
	s_add_i32 s69, s59, s48
	v_lshl_add_u64 v[172:173], s[38:39], 0, v[136:137]
	s_mov_b32 m0, s69
	ds_read_b128 v[214:217], v180
	ds_read_b128 v[218:221], v180 offset:1024
	ds_read_b128 v[222:225], v180 offset:2048
	ds_read_b128 v[226:229], v180 offset:3072
	global_load_lds_dwordx4 v[172:173], off
	v_lshl_add_u64 v[186:187], s[38:39], 0, v[144:145]
	s_add_i32 m0, s69, 0x2000
	s_nop 0
	global_load_lds_dwordx4 v[186:187], off
	s_barrier
	s_waitcnt lgkmcnt(0)
	s_waitcnt lgkmcnt(0)
	v_mfma_f32_16x16x32_bf16 v[124:127], v[214:217], v[168:171], v[124:127]
	v_mfma_f32_16x16x32_bf16 v[120:123], v[222:225], v[168:171], v[120:123]
	v_mfma_f32_16x16x32_bf16 v[108:111], v[214:217], v[190:193], v[108:111]
	v_mfma_f32_16x16x32_bf16 v[104:107], v[222:225], v[190:193], v[104:107]
	v_mfma_f32_16x16x32_bf16 v[92:95], v[214:217], v[198:201], v[92:95]
	v_mfma_f32_16x16x32_bf16 v[88:91], v[222:225], v[198:201], v[88:91]
	v_mfma_f32_16x16x32_bf16 v[76:79], v[214:217], v[206:209], v[76:79]
	v_mfma_f32_16x16x32_bf16 v[72:75], v[222:225], v[206:209], v[72:75]
	v_mfma_f32_16x16x32_bf16 v[124:127], v[218:221], v[182:185], v[124:127]
	v_mfma_f32_16x16x32_bf16 v[120:123], v[226:229], v[182:185], v[120:123]
	v_mfma_f32_16x16x32_bf16 v[108:111], v[218:221], v[194:197], v[108:111]
	v_mfma_f32_16x16x32_bf16 v[104:107], v[226:229], v[194:197], v[104:107]
	v_mfma_f32_16x16x32_bf16 v[92:95], v[218:221], v[202:205], v[92:95]
	v_mfma_f32_16x16x32_bf16 v[88:91], v[226:229], v[202:205], v[88:91]
	v_mfma_f32_16x16x32_bf16 v[76:79], v[218:221], v[210:213], v[76:79]
	v_mfma_f32_16x16x32_bf16 v[72:75], v[226:229], v[210:213], v[72:75]
	s_mov_b32 m0, s49
	v_lshl_add_u64 v[230:231], s[40:41], 0, v[140:141]
	s_barrier
	ds_read_b128 v[168:171], v179 offset:16384
	ds_read_b128 v[182:185], v179 offset:17408
	ds_read_b128 v[190:193], v179 offset:18432
	ds_read_b128 v[194:197], v179 offset:19456
	ds_read_b128 v[198:201], v179 offset:20480
	ds_read_b128 v[202:205], v179 offset:21504
	ds_read_b128 v[206:209], v179 offset:22528
	ds_read_b128 v[210:213], v179 offset:23552
	global_load_lds_dwordx4 v[230:231], off
	v_lshl_add_u64 v[232:233], s[40:41], 0, v[142:143]
	s_mov_b32 m0, s50
	s_nop 0
	global_load_lds_dwordx4 v[232:233], off
	s_barrier
	s_waitcnt lgkmcnt(0)
	s_waitcnt lgkmcnt(0)
	v_mfma_f32_16x16x32_bf16 v[68:71], v[24:27], v[168:171], v[68:71]
	v_mfma_f32_16x16x32_bf16 v[64:67], v[160:163], v[168:171], v[64:67]
	v_mfma_f32_16x16x32_bf16 v[52:55], v[24:27], v[190:193], v[52:55]
	v_mfma_f32_16x16x32_bf16 v[48:51], v[160:163], v[190:193], v[48:51]
	v_mfma_f32_16x16x32_bf16 v[36:39], v[24:27], v[198:201], v[36:39]
	v_mfma_f32_16x16x32_bf16 v[32:35], v[160:163], v[198:201], v[32:35]
	v_mfma_f32_16x16x32_bf16 v[12:15], v[24:27], v[206:209], v[12:15]
	v_mfma_f32_16x16x32_bf16 v[8:11], v[160:163], v[206:209], v[8:11]
	v_mfma_f32_16x16x32_bf16 v[68:71], v[28:31], v[182:185], v[68:71]
	v_mfma_f32_16x16x32_bf16 v[64:67], v[164:167], v[182:185], v[64:67]
	v_mfma_f32_16x16x32_bf16 v[52:55], v[28:31], v[194:197], v[52:55]
	v_mfma_f32_16x16x32_bf16 v[48:51], v[164:167], v[194:197], v[48:51]
	v_mfma_f32_16x16x32_bf16 v[36:39], v[28:31], v[202:205], v[36:39]
	v_mfma_f32_16x16x32_bf16 v[32:35], v[164:167], v[202:205], v[32:35]
	v_mfma_f32_16x16x32_bf16 v[12:15], v[28:31], v[210:213], v[12:15]
	v_mfma_f32_16x16x32_bf16 v[8:11], v[164:167], v[210:213], v[8:11]
	s_barrier
	s_add_u32 s70, s38, 0x40000
	s_addc_u32 s71, s39, 0
	s_add_i32 s69, s60, s48
	v_lshl_add_u64 v[24:25], s[70:71], 0, v[136:137]
	s_mov_b32 m0, s69
	s_nop 0
	global_load_lds_dwordx4 v[24:25], off
	v_lshl_add_u64 v[24:25], s[70:71], 0, v[144:145]
	s_add_i32 m0, s69, 0x2000
	s_nop 0
	global_load_lds_dwordx4 v[24:25], off
	s_waitcnt vmcnt(6)
	s_barrier
	v_mfma_f32_16x16x32_bf16 v[44:47], v[214:217], v[190:193], v[44:47]
	v_mfma_f32_16x16x32_bf16 v[40:43], v[222:225], v[190:193], v[40:43]
	v_mfma_f32_16x16x32_bf16 v[20:23], v[214:217], v[198:201], v[20:23]
	v_mfma_f32_16x16x32_bf16 v[16:19], v[222:225], v[198:201], v[16:19]
	v_mfma_f32_16x16x32_bf16 v[4:7], v[214:217], v[206:209], v[4:7]
	v_mfma_f32_16x16x32_bf16 v[0:3], v[222:225], v[206:209], v[0:3]
	v_mfma_f32_16x16x32_bf16 v[24:27], v[214:217], v[168:171], v[60:63]
	v_mfma_f32_16x16x32_bf16 v[28:31], v[222:225], v[168:171], v[56:59]
	v_mfma_f32_16x16x32_bf16 v[44:47], v[218:221], v[194:197], v[44:47]
	v_mfma_f32_16x16x32_bf16 v[40:43], v[226:229], v[194:197], v[40:43]
	v_mfma_f32_16x16x32_bf16 v[20:23], v[218:221], v[202:205], v[20:23]
	v_mfma_f32_16x16x32_bf16 v[16:19], v[226:229], v[202:205], v[16:19]
	v_mfma_f32_16x16x32_bf16 v[4:7], v[218:221], v[210:213], v[4:7]
	v_mfma_f32_16x16x32_bf16 v[0:3], v[226:229], v[210:213], v[0:3]
	v_mfma_f32_16x16x32_bf16 v[24:27], v[218:221], v[182:185], v[24:27]
	v_mfma_f32_16x16x32_bf16 v[28:31], v[226:229], v[182:185], v[28:31]
	s_add_i32 s69, 0, 0x18000
	v_add_u32_e32 v138, s69, v175
	s_barrier
	ds_read_b128 v[56:59], v138
	ds_read_b128 v[60:63], v138 offset:1024
	ds_read_b128 v[160:163], v138 offset:2048
	ds_read_b128 v[164:167], v138 offset:3072
	s_add_u32 s40, s40, 0x40000
	s_addc_u32 s41, s41, 0
	s_mov_b32 m0, s51
	v_lshl_add_u64 v[214:215], s[40:41], 0, v[140:141]
	ds_read_b128 v[168:171], v179 offset:32768
	ds_read_b128 v[182:185], v179 offset:33792
	ds_read_b128 v[190:193], v179 offset:34816
	ds_read_b128 v[194:197], v179 offset:35840
	ds_read_b128 v[198:201], v179 offset:36864
	ds_read_b128 v[202:205], v179 offset:37888
	ds_read_b128 v[206:209], v179 offset:38912
	ds_read_b128 v[210:213], v179 offset:39936
	global_load_lds_dwordx4 v[214:215], off
	v_lshl_add_u64 v[214:215], s[40:41], 0, v[142:143]
	s_mov_b32 m0, s52
	s_nop 0
	global_load_lds_dwordx4 v[214:215], off
	s_waitcnt lgkmcnt(8)
	s_barrier
	s_waitcnt lgkmcnt(0)
	s_waitcnt lgkmcnt(0)
	v_mfma_f32_16x16x32_bf16 v[132:135], v[56:59], v[168:171], v[132:135]
	v_mfma_f32_16x16x32_bf16 v[128:131], v[160:163], v[168:171], v[128:131]
	v_mfma_f32_16x16x32_bf16 v[116:119], v[56:59], v[190:193], v[116:119]
	v_mfma_f32_16x16x32_bf16 v[112:115], v[160:163], v[190:193], v[112:115]
	v_mfma_f32_16x16x32_bf16 v[100:103], v[56:59], v[198:201], v[100:103]
	v_mfma_f32_16x16x32_bf16 v[96:99], v[160:163], v[198:201], v[96:99]
	v_mfma_f32_16x16x32_bf16 v[84:87], v[56:59], v[206:209], v[84:87]
	v_mfma_f32_16x16x32_bf16 v[80:83], v[160:163], v[206:209], v[80:83]
	v_mfma_f32_16x16x32_bf16 v[132:135], v[60:63], v[182:185], v[132:135]
	v_mfma_f32_16x16x32_bf16 v[128:131], v[164:167], v[182:185], v[128:131]
	v_mfma_f32_16x16x32_bf16 v[116:119], v[60:63], v[194:197], v[116:119]
	v_mfma_f32_16x16x32_bf16 v[112:115], v[164:167], v[194:197], v[112:115]
	v_mfma_f32_16x16x32_bf16 v[100:103], v[60:63], v[202:205], v[100:103]
	v_mfma_f32_16x16x32_bf16 v[96:99], v[164:167], v[202:205], v[96:99]
	v_mfma_f32_16x16x32_bf16 v[84:87], v[60:63], v[210:213], v[84:87]
	v_mfma_f32_16x16x32_bf16 v[80:83], v[164:167], v[210:213], v[80:83]
	s_barrier
	s_add_i32 s40, 0, 0x1c000
	s_add_i32 s41, s69, s48
	v_add_u32_e32 v138, s40, v175
	v_lshl_add_u64 v[172:173], v[172:173], 0, s[12:13]
	s_mov_b32 m0, s41
	ds_read_b128 v[214:217], v138
	ds_read_b128 v[218:221], v138 offset:1024
	ds_read_b128 v[222:225], v138 offset:2048
	ds_read_b128 v[226:229], v138 offset:3072
	global_load_lds_dwordx4 v[172:173], off
	v_lshl_add_u64 v[172:173], v[186:187], 0, s[12:13]
	s_add_i32 m0, s41, 0x2000
	s_nop 0
	global_load_lds_dwordx4 v[172:173], off
	s_barrier
	s_waitcnt lgkmcnt(0)
	s_waitcnt lgkmcnt(0)
	v_mfma_f32_16x16x32_bf16 v[124:127], v[214:217], v[168:171], v[124:127]
	v_mfma_f32_16x16x32_bf16 v[120:123], v[222:225], v[168:171], v[120:123]
	v_mfma_f32_16x16x32_bf16 v[108:111], v[214:217], v[190:193], v[108:111]
	v_mfma_f32_16x16x32_bf16 v[104:107], v[222:225], v[190:193], v[104:107]
	v_mfma_f32_16x16x32_bf16 v[92:95], v[214:217], v[198:201], v[92:95]
	v_mfma_f32_16x16x32_bf16 v[88:91], v[222:225], v[198:201], v[88:91]
	v_mfma_f32_16x16x32_bf16 v[76:79], v[214:217], v[206:209], v[76:79]
	v_mfma_f32_16x16x32_bf16 v[72:75], v[222:225], v[206:209], v[72:75]
	v_mfma_f32_16x16x32_bf16 v[124:127], v[218:221], v[182:185], v[124:127]
	v_mfma_f32_16x16x32_bf16 v[120:123], v[226:229], v[182:185], v[120:123]
	v_mfma_f32_16x16x32_bf16 v[108:111], v[218:221], v[194:197], v[108:111]
	v_mfma_f32_16x16x32_bf16 v[104:107], v[226:229], v[194:197], v[104:107]
	v_mfma_f32_16x16x32_bf16 v[92:95], v[218:221], v[202:205], v[92:95]
	v_mfma_f32_16x16x32_bf16 v[88:91], v[226:229], v[202:205], v[88:91]
	v_mfma_f32_16x16x32_bf16 v[76:79], v[218:221], v[210:213], v[76:79]
	v_mfma_f32_16x16x32_bf16 v[72:75], v[226:229], v[210:213], v[72:75]
	s_mov_b32 m0, s54
	v_lshl_add_u64 v[172:173], v[230:231], 0, s[12:13]
	s_barrier
	ds_read_b128 v[168:171], v179 offset:49152
	ds_read_b128 v[182:185], v179 offset:50176
	ds_read_b128 v[190:193], v179 offset:51200
	ds_read_b128 v[194:197], v179 offset:52224
	ds_read_b128 v[198:201], v179 offset:53248
	ds_read_b128 v[202:205], v179 offset:54272
	ds_read_b128 v[206:209], v179 offset:55296
	ds_read_b128 v[210:213], v179 offset:56320
	global_load_lds_dwordx4 v[172:173], off
	v_lshl_add_u64 v[172:173], v[232:233], 0, s[12:13]
	s_mov_b32 m0, s55
	s_nop 0
	global_load_lds_dwordx4 v[172:173], off
	s_barrier
	s_waitcnt lgkmcnt(0)
	s_waitcnt lgkmcnt(0)
	v_mfma_f32_16x16x32_bf16 v[68:71], v[56:59], v[168:171], v[68:71]
	v_mfma_f32_16x16x32_bf16 v[64:67], v[160:163], v[168:171], v[64:67]
	v_mfma_f32_16x16x32_bf16 v[52:55], v[56:59], v[190:193], v[52:55]
	v_mfma_f32_16x16x32_bf16 v[48:51], v[160:163], v[190:193], v[48:51]
	v_mfma_f32_16x16x32_bf16 v[36:39], v[56:59], v[198:201], v[36:39]
	v_mfma_f32_16x16x32_bf16 v[32:35], v[160:163], v[198:201], v[32:35]
	v_mfma_f32_16x16x32_bf16 v[12:15], v[56:59], v[206:209], v[12:15]
	v_mfma_f32_16x16x32_bf16 v[8:11], v[160:163], v[206:209], v[8:11]
	v_mfma_f32_16x16x32_bf16 v[68:71], v[60:63], v[182:185], v[68:71]
	v_mfma_f32_16x16x32_bf16 v[64:67], v[164:167], v[182:185], v[64:67]
	v_mfma_f32_16x16x32_bf16 v[52:55], v[60:63], v[194:197], v[52:55]
	v_mfma_f32_16x16x32_bf16 v[48:51], v[164:167], v[194:197], v[48:51]
	v_mfma_f32_16x16x32_bf16 v[36:39], v[60:63], v[202:205], v[36:39]
	v_mfma_f32_16x16x32_bf16 v[32:35], v[164:167], v[202:205], v[32:35]
	v_mfma_f32_16x16x32_bf16 v[12:15], v[60:63], v[210:213], v[12:15]
	v_mfma_f32_16x16x32_bf16 v[8:11], v[164:167], v[210:213], v[8:11]
	s_barrier
	s_add_u32 s38, s38, 0x40080
	s_addc_u32 s39, s39, 0
	s_add_i32 s40, s40, s48
	v_lshl_add_u64 v[56:57], s[38:39], 0, v[136:137]
	s_mov_b32 m0, s40
	s_nop 0
	global_load_lds_dwordx4 v[56:57], off
	v_lshl_add_u64 v[56:57], s[38:39], 0, v[144:145]
	s_add_i32 m0, s40, 0x2000
	s_nop 0
	global_load_lds_dwordx4 v[56:57], off
	s_waitcnt vmcnt(6)
	s_barrier
	v_mfma_f32_16x16x32_bf16 v[24:27], v[214:217], v[168:171], v[24:27]
	v_mfma_f32_16x16x32_bf16 v[60:63], v[218:221], v[182:185], v[24:27]
	v_mfma_f32_16x16x32_bf16 v[24:27], v[222:225], v[168:171], v[28:31]
	v_mfma_f32_16x16x32_bf16 v[56:59], v[226:229], v[182:185], v[24:27]
	v_mfma_f32_16x16x32_bf16 v[24:27], v[214:217], v[190:193], v[44:47]
	v_mfma_f32_16x16x32_bf16 v[44:47], v[218:221], v[194:197], v[24:27]
	v_mfma_f32_16x16x32_bf16 v[24:27], v[222:225], v[190:193], v[40:43]
	v_mfma_f32_16x16x32_bf16 v[20:23], v[214:217], v[198:201], v[20:23]
	v_mfma_f32_16x16x32_bf16 v[16:19], v[222:225], v[198:201], v[16:19]
	v_mfma_f32_16x16x32_bf16 v[4:7], v[214:217], v[206:209], v[4:7]
	v_mfma_f32_16x16x32_bf16 v[0:3], v[222:225], v[206:209], v[0:3]
	v_mfma_f32_16x16x32_bf16 v[40:43], v[226:229], v[194:197], v[24:27]
	v_mfma_f32_16x16x32_bf16 v[20:23], v[218:221], v[202:205], v[20:23]
	v_mfma_f32_16x16x32_bf16 v[16:19], v[226:229], v[202:205], v[16:19]
	v_mfma_f32_16x16x32_bf16 v[4:7], v[218:221], v[210:213], v[4:7]
	v_mfma_f32_16x16x32_bf16 v[0:3], v[226:229], v[210:213], v[0:3]
	s_add_i32 s68, s68, 2
	s_add_u32 s6, s6, 0x100
	s_addc_u32 s7, s7, 0
	s_add_u32 s45, s45, 0x100
	s_addc_u32 s67, s67, 0
	s_cmp_gt_u32 s68, 13
	s_barrier
	s_cbranch_scc0 .LBB0_642
	v_cndmask_b32_e64 v24, 0, 1, s[8:9]
	v_cmp_ne_u32_e64 s[6:7], 1, v24
	s_andn2_b64 vcc, exec, s[8:9]
	s_cbranch_vccnz .LBB0_645
	s_lshl_b64 s[8:9], s[28:29], 14
	v_lshl_add_u64 v[28:29], v[148:149], 0, s[8:9]
	global_load_dwordx4 v[24:27], v[28:29], off offset:16
	s_nop 0
	global_load_dwordx4 v[28:31], v[28:29], off

.LBB0_870:
	v_add_u32_e32 v80, s60, v94
	ds_read_b128 v[8:11], v80
	ds_read_b128 v[16:19], v80 offset:1024
	ds_read_b128 v[98:101], v80 offset:2048
	ds_read_b128 v[102:105], v80 offset:3072
	s_and_b64 s[0:1], exec, s[0:1]
	s_cselect_b32 s1, s21, s78
	s_cselect_b32 s0, s31, s71
	v_lshl_add_u64 v[138:139], s[34:35], 0, v[86:87]
	s_add_i32 m0, s42, 0xc000
	ds_read_b128 v[106:109], v95
	ds_read_b128 v[110:113], v95 offset:1024
	ds_read_b128 v[114:117], v95 offset:2048
	ds_read_b128 v[118:121], v95 offset:3072
	ds_read_b128 v[122:125], v95 offset:4096
	ds_read_b128 v[126:129], v95 offset:5120
	ds_read_b128 v[130:133], v95 offset:6144
	ds_read_b128 v[134:137], v95 offset:7168
	global_load_lds_dwordx4 v[138:139], off
	v_lshl_add_u64 v[138:139], s[34:35], 0, v[88:89]
	s_add_i32 m0, s42, 0xe000
	s_nop 0
	global_load_lds_dwordx4 v[138:139], off
	s_waitcnt lgkmcnt(8)
	s_barrier
	s_waitcnt lgkmcnt(0)
	s_waitcnt lgkmcnt(0)
	v_mfma_f32_16x16x32_bf16 v[68:71], v[8:11], v[106:109], v[68:71]
	v_mfma_f32_16x16x32_bf16 v[64:67], v[98:101], v[106:109], v[64:67]
	v_mfma_f32_16x16x32_bf16 v[60:63], v[8:11], v[114:117], v[60:63]
	v_mfma_f32_16x16x32_bf16 v[56:59], v[98:101], v[114:117], v[56:59]
	v_mfma_f32_16x16x32_bf16 v[52:55], v[8:11], v[122:125], v[52:55]
	v_mfma_f32_16x16x32_bf16 v[48:51], v[98:101], v[122:125], v[48:51]
	v_mfma_f32_16x16x32_bf16 v[44:47], v[8:11], v[130:133], v[44:47]
	v_mfma_f32_16x16x32_bf16 v[40:43], v[98:101], v[130:133], v[40:43]
	v_mfma_f32_16x16x32_bf16 v[68:71], v[16:19], v[110:113], v[68:71]
	v_mfma_f32_16x16x32_bf16 v[64:67], v[102:105], v[110:113], v[64:67]
	v_mfma_f32_16x16x32_bf16 v[60:63], v[16:19], v[118:121], v[60:63]
	v_mfma_f32_16x16x32_bf16 v[56:59], v[102:105], v[118:121], v[56:59]
	v_mfma_f32_16x16x32_bf16 v[52:55], v[16:19], v[126:129], v[52:55]
	v_mfma_f32_16x16x32_bf16 v[48:51], v[102:105], v[126:129], v[48:51]
	v_mfma_f32_16x16x32_bf16 v[44:47], v[16:19], v[134:137], v[44:47]
	v_mfma_f32_16x16x32_bf16 v[40:43], v[102:105], v[134:137], v[40:43]
	s_barrier
	s_add_i32 s80, s60, s41
	v_lshl_add_u64 v[138:139], s[0:1], 0, v[74:75]
	s_mov_b32 m0, s80
	v_lshl_add_u64 v[140:141], s[0:1], 0, v[78:79]
	global_load_lds_dwordx4 v[138:139], off
	s_add_i32 m0, s80, 0x2000
	s_nop 0
	global_load_lds_dwordx4 v[140:141], off
	s_barrier
	s_waitcnt lgkmcnt(0)
	s_mov_b32 m0, s42
	v_lshl_add_u64 v[142:143], s[36:37], 0, v[72:73]
	s_barrier
	ds_read_b128 v[106:109], v95 offset:16384
	ds_read_b128 v[110:113], v95 offset:17408
	ds_read_b128 v[114:117], v95 offset:18432
	ds_read_b128 v[118:121], v95 offset:19456
	ds_read_b128 v[122:125], v95 offset:20480
	ds_read_b128 v[126:129], v95 offset:21504
	ds_read_b128 v[130:133], v95 offset:22528
	ds_read_b128 v[134:137], v95 offset:23552
	global_load_lds_dwordx4 v[142:143], off
	v_lshl_add_u64 v[144:145], s[36:37], 0, v[76:77]
	s_mov_b32 m0, s43
	s_nop 0
	global_load_lds_dwordx4 v[144:145], off
	s_barrier
	s_waitcnt lgkmcnt(0)
	s_waitcnt lgkmcnt(0)
	v_mfma_f32_16x16x32_bf16 v[36:39], v[8:11], v[106:109], v[36:39]
	v_mfma_f32_16x16x32_bf16 v[32:35], v[98:101], v[106:109], v[32:35]
	v_mfma_f32_16x16x32_bf16 v[28:31], v[8:11], v[114:117], v[28:31]
	v_mfma_f32_16x16x32_bf16 v[24:27], v[98:101], v[114:117], v[24:27]
	v_mfma_f32_16x16x32_bf16 v[20:23], v[8:11], v[122:125], v[20:23]
	v_mfma_f32_16x16x32_bf16 v[12:15], v[98:101], v[122:125], v[12:15]
	v_mfma_f32_16x16x32_bf16 v[4:7], v[8:11], v[130:133], v[4:7]
	v_mfma_f32_16x16x32_bf16 v[0:3], v[98:101], v[130:133], v[0:3]
	v_mfma_f32_16x16x32_bf16 v[36:39], v[16:19], v[110:113], v[36:39]
	v_mfma_f32_16x16x32_bf16 v[32:35], v[102:105], v[110:113], v[32:35]
	v_mfma_f32_16x16x32_bf16 v[28:31], v[16:19], v[118:121], v[28:31]
	v_mfma_f32_16x16x32_bf16 v[24:27], v[102:105], v[118:121], v[24:27]
	v_mfma_f32_16x16x32_bf16 v[20:23], v[16:19], v[126:129], v[20:23]
	v_mfma_f32_16x16x32_bf16 v[12:15], v[102:105], v[126:129], v[12:15]
	v_mfma_f32_16x16x32_bf16 v[4:7], v[16:19], v[134:137], v[4:7]
	v_mfma_f32_16x16x32_bf16 v[0:3], v[102:105], v[134:137], v[0:3]
	s_barrier
	s_add_u32 s80, s0, 0x80000
	s_addc_u32 s81, s1, 0
	s_mov_b32 m0, s44
	v_lshl_add_u64 v[8:9], s[80:81], 0, v[74:75]
	global_load_lds_dwordx4 v[8:9], off
	v_lshl_add_u64 v[8:9], s[80:81], 0, v[78:79]
	s_mov_b32 m0, s45
	s_nop 0
	global_load_lds_dwordx4 v[8:9], off
	s_waitcnt vmcnt(6)
	s_barrier
	s_add_i32 s80, 0, 0x18000
	v_add_u32_e32 v80, s80, v94
	s_barrier
	ds_read_b128 v[8:11], v80
	ds_read_b128 v[16:19], v80 offset:1024
	ds_read_b128 v[98:101], v80 offset:2048
	ds_read_b128 v[102:105], v80 offset:3072
	s_add_u32 s36, s36, 0x180000
	s_addc_u32 s37, s37, 0
	s_mov_b32 m0, s46
	v_lshl_add_u64 v[146:147], s[36:37], 0, v[72:73]
	ds_read_b128 v[106:109], v95 offset:32768
	ds_read_b128 v[110:113], v95 offset:33792
	ds_read_b128 v[114:117], v95 offset:34816
	ds_read_b128 v[118:121], v95 offset:35840
	ds_read_b128 v[122:125], v95 offset:36864
	ds_read_b128 v[126:129], v95 offset:37888
	ds_read_b128 v[130:133], v95 offset:38912
	ds_read_b128 v[134:137], v95 offset:39936
	global_load_lds_dwordx4 v[146:147], off
	v_lshl_add_u64 v[146:147], s[36:37], 0, v[76:77]
	s_mov_b32 m0, s47
	s_nop 0
	global_load_lds_dwordx4 v[146:147], off
	s_waitcnt lgkmcnt(8)
	s_barrier
	s_waitcnt lgkmcnt(0)
	s_waitcnt lgkmcnt(0)
	v_mfma_f32_16x16x32_bf16 v[68:71], v[8:11], v[106:109], v[68:71]
	v_mfma_f32_16x16x32_bf16 v[64:67], v[98:101], v[106:109], v[64:67]
	v_mfma_f32_16x16x32_bf16 v[60:63], v[8:11], v[114:117], v[60:63]
	v_mfma_f32_16x16x32_bf16 v[56:59], v[98:101], v[114:117], v[56:59]
	v_mfma_f32_16x16x32_bf16 v[52:55], v[8:11], v[122:125], v[52:55]
	v_mfma_f32_16x16x32_bf16 v[48:51], v[98:101], v[122:125], v[48:51]
	v_mfma_f32_16x16x32_bf16 v[44:47], v[8:11], v[130:133], v[44:47]
	v_mfma_f32_16x16x32_bf16 v[40:43], v[98:101], v[130:133], v[40:43]
	v_mfma_f32_16x16x32_bf16 v[68:71], v[16:19], v[110:113], v[68:71]
	v_mfma_f32_16x16x32_bf16 v[64:67], v[102:105], v[110:113], v[64:67]
	v_mfma_f32_16x16x32_bf16 v[60:63], v[16:19], v[118:121], v[60:63]
	v_mfma_f32_16x16x32_bf16 v[56:59], v[102:105], v[118:121], v[56:59]
	v_mfma_f32_16x16x32_bf16 v[52:55], v[16:19], v[126:129], v[52:55]
	v_mfma_f32_16x16x32_bf16 v[48:51], v[102:105], v[126:129], v[48:51]
	v_mfma_f32_16x16x32_bf16 v[44:47], v[16:19], v[134:137], v[44:47]
	v_mfma_f32_16x16x32_bf16 v[40:43], v[102:105], v[134:137], v[40:43]
	s_barrier
	s_add_i32 s36, s80, s41
	v_lshl_add_u64 v[106:107], v[138:139], 0, s[6:7]
	s_mov_b32 m0, s36
	s_nop 0
	global_load_lds_dwordx4 v[106:107], off
	v_lshl_add_u64 v[106:107], v[140:141], 0, s[6:7]
	s_add_i32 m0, s36, 0x2000
	s_nop 0
	global_load_lds_dwordx4 v[106:107], off
	s_barrier
	s_waitcnt lgkmcnt(0)
	s_mov_b32 m0, s54
	v_lshl_add_u64 v[138:139], v[142:143], 0, s[8:9]
	s_barrier
	ds_read_b128 v[106:109], v95 offset:49152
	ds_read_b128 v[110:113], v95 offset:50176
	ds_read_b128 v[114:117], v95 offset:51200
	ds_read_b128 v[118:121], v95 offset:52224
	ds_read_b128 v[122:125], v95 offset:53248
	ds_read_b128 v[126:129], v95 offset:54272
	ds_read_b128 v[130:133], v95 offset:55296
	ds_read_b128 v[134:137], v95 offset:56320
	global_load_lds_dwordx4 v[138:139], off
	v_lshl_add_u64 v[138:139], v[144:145], 0, s[8:9]
	s_mov_b32 m0, s55
	s_nop 0
	global_load_lds_dwordx4 v[138:139], off
	s_barrier
	s_waitcnt lgkmcnt(0)
	s_waitcnt lgkmcnt(0)
	v_mfma_f32_16x16x32_bf16 v[36:39], v[8:11], v[106:109], v[36:39]
	v_mfma_f32_16x16x32_bf16 v[32:35], v[98:101], v[106:109], v[32:35]
	v_mfma_f32_16x16x32_bf16 v[28:31], v[8:11], v[114:117], v[28:31]
	v_mfma_f32_16x16x32_bf16 v[24:27], v[98:101], v[114:117], v[24:27]
	v_mfma_f32_16x16x32_bf16 v[20:23], v[8:11], v[122:125], v[20:23]
	v_mfma_f32_16x16x32_bf16 v[12:15], v[98:101], v[122:125], v[12:15]
	v_mfma_f32_16x16x32_bf16 v[4:7], v[8:11], v[130:133], v[4:7]
	v_mfma_f32_16x16x32_bf16 v[0:3], v[98:101], v[130:133], v[0:3]
	v_mfma_f32_16x16x32_bf16 v[36:39], v[16:19], v[110:113], v[36:39]
	v_mfma_f32_16x16x32_bf16 v[32:35], v[102:105], v[110:113], v[32:35]
	v_mfma_f32_16x16x32_bf16 v[28:31], v[16:19], v[118:121], v[28:31]
	v_mfma_f32_16x16x32_bf16 v[24:27], v[102:105], v[118:121], v[24:27]
	v_mfma_f32_16x16x32_bf16 v[20:23], v[16:19], v[126:129], v[20:23]
	v_mfma_f32_16x16x32_bf16 v[12:15], v[102:105], v[126:129], v[12:15]
	v_mfma_f32_16x16x32_bf16 v[4:7], v[16:19], v[134:137], v[4:7]
	v_mfma_f32_16x16x32_bf16 v[0:3], v[102:105], v[134:137], v[0:3]
	s_barrier
	s_add_u32 s0, s0, 0x80080
	s_addc_u32 s1, s1, 0
	s_mov_b32 m0, s56
	v_lshl_add_u64 v[8:9], s[0:1], 0, v[74:75]
	global_load_lds_dwordx4 v[8:9], off
	v_lshl_add_u64 v[8:9], s[0:1], 0, v[78:79]
	s_mov_b32 m0, s57
	s_nop 0
	global_load_lds_dwordx4 v[8:9], off
	s_waitcnt vmcnt(6)
	s_barrier
	s_add_i32 s79, s79, 2
	s_add_u32 s71, s71, 0x100
	s_addc_u32 s78, s78, 0
	s_add_u32 s34, s34, 0x1800
	s_addc_u32 s35, s35, 0
	s_cmp_gt_u32 s79, 29
	s_barrier
	s_cbranch_scc1 .LBB0_875

.LBB0_1551:
	ds_read_b128 v[128:131], v190
	ds_read_b128 v[132:135], v190 offset:1024
	ds_read_b128 v[136:139], v190 offset:2048
	ds_read_b128 v[140:143], v190 offset:3072
	s_add_u32 s22, s20, 0xfffc0080
	s_addc_u32 s23, s21, -1
	s_cmp_eq_u32 s51, 12
	s_cselect_b32 s29, s13, s23
	s_cselect_b32 s28, s19, s22
	s_cselect_b32 s23, s11, s50
	s_cselect_b32 s22, s48, s49
	v_lshl_add_u64 v[184:185], s[20:21], 0, v[160:161]
	s_add_i32 m0, s36, 0xc000
	ds_read_b128 v[144:147], v191
	ds_read_b128 v[148:151], v191 offset:1024
	ds_read_b128 v[168:171], v191 offset:2048
	ds_read_b128 v[172:175], v191 offset:3072
	ds_read_b128 v[176:179], v191 offset:4096
	ds_read_b128 v[180:183], v191 offset:5120
	ds_read_b128 v[194:197], v191 offset:6144
	ds_read_b128 v[198:201], v191 offset:7168
	global_load_lds_dwordx4 v[184:185], off
	v_lshl_add_u64 v[184:185], s[20:21], 0, v[162:163]
	s_add_i32 m0, s36, 0xe000
	s_nop 0
	global_load_lds_dwordx4 v[184:185], off
	s_waitcnt lgkmcnt(8)
	s_barrier
	s_waitcnt lgkmcnt(0)
	s_waitcnt lgkmcnt(0)
	v_mfma_f32_16x16x32_bf16 v[124:127], v[128:131], v[144:147], v[124:127]
	v_mfma_f32_16x16x32_bf16 v[120:123], v[136:139], v[144:147], v[120:123]
	v_mfma_f32_16x16x32_bf16 v[108:111], v[128:131], v[168:171], v[108:111]
	v_mfma_f32_16x16x32_bf16 v[104:107], v[136:139], v[168:171], v[104:107]
	v_mfma_f32_16x16x32_bf16 v[92:95], v[128:131], v[176:179], v[92:95]
	v_mfma_f32_16x16x32_bf16 v[88:91], v[136:139], v[176:179], v[88:91]
	v_mfma_f32_16x16x32_bf16 v[76:79], v[128:131], v[194:197], v[76:79]
	v_mfma_f32_16x16x32_bf16 v[72:75], v[136:139], v[194:197], v[72:75]
	v_mfma_f32_16x16x32_bf16 v[124:127], v[132:135], v[148:151], v[124:127]
	v_mfma_f32_16x16x32_bf16 v[120:123], v[140:143], v[148:151], v[120:123]
	v_mfma_f32_16x16x32_bf16 v[108:111], v[132:135], v[172:175], v[108:111]
	v_mfma_f32_16x16x32_bf16 v[104:107], v[140:143], v[172:175], v[104:107]
	v_mfma_f32_16x16x32_bf16 v[92:95], v[132:135], v[180:183], v[92:95]
	v_mfma_f32_16x16x32_bf16 v[88:91], v[140:143], v[180:183], v[88:91]
	v_mfma_f32_16x16x32_bf16 v[76:79], v[132:135], v[198:201], v[76:79]
	v_mfma_f32_16x16x32_bf16 v[72:75], v[140:143], v[198:201], v[72:75]
	s_barrier
	s_add_i32 s52, s45, s35
	v_lshl_add_u64 v[184:185], s[22:23], 0, v[154:155]
	s_mov_b32 m0, s52
	ds_read_b128 v[202:205], v192
	ds_read_b128 v[206:209], v192 offset:1024
	ds_read_b128 v[210:213], v192 offset:2048
	ds_read_b128 v[214:217], v192 offset:3072
	global_load_lds_dwordx4 v[184:185], off
	v_lshl_add_u64 v[218:219], s[22:23], 0, v[158:159]
	s_add_i32 m0, s52, 0x2000
	s_nop 0
	global_load_lds_dwordx4 v[218:219], off
	s_barrier
	s_waitcnt lgkmcnt(0)
	s_waitcnt lgkmcnt(0)
	v_mfma_f32_16x16x32_bf16 v[116:119], v[202:205], v[144:147], v[116:119]
	v_mfma_f32_16x16x32_bf16 v[112:115], v[210:213], v[144:147], v[112:115]
	v_mfma_f32_16x16x32_bf16 v[100:103], v[202:205], v[168:171], v[100:103]
	v_mfma_f32_16x16x32_bf16 v[96:99], v[210:213], v[168:171], v[96:99]
	v_mfma_f32_16x16x32_bf16 v[84:87], v[202:205], v[176:179], v[84:87]
	v_mfma_f32_16x16x32_bf16 v[80:83], v[210:213], v[176:179], v[80:83]
	v_mfma_f32_16x16x32_bf16 v[68:71], v[202:205], v[194:197], v[68:71]
	v_mfma_f32_16x16x32_bf16 v[64:67], v[210:213], v[194:197], v[64:67]
	v_mfma_f32_16x16x32_bf16 v[116:119], v[206:209], v[148:151], v[116:119]
	v_mfma_f32_16x16x32_bf16 v[112:115], v[214:217], v[148:151], v[112:115]
	v_mfma_f32_16x16x32_bf16 v[100:103], v[206:209], v[172:175], v[100:103]
	v_mfma_f32_16x16x32_bf16 v[96:99], v[214:217], v[172:175], v[96:99]
	v_mfma_f32_16x16x32_bf16 v[84:87], v[206:209], v[180:183], v[84:87]
	v_mfma_f32_16x16x32_bf16 v[80:83], v[214:217], v[180:183], v[80:83]
	v_mfma_f32_16x16x32_bf16 v[68:71], v[206:209], v[198:201], v[68:71]
	v_mfma_f32_16x16x32_bf16 v[64:67], v[214:217], v[198:201], v[64:67]
	s_mov_b32 m0, s36
	v_lshl_add_u64 v[220:221], s[28:29], 0, v[152:153]
	s_barrier
	ds_read_b128 v[144:147], v191 offset:16384
	ds_read_b128 v[148:151], v191 offset:17408
	ds_read_b128 v[168:171], v191 offset:18432
	ds_read_b128 v[172:175], v191 offset:19456
	ds_read_b128 v[176:179], v191 offset:20480
	ds_read_b128 v[180:183], v191 offset:21504
	ds_read_b128 v[194:197], v191 offset:22528
	ds_read_b128 v[198:201], v191 offset:23552
	global_load_lds_dwordx4 v[220:221], off
	v_lshl_add_u64 v[222:223], s[28:29], 0, v[156:157]
	s_mov_b32 m0, s37
	s_nop 0
	global_load_lds_dwordx4 v[222:223], off
	s_barrier
	s_waitcnt lgkmcnt(0)
	s_waitcnt lgkmcnt(0)
	v_mfma_f32_16x16x32_bf16 v[60:63], v[128:131], v[144:147], v[60:63]
	v_mfma_f32_16x16x32_bf16 v[56:59], v[136:139], v[144:147], v[56:59]
	v_mfma_f32_16x16x32_bf16 v[44:47], v[128:131], v[168:171], v[44:47]
	v_mfma_f32_16x16x32_bf16 v[40:43], v[136:139], v[168:171], v[40:43]
	v_mfma_f32_16x16x32_bf16 v[28:31], v[128:131], v[176:179], v[28:31]
	v_mfma_f32_16x16x32_bf16 v[24:27], v[136:139], v[176:179], v[24:27]
	v_mfma_f32_16x16x32_bf16 v[12:15], v[128:131], v[194:197], v[12:15]
	v_mfma_f32_16x16x32_bf16 v[8:11], v[136:139], v[194:197], v[8:11]
	v_mfma_f32_16x16x32_bf16 v[60:63], v[132:135], v[148:151], v[60:63]
	v_mfma_f32_16x16x32_bf16 v[56:59], v[140:143], v[148:151], v[56:59]
	v_mfma_f32_16x16x32_bf16 v[44:47], v[132:135], v[172:175], v[44:47]
	v_mfma_f32_16x16x32_bf16 v[40:43], v[140:143], v[172:175], v[40:43]
	v_mfma_f32_16x16x32_bf16 v[28:31], v[132:135], v[180:183], v[28:31]
	v_mfma_f32_16x16x32_bf16 v[24:27], v[140:143], v[180:183], v[24:27]
	v_mfma_f32_16x16x32_bf16 v[12:15], v[132:135], v[198:201], v[12:15]
	v_mfma_f32_16x16x32_bf16 v[8:11], v[140:143], v[198:201], v[8:11]
	s_barrier
	s_add_u32 s52, s22, 0x40000
	s_addc_u32 s53, s23, 0
	s_add_i32 s54, s46, s35
	v_lshl_add_u64 v[128:129], s[52:53], 0, v[154:155]
	s_mov_b32 m0, s54
	s_nop 0
	global_load_lds_dwordx4 v[128:129], off
	v_lshl_add_u64 v[128:129], s[52:53], 0, v[158:159]
	s_add_i32 m0, s54, 0x2000
	s_nop 0
	global_load_lds_dwordx4 v[128:129], off
	s_waitcnt vmcnt(6)
	s_barrier
	v_mfma_f32_16x16x32_bf16 v[52:55], v[202:205], v[144:147], v[52:55]
	v_mfma_f32_16x16x32_bf16 v[48:51], v[210:213], v[144:147], v[48:51]
	v_mfma_f32_16x16x32_bf16 v[36:39], v[202:205], v[168:171], v[36:39]
	v_mfma_f32_16x16x32_bf16 v[32:35], v[210:213], v[168:171], v[32:35]
	v_mfma_f32_16x16x32_bf16 v[20:23], v[202:205], v[176:179], v[20:23]
	v_mfma_f32_16x16x32_bf16 v[16:19], v[210:213], v[176:179], v[16:19]
	v_mfma_f32_16x16x32_bf16 v[4:7], v[202:205], v[194:197], v[4:7]
	v_mfma_f32_16x16x32_bf16 v[0:3], v[210:213], v[194:197], v[0:3]
	v_mfma_f32_16x16x32_bf16 v[52:55], v[206:209], v[148:151], v[52:55]
	v_mfma_f32_16x16x32_bf16 v[48:51], v[214:217], v[148:151], v[48:51]
	v_mfma_f32_16x16x32_bf16 v[36:39], v[206:209], v[172:175], v[36:39]
	v_mfma_f32_16x16x32_bf16 v[32:35], v[214:217], v[172:175], v[32:35]
	v_mfma_f32_16x16x32_bf16 v[20:23], v[206:209], v[180:183], v[20:23]
	v_mfma_f32_16x16x32_bf16 v[16:19], v[214:217], v[180:183], v[16:19]
	v_mfma_f32_16x16x32_bf16 v[4:7], v[206:209], v[198:201], v[4:7]
	v_mfma_f32_16x16x32_bf16 v[0:3], v[214:217], v[198:201], v[0:3]
	s_add_i32 s52, 0, 0x18000
	v_add_u32_e32 v140, s52, v187
	s_barrier
	ds_read_b128 v[128:131], v140
	ds_read_b128 v[132:135], v140 offset:1024
	ds_read_b128 v[136:139], v140 offset:2048
	ds_read_b128 v[140:143], v140 offset:3072
	s_add_u32 s28, s28, 0x40000
	s_addc_u32 s29, s29, 0
	s_mov_b32 m0, s38
	v_lshl_add_u64 v[202:203], s[28:29], 0, v[152:153]
	ds_read_b128 v[144:147], v191 offset:32768
	ds_read_b128 v[148:151], v191 offset:33792
	ds_read_b128 v[168:171], v191 offset:34816
	ds_read_b128 v[172:175], v191 offset:35840
	ds_read_b128 v[176:179], v191 offset:36864
	ds_read_b128 v[180:183], v191 offset:37888
	ds_read_b128 v[194:197], v191 offset:38912
	ds_read_b128 v[198:201], v191 offset:39936
	global_load_lds_dwordx4 v[202:203], off
	v_lshl_add_u64 v[202:203], s[28:29], 0, v[156:157]
	s_mov_b32 m0, s39
	s_nop 0
	global_load_lds_dwordx4 v[202:203], off
	s_waitcnt lgkmcnt(8)
	s_barrier
	s_waitcnt lgkmcnt(0)
	s_waitcnt lgkmcnt(0)
	v_mfma_f32_16x16x32_bf16 v[124:127], v[128:131], v[144:147], v[124:127]
	v_mfma_f32_16x16x32_bf16 v[120:123], v[136:139], v[144:147], v[120:123]
	v_mfma_f32_16x16x32_bf16 v[108:111], v[128:131], v[168:171], v[108:111]
	v_mfma_f32_16x16x32_bf16 v[104:107], v[136:139], v[168:171], v[104:107]
	v_mfma_f32_16x16x32_bf16 v[92:95], v[128:131], v[176:179], v[92:95]
	v_mfma_f32_16x16x32_bf16 v[88:91], v[136:139], v[176:179], v[88:91]
	v_mfma_f32_16x16x32_bf16 v[76:79], v[128:131], v[194:197], v[76:79]
	v_mfma_f32_16x16x32_bf16 v[72:75], v[136:139], v[194:197], v[72:75]
	v_mfma_f32_16x16x32_bf16 v[124:127], v[132:135], v[148:151], v[124:127]
	v_mfma_f32_16x16x32_bf16 v[120:123], v[140:143], v[148:151], v[120:123]
	v_mfma_f32_16x16x32_bf16 v[108:111], v[132:135], v[172:175], v[108:111]
	v_mfma_f32_16x16x32_bf16 v[104:107], v[140:143], v[172:175], v[104:107]
	v_mfma_f32_16x16x32_bf16 v[92:95], v[132:135], v[180:183], v[92:95]
	v_mfma_f32_16x16x32_bf16 v[88:91], v[140:143], v[180:183], v[88:91]
	v_mfma_f32_16x16x32_bf16 v[76:79], v[132:135], v[198:201], v[76:79]
	v_mfma_f32_16x16x32_bf16 v[72:75], v[140:143], v[198:201], v[72:75]
	s_barrier
	s_add_i32 s28, 0, 0x1c000
	s_add_i32 s29, s52, s35
	v_add_u32_e32 v214, s28, v187
	v_lshl_add_u64 v[184:185], v[184:185], 0, s[8:9]
	s_mov_b32 m0, s29
	ds_read_b128 v[202:205], v214
	ds_read_b128 v[206:209], v214 offset:1024
	ds_read_b128 v[210:213], v214 offset:2048
	ds_read_b128 v[214:217], v214 offset:3072
	global_load_lds_dwordx4 v[184:185], off
	v_lshl_add_u64 v[184:185], v[218:219], 0, s[8:9]
	s_add_i32 m0, s29, 0x2000
	s_nop 0
	global_load_lds_dwordx4 v[184:185], off
	s_barrier
	s_waitcnt lgkmcnt(0)
	s_waitcnt lgkmcnt(0)
	v_mfma_f32_16x16x32_bf16 v[116:119], v[202:205], v[144:147], v[116:119]
	v_mfma_f32_16x16x32_bf16 v[112:115], v[210:213], v[144:147], v[112:115]
	v_mfma_f32_16x16x32_bf16 v[100:103], v[202:205], v[168:171], v[100:103]
	v_mfma_f32_16x16x32_bf16 v[96:99], v[210:213], v[168:171], v[96:99]
	v_mfma_f32_16x16x32_bf16 v[84:87], v[202:205], v[176:179], v[84:87]
	v_mfma_f32_16x16x32_bf16 v[80:83], v[210:213], v[176:179], v[80:83]
	v_mfma_f32_16x16x32_bf16 v[68:71], v[202:205], v[194:197], v[68:71]
	v_mfma_f32_16x16x32_bf16 v[64:67], v[210:213], v[194:197], v[64:67]
	v_mfma_f32_16x16x32_bf16 v[116:119], v[206:209], v[148:151], v[116:119]
	v_mfma_f32_16x16x32_bf16 v[112:115], v[214:217], v[148:151], v[112:115]
	v_mfma_f32_16x16x32_bf16 v[100:103], v[206:209], v[172:175], v[100:103]
	v_mfma_f32_16x16x32_bf16 v[96:99], v[214:217], v[172:175], v[96:99]
	v_mfma_f32_16x16x32_bf16 v[84:87], v[206:209], v[180:183], v[84:87]
	v_mfma_f32_16x16x32_bf16 v[80:83], v[214:217], v[180:183], v[80:83]
	v_mfma_f32_16x16x32_bf16 v[68:71], v[206:209], v[198:201], v[68:71]
	v_mfma_f32_16x16x32_bf16 v[64:67], v[214:217], v[198:201], v[64:67]
	s_mov_b32 m0, s41
	v_lshl_add_u64 v[184:185], v[220:221], 0, s[8:9]
	s_barrier
	ds_read_b128 v[144:147], v191 offset:49152
	ds_read_b128 v[148:151], v191 offset:50176
	ds_read_b128 v[168:171], v191 offset:51200
	ds_read_b128 v[172:175], v191 offset:52224
	ds_read_b128 v[176:179], v191 offset:53248
	ds_read_b128 v[180:183], v191 offset:54272
	ds_read_b128 v[194:197], v191 offset:55296
	ds_read_b128 v[198:201], v191 offset:56320
	global_load_lds_dwordx4 v[184:185], off
	v_lshl_add_u64 v[184:185], v[222:223], 0, s[8:9]
	s_mov_b32 m0, s42
	s_nop 0
	global_load_lds_dwordx4 v[184:185], off
	s_barrier
	s_waitcnt lgkmcnt(0)
	s_waitcnt lgkmcnt(0)
	v_mfma_f32_16x16x32_bf16 v[60:63], v[128:131], v[144:147], v[60:63]
	v_mfma_f32_16x16x32_bf16 v[56:59], v[136:139], v[144:147], v[56:59]
	v_mfma_f32_16x16x32_bf16 v[44:47], v[128:131], v[168:171], v[44:47]
	v_mfma_f32_16x16x32_bf16 v[40:43], v[136:139], v[168:171], v[40:43]
	v_mfma_f32_16x16x32_bf16 v[28:31], v[128:131], v[176:179], v[28:31]
	v_mfma_f32_16x16x32_bf16 v[24:27], v[136:139], v[176:179], v[24:27]
	v_mfma_f32_16x16x32_bf16 v[12:15], v[128:131], v[194:197], v[12:15]
	v_mfma_f32_16x16x32_bf16 v[8:11], v[136:139], v[194:197], v[8:11]
	v_mfma_f32_16x16x32_bf16 v[60:63], v[132:135], v[148:151], v[60:63]
	v_mfma_f32_16x16x32_bf16 v[56:59], v[140:143], v[148:151], v[56:59]
	v_mfma_f32_16x16x32_bf16 v[44:47], v[132:135], v[172:175], v[44:47]
	v_mfma_f32_16x16x32_bf16 v[40:43], v[140:143], v[172:175], v[40:43]
	v_mfma_f32_16x16x32_bf16 v[28:31], v[132:135], v[180:183], v[28:31]
	v_mfma_f32_16x16x32_bf16 v[24:27], v[140:143], v[180:183], v[24:27]
	v_mfma_f32_16x16x32_bf16 v[12:15], v[132:135], v[198:201], v[12:15]
	v_mfma_f32_16x16x32_bf16 v[8:11], v[140:143], v[198:201], v[8:11]
	s_barrier
	s_add_u32 s22, s22, 0x40080
	s_addc_u32 s23, s23, 0
	s_add_i32 s28, s28, s35
	v_lshl_add_u64 v[128:129], s[22:23], 0, v[154:155]
	s_mov_b32 m0, s28
	s_nop 0
	global_load_lds_dwordx4 v[128:129], off
	v_lshl_add_u64 v[128:129], s[22:23], 0, v[158:159]
	s_add_i32 m0, s28, 0x2000
	s_nop 0
	global_load_lds_dwordx4 v[128:129], off
	s_waitcnt vmcnt(6)
	s_barrier
	v_mfma_f32_16x16x32_bf16 v[52:55], v[202:205], v[144:147], v[52:55]
	v_mfma_f32_16x16x32_bf16 v[48:51], v[210:213], v[144:147], v[48:51]
	v_mfma_f32_16x16x32_bf16 v[36:39], v[202:205], v[168:171], v[36:39]
	v_mfma_f32_16x16x32_bf16 v[32:35], v[210:213], v[168:171], v[32:35]
	v_mfma_f32_16x16x32_bf16 v[20:23], v[202:205], v[176:179], v[20:23]
	v_mfma_f32_16x16x32_bf16 v[16:19], v[210:213], v[176:179], v[16:19]
	v_mfma_f32_16x16x32_bf16 v[4:7], v[202:205], v[194:197], v[4:7]
	v_mfma_f32_16x16x32_bf16 v[0:3], v[210:213], v[194:197], v[0:3]
	v_mfma_f32_16x16x32_bf16 v[52:55], v[206:209], v[148:151], v[52:55]
	v_mfma_f32_16x16x32_bf16 v[48:51], v[214:217], v[148:151], v[48:51]
	v_mfma_f32_16x16x32_bf16 v[36:39], v[206:209], v[172:175], v[36:39]
	v_mfma_f32_16x16x32_bf16 v[32:35], v[214:217], v[172:175], v[32:35]
	v_mfma_f32_16x16x32_bf16 v[20:23], v[206:209], v[180:183], v[20:23]
	v_mfma_f32_16x16x32_bf16 v[16:19], v[214:217], v[180:183], v[16:19]
	v_mfma_f32_16x16x32_bf16 v[4:7], v[206:209], v[198:201], v[4:7]
	v_mfma_f32_16x16x32_bf16 v[0:3], v[214:217], v[198:201], v[0:3]
	s_add_i32 s51, s51, 2
	s_add_u32 s20, s20, 0x100
	s_addc_u32 s21, s21, 0
	s_add_u32 s49, s49, 0x100
	s_addc_u32 s50, s50, 0
	s_cmp_gt_u32 s51, 13
	s_barrier
	s_cbranch_scc0 .LBB0_1551
	v_lshl_or_b32 v168, s6, 8, v189
	v_lshl_add_u32 v170, s18, 8, v186
	v_ashrrev_i32_e32 v169, 31, v168
	v_lshlrev_b64 v[202:203], 1, v[168:169]
	v_ashrrev_i32_e32 v171, 31, v170
	v_or_b32_e32 v182, 16, v170
	v_lshl_add_u64 v[172:173], s[64:65], 0, v[202:203]
	v_lshlrev_b64 v[204:205], 11, v[170:171]
	v_ashrrev_i32_e32 v183, 31, v182
	v_or_b32_e32 v178, 32, v170
	v_lshl_add_u64 v[128:129], v[172:173], 0, v[204:205]
	v_lshlrev_b64 v[184:185], 11, v[182:183]
	v_ashrrev_i32_e32 v179, 31, v178
	v_or_b32_e32 v174, 48, v170
	global_load_dwordx4 v[194:197], v[128:129], off
	global_load_dwordx4 v[198:201], v[128:129], off offset:256
	v_lshl_add_u64 v[128:129], v[172:173], 0, v[184:185]
	v_lshlrev_b64 v[180:181], 11, v[178:179]
	v_ashrrev_i32_e32 v175, 31, v174
	global_load_dwordx4 v[148:151], v[128:129], off
	global_load_dwordx4 v[144:147], v[128:129], off offset:256
	v_lshl_add_u64 v[128:129], v[172:173], 0, v[180:181]
	v_lshlrev_b64 v[176:177], 11, v[174:175]
	global_load_dwordx4 v[140:143], v[128:129], off
	global_load_dwordx4 v[136:139], v[128:129], off offset:256
	v_lshl_add_u64 v[128:129], v[172:173], 0, v[176:177]
	global_load_dwordx4 v[132:135], v[128:129], off
	s_nop 0
	global_load_dwordx4 v[128:131], v[128:129], off offset:256
	s_lshl_b32 s18, s6, 2
	s_ashr_i32 s19, s18, 31
	v_add_u32_e32 v252, 0x80, v170
	v_ashrrev_i32_e32 v253, 31, v252
	v_lshlrev_b64 v[252:253], 11, v[252:253]
	v_lshl_add_u64 v[252:253], v[172:173], 0, v[252:253]
	global_load_dwordx4 v[236:239], v[252:253], off
	global_load_dwordx4 v[240:243], v[252:253], off offset:256
	v_add_u32_e32 v252, 0x90, v170
	v_ashrrev_i32_e32 v253, 31, v252
	v_lshlrev_b64 v[252:253], 11, v[252:253]
	v_lshl_add_u64 v[252:253], v[172:173], 0, v[252:253]
	global_load_dwordx4 v[244:247], v[252:253], off
	global_load_dwordx4 v[248:251], v[252:253], off offset:256
	v_add_u32_e32 v252, 0xa0, v170
	v_ashrrev_i32_e32 v253, 31, v252
	v_lshlrev_b64 v[252:253], 11, v[252:253]
	v_lshl_add_u64 v[252:253], v[172:173], 0, v[252:253]
	global_load_dwordx4 v[210:213], v[252:253], off
	global_load_dwordx4 v[214:217], v[252:253], off offset:256
	s_waitcnt vmcnt(6)
	v_lshlrev_b32_e32 v206, 16, v194
	v_and_b32_e32 v207, 0xffff0000, v194
	v_lshlrev_b32_e32 v194, 16, v195
	v_and_b32_e32 v195, 0xffff0000, v195
	v_lshlrev_b32_e32 v208, 16, v196
	v_and_b32_e32 v209, 0xffff0000, v196
	v_lshlrev_b32_e32 v196, 16, v197
	v_and_b32_e32 v197, 0xffff0000, v197
	v_pk_add_f32 v[126:127], v[126:127], v[194:195]
	v_pk_add_f32 v[124:125], v[124:125], v[206:207]
	v_pk_add_f32 v[194:195], v[122:123], v[196:197]
	v_pk_add_f32 v[122:123], v[120:121], v[208:209]
	v_mul_f32_e32 v120, v125, v125
	v_mul_f32_e32 v121, v127, v127
	v_fmac_f32_e32 v120, v124, v124
	v_fmac_f32_e32 v121, v126, v126
	v_add_f32_e32 v120, v120, v121
	v_mul_f32_e32 v121, v123, v123
	v_mul_f32_e32 v196, v195, v195
	v_fmac_f32_e32 v121, v122, v122
	v_fmac_f32_e32 v196, v194, v194
	v_add_f32_e32 v121, v121, v196
	v_add_f32_e32 v206, v120, v121
	v_cvt_pk_bf16_f32 v120, v124, v125
	v_cvt_pk_bf16_f32 v121, v126, v127
	v_lshlrev_b32_e32 v124, 16, v198
	v_and_b32_e32 v125, 0xffff0000, v198
	v_lshlrev_b32_e32 v126, 16, v199
	v_and_b32_e32 v127, 0xffff0000, v199
	v_cvt_pk_bf16_f32 v122, v122, v123
	v_cvt_pk_bf16_f32 v123, v194, v195
	v_lshlrev_b32_e32 v194, 16, v200
	v_and_b32_e32 v195, 0xffff0000, v200
	v_pk_add_f32 v[118:119], v[118:119], v[126:127]
	v_pk_add_f32 v[116:117], v[116:117], v[124:125]
	v_lshlrev_b32_e32 v196, 16, v201
	v_and_b32_e32 v197, 0xffff0000, v201
	v_pk_add_f32 v[126:127], v[112:113], v[194:195]
	v_mul_f32_e32 v112, v117, v117
	v_mul_f32_e32 v113, v119, v119
	v_pk_add_f32 v[124:125], v[114:115], v[196:197]
	v_fmac_f32_e32 v112, v116, v116
	v_fmac_f32_e32 v113, v118, v118
	v_add_f32_e32 v112, v112, v113
	v_mul_f32_e32 v113, v127, v127
	v_mul_f32_e32 v114, v125, v125
	v_fmac_f32_e32 v113, v126, v126
	v_fmac_f32_e32 v114, v124, v124
	v_add_f32_e32 v113, v113, v114
	v_add_f32_e32 v112, v112, v113
	v_and_b32_e32 v114, 64, v193
	v_add_f32_e32 v113, v206, v112
	v_xor_b32_e32 v112, 16, v193
	v_add_u32_e32 v196, 64, v114
	v_cmp_lt_i32_e32 vcc, v112, v196
	v_lshl_add_u64 v[114:115], s[64:65], 0, v[204:205]
	v_lshl_add_u64 v[194:195], v[114:115], 0, v[202:203]
	v_cndmask_b32_e32 v112, v193, v112, vcc
	v_lshlrev_b32_e32 v112, 2, v112
	ds_bpermute_b32 v197, v112, v113
	global_store_dwordx4 v[194:195], v[120:123], off
	v_cvt_pk_bf16_f32 v116, v116, v117
	v_cvt_pk_bf16_f32 v117, v118, v119
	v_cvt_pk_bf16_f32 v118, v126, v127
	s_waitcnt lgkmcnt(0)
	v_add_f32_e32 v114, v113, v197
	v_xor_b32_e32 v113, 32, v193
	v_cmp_lt_i32_e32 vcc, v113, v196
	v_cvt_pk_bf16_f32 v119, v124, v125
	global_store_dwordx4 v[194:195], v[116:119], off offset:256
	s_nop 0
	v_cndmask_b32_e32 v113, v193, v113, vcc
	v_lshlrev_b32_e32 v113, 2, v113
	ds_bpermute_b32 v115, v113, v114
	s_and_saveexec_b64 s[20:21], s[2:3]
	s_cbranch_execz .LBB0_1554
	s_waitcnt lgkmcnt(0)
	v_add_f32_e32 v116, v114, v115
	v_lshlrev_b64 v[114:115], 6, v[170:171]
	v_lshl_add_u64 v[114:115], s[74:75], 0, v[114:115]
	v_lshl_add_u64 v[114:115], s[18:19], 2, v[114:115]
	s_lshl_b32 s6, s40, 2
	v_lshl_add_u64 v[114:115], v[114:115], 0, s[6:7]
	global_store_dword v[114:115], v116, off

.LBB0_1639:
	ds_read_b128 v[16:19], v212
	ds_read_b128 v[20:23], v212 offset:1024
	ds_read_b128 v[24:27], v212 offset:2048
	ds_read_b128 v[68:71], v212 offset:3072
	s_add_u32 s28, s8, 0x100
	s_addc_u32 s29, s9, 0
	s_cmp_eq_u32 s67, 12
	s_cselect_b32 s35, s59, s29
	s_cselect_b32 s34, s60, s28
	s_cselect_b32 s31, s11, s63
	s_cselect_b32 s30, s61, s62
	v_lshl_add_u64 v[176:177], s[8:9], 0, v[204:205]
	s_add_i32 m0, s42, 0xc000
	ds_read_b128 v[96:99], v213
	ds_read_b128 v[148:151], v213 offset:1024
	ds_read_b128 v[152:155], v213 offset:2048
	ds_read_b128 v[156:159], v213 offset:3072
	ds_read_b128 v[160:163], v213 offset:4096
	ds_read_b128 v[164:167], v213 offset:5120
	ds_read_b128 v[168:171], v213 offset:6144
	ds_read_b128 v[172:175], v213 offset:7168
	global_load_lds_dwordx4 v[176:177], off
	v_lshl_add_u64 v[176:177], s[8:9], 0, v[206:207]
	s_add_i32 m0, s42, 0xe000
	s_nop 0
	global_load_lds_dwordx4 v[176:177], off
	s_waitcnt lgkmcnt(8)
	s_barrier
	s_waitcnt lgkmcnt(0)
	s_waitcnt lgkmcnt(0)
	v_mfma_f32_16x16x32_bf16 v[112:115], v[16:19], v[96:99], v[112:115]
	v_mfma_f32_16x16x32_bf16 v[40:43], v[24:27], v[96:99], v[40:43]
	v_mfma_f32_16x16x32_bf16 v[108:111], v[16:19], v[152:155], v[108:111]
	v_mfma_f32_16x16x32_bf16 v[36:39], v[24:27], v[152:155], v[36:39]
	v_mfma_f32_16x16x32_bf16 v[144:147], v[16:19], v[160:163], v[144:147]
	v_mfma_f32_16x16x32_bf16 v[140:143], v[24:27], v[160:163], v[140:143]
	v_mfma_f32_16x16x32_bf16 v[136:139], v[16:19], v[168:171], v[136:139]
	v_mfma_f32_16x16x32_bf16 v[132:135], v[24:27], v[168:171], v[132:135]
	v_mfma_f32_16x16x32_bf16 v[112:115], v[20:23], v[148:151], v[112:115]
	v_mfma_f32_16x16x32_bf16 v[40:43], v[68:71], v[148:151], v[40:43]
	v_mfma_f32_16x16x32_bf16 v[108:111], v[20:23], v[156:159], v[108:111]
	v_mfma_f32_16x16x32_bf16 v[36:39], v[68:71], v[156:159], v[36:39]
	v_mfma_f32_16x16x32_bf16 v[144:147], v[20:23], v[164:167], v[144:147]
	v_mfma_f32_16x16x32_bf16 v[140:143], v[68:71], v[164:167], v[140:143]
	v_mfma_f32_16x16x32_bf16 v[136:139], v[20:23], v[172:175], v[136:139]
	v_mfma_f32_16x16x32_bf16 v[132:135], v[68:71], v[172:175], v[132:135]
	s_barrier
	s_add_i32 s8, s52, s41
	v_lshl_add_u64 v[222:223], s[30:31], 0, v[192:193]
	s_mov_b32 m0, s8
	ds_read_b128 v[176:179], v214
	ds_read_b128 v[180:183], v214 offset:1024
	ds_read_b128 v[184:187], v214 offset:2048
	ds_read_b128 v[218:221], v214 offset:3072
	global_load_lds_dwordx4 v[222:223], off
	v_lshl_add_u64 v[224:225], s[30:31], 0, v[198:199]
	s_add_i32 m0, s8, 0x2000
	s_nop 0
	global_load_lds_dwordx4 v[224:225], off
	s_barrier
	s_waitcnt lgkmcnt(0)
	s_waitcnt lgkmcnt(0)
	v_mfma_f32_16x16x32_bf16 v[104:107], v[176:179], v[96:99], v[104:107]
	v_mfma_f32_16x16x32_bf16 v[32:35], v[184:187], v[96:99], v[32:35]
	v_mfma_f32_16x16x32_bf16 v[28:31], v[184:187], v[152:155], v[28:31]
	v_mfma_f32_16x16x32_bf16 v[80:83], v[176:179], v[160:163], v[80:83]
	v_mfma_f32_16x16x32_bf16 v[92:95], v[184:187], v[160:163], v[92:95]
	v_mfma_f32_16x16x32_bf16 v[84:87], v[176:179], v[168:171], v[84:87]
	v_mfma_f32_16x16x32_bf16 v[88:91], v[184:187], v[168:171], v[88:91]
	v_mfma_f32_16x16x32_bf16 v[104:107], v[180:183], v[148:151], v[104:107]
	v_mfma_f32_16x16x32_bf16 v[32:35], v[218:221], v[148:151], v[32:35]
	v_mfma_f32_16x16x32_bf16 v[96:99], v[176:179], v[152:155], v[100:103]
	v_mfma_f32_16x16x32_bf16 v[28:31], v[218:221], v[156:159], v[28:31]
	v_mfma_f32_16x16x32_bf16 v[80:83], v[180:183], v[164:167], v[80:83]
	v_mfma_f32_16x16x32_bf16 v[92:95], v[218:221], v[164:167], v[92:95]
	v_mfma_f32_16x16x32_bf16 v[84:87], v[180:183], v[172:175], v[84:87]
	v_mfma_f32_16x16x32_bf16 v[88:91], v[218:221], v[172:175], v[88:91]
	v_mfma_f32_16x16x32_bf16 v[96:99], v[180:183], v[156:159], v[96:99]
	s_mov_b32 m0, s42
	v_lshl_add_u64 v[226:227], s[34:35], 0, v[194:195]
	s_barrier
	ds_read_b128 v[100:103], v213 offset:16384
	ds_read_b128 v[148:151], v213 offset:17408
	ds_read_b128 v[152:155], v213 offset:18432
	ds_read_b128 v[156:159], v213 offset:19456
	ds_read_b128 v[160:163], v213 offset:20480
	ds_read_b128 v[164:167], v213 offset:21504
	ds_read_b128 v[168:171], v213 offset:22528
	ds_read_b128 v[172:175], v213 offset:23552
	global_load_lds_dwordx4 v[226:227], off
	v_lshl_add_u64 v[228:229], s[34:35], 0, v[196:197]
	s_mov_b32 m0, s43
	s_nop 0
	global_load_lds_dwordx4 v[228:229], off
	s_barrier
	s_waitcnt lgkmcnt(0)
	s_waitcnt lgkmcnt(0)
	v_mfma_f32_16x16x32_bf16 v[76:79], v[16:19], v[100:103], v[76:79]
	v_mfma_f32_16x16x32_bf16 v[12:15], v[24:27], v[100:103], v[12:15]
	v_mfma_f32_16x16x32_bf16 v[72:75], v[16:19], v[152:155], v[72:75]
	v_mfma_f32_16x16x32_bf16 v[8:11], v[24:27], v[152:155], v[8:11]
	v_mfma_f32_16x16x32_bf16 v[128:131], v[16:19], v[160:163], v[128:131]
	v_mfma_f32_16x16x32_bf16 v[124:127], v[24:27], v[160:163], v[124:127]
	v_mfma_f32_16x16x32_bf16 v[16:19], v[16:19], v[168:171], v[120:123]
	v_mfma_f32_16x16x32_bf16 v[76:79], v[20:23], v[148:151], v[76:79]
	v_mfma_f32_16x16x32_bf16 v[12:15], v[68:71], v[148:151], v[12:15]
	v_mfma_f32_16x16x32_bf16 v[72:75], v[20:23], v[156:159], v[72:75]
	v_mfma_f32_16x16x32_bf16 v[8:11], v[68:71], v[156:159], v[8:11]
	v_mfma_f32_16x16x32_bf16 v[128:131], v[20:23], v[164:167], v[128:131]
	v_mfma_f32_16x16x32_bf16 v[124:127], v[68:71], v[164:167], v[124:127]
	v_mfma_f32_16x16x32_bf16 v[16:19], v[20:23], v[172:175], v[16:19]
	v_mfma_f32_16x16x32_bf16 v[20:23], v[24:27], v[168:171], v[116:119]
	v_mfma_f32_16x16x32_bf16 v[20:23], v[68:71], v[172:175], v[20:23]
	s_barrier
	s_add_u32 s8, s30, 0x40000
	s_addc_u32 s9, s31, 0
	s_add_i32 s68, s53, s41
	v_lshl_add_u64 v[24:25], s[8:9], 0, v[192:193]
	s_mov_b32 m0, s68
	s_nop 0
	global_load_lds_dwordx4 v[24:25], off
	v_lshl_add_u64 v[24:25], s[8:9], 0, v[198:199]
	s_add_i32 m0, s68, 0x2000
	s_nop 0
	global_load_lds_dwordx4 v[24:25], off
	s_waitcnt vmcnt(6)
	s_barrier
	v_mfma_f32_16x16x32_bf16 v[4:7], v[184:187], v[100:103], v[4:7]
	v_mfma_f32_16x16x32_bf16 v[60:63], v[176:179], v[152:155], v[60:63]
	v_mfma_f32_16x16x32_bf16 v[0:3], v[184:187], v[152:155], v[0:3]
	v_mfma_f32_16x16x32_bf16 v[44:47], v[176:179], v[160:163], v[44:47]
	v_mfma_f32_16x16x32_bf16 v[48:51], v[184:187], v[160:163], v[48:51]
	v_mfma_f32_16x16x32_bf16 v[52:55], v[176:179], v[168:171], v[52:55]
	v_mfma_f32_16x16x32_bf16 v[56:59], v[184:187], v[168:171], v[56:59]
	v_mfma_f32_16x16x32_bf16 v[24:27], v[176:179], v[100:103], v[64:67]
	v_mfma_f32_16x16x32_bf16 v[4:7], v[218:221], v[148:151], v[4:7]
	v_mfma_f32_16x16x32_bf16 v[60:63], v[180:183], v[156:159], v[60:63]
	v_mfma_f32_16x16x32_bf16 v[0:3], v[218:221], v[156:159], v[0:3]
	v_mfma_f32_16x16x32_bf16 v[44:47], v[180:183], v[164:167], v[44:47]
	v_mfma_f32_16x16x32_bf16 v[48:51], v[218:221], v[164:167], v[48:51]
	v_mfma_f32_16x16x32_bf16 v[52:55], v[180:183], v[172:175], v[52:55]
	v_mfma_f32_16x16x32_bf16 v[56:59], v[218:221], v[172:175], v[56:59]
	v_mfma_f32_16x16x32_bf16 v[24:27], v[180:183], v[148:151], v[24:27]
	s_add_i32 s68, 0, 0x18000
	v_add_u32_e32 v100, s68, v208
	s_barrier
	ds_read_b128 v[64:67], v100
	ds_read_b128 v[68:71], v100 offset:1024
	ds_read_b128 v[116:119], v100 offset:2048
	ds_read_b128 v[148:151], v100 offset:3072
	s_add_u32 s8, s34, 0x40000
	s_addc_u32 s9, s35, 0
	s_mov_b32 m0, s44
	v_lshl_add_u64 v[176:177], s[8:9], 0, v[194:195]
	ds_read_b128 v[100:103], v213 offset:32768
	ds_read_b128 v[120:123], v213 offset:33792
	ds_read_b128 v[152:155], v213 offset:34816
	ds_read_b128 v[156:159], v213 offset:35840
	ds_read_b128 v[160:163], v213 offset:36864
	ds_read_b128 v[164:167], v213 offset:37888
	ds_read_b128 v[168:171], v213 offset:38912
	ds_read_b128 v[172:175], v213 offset:39936
	global_load_lds_dwordx4 v[176:177], off
	v_lshl_add_u64 v[176:177], s[8:9], 0, v[196:197]
	s_mov_b32 m0, s45
	s_nop 0
	global_load_lds_dwordx4 v[176:177], off
	s_waitcnt lgkmcnt(8)
	s_barrier
	s_waitcnt lgkmcnt(0)
	s_waitcnt lgkmcnt(0)
	v_mfma_f32_16x16x32_bf16 v[112:115], v[64:67], v[100:103], v[112:115]
	v_mfma_f32_16x16x32_bf16 v[40:43], v[116:119], v[100:103], v[40:43]
	v_mfma_f32_16x16x32_bf16 v[108:111], v[64:67], v[152:155], v[108:111]
	v_mfma_f32_16x16x32_bf16 v[36:39], v[116:119], v[152:155], v[36:39]
	v_mfma_f32_16x16x32_bf16 v[144:147], v[64:67], v[160:163], v[144:147]
	v_mfma_f32_16x16x32_bf16 v[140:143], v[116:119], v[160:163], v[140:143]
	v_mfma_f32_16x16x32_bf16 v[136:139], v[64:67], v[168:171], v[136:139]
	v_mfma_f32_16x16x32_bf16 v[132:135], v[116:119], v[168:171], v[132:135]
	v_mfma_f32_16x16x32_bf16 v[112:115], v[68:71], v[120:123], v[112:115]
	v_mfma_f32_16x16x32_bf16 v[40:43], v[148:151], v[120:123], v[40:43]
	v_mfma_f32_16x16x32_bf16 v[108:111], v[68:71], v[156:159], v[108:111]
	v_mfma_f32_16x16x32_bf16 v[36:39], v[148:151], v[156:159], v[36:39]
	v_mfma_f32_16x16x32_bf16 v[144:147], v[68:71], v[164:167], v[144:147]
	v_mfma_f32_16x16x32_bf16 v[140:143], v[148:151], v[164:167], v[140:143]
	v_mfma_f32_16x16x32_bf16 v[136:139], v[68:71], v[172:175], v[136:139]
	v_mfma_f32_16x16x32_bf16 v[132:135], v[148:151], v[172:175], v[132:135]
	s_barrier
	s_add_i32 s34, 0, 0x1c000
	s_add_i32 s8, s68, s41
	v_add_u32_e32 v217, s34, v208
	v_lshl_add_u64 v[222:223], v[222:223], 0, s[18:19]
	s_mov_b32 m0, s8
	ds_read_b128 v[176:179], v217
	ds_read_b128 v[180:183], v217 offset:1024
	ds_read_b128 v[184:187], v217 offset:2048
	ds_read_b128 v[218:221], v217 offset:3072
	global_load_lds_dwordx4 v[222:223], off
	v_lshl_add_u64 v[222:223], v[224:225], 0, s[18:19]
	s_add_i32 m0, s8, 0x2000
	s_nop 0
	global_load_lds_dwordx4 v[222:223], off
	s_barrier
	s_waitcnt lgkmcnt(0)
	s_waitcnt lgkmcnt(0)
	v_mfma_f32_16x16x32_bf16 v[104:107], v[176:179], v[100:103], v[104:107]
	v_mfma_f32_16x16x32_bf16 v[32:35], v[184:187], v[100:103], v[32:35]
	v_mfma_f32_16x16x32_bf16 v[96:99], v[176:179], v[152:155], v[96:99]
	v_mfma_f32_16x16x32_bf16 v[28:31], v[184:187], v[152:155], v[28:31]
	v_mfma_f32_16x16x32_bf16 v[80:83], v[176:179], v[160:163], v[80:83]
	v_mfma_f32_16x16x32_bf16 v[92:95], v[184:187], v[160:163], v[92:95]
	v_mfma_f32_16x16x32_bf16 v[84:87], v[176:179], v[168:171], v[84:87]
	v_mfma_f32_16x16x32_bf16 v[88:91], v[184:187], v[168:171], v[88:91]
	v_mfma_f32_16x16x32_bf16 v[104:107], v[180:183], v[120:123], v[104:107]
	v_mfma_f32_16x16x32_bf16 v[32:35], v[218:221], v[120:123], v[32:35]
	v_mfma_f32_16x16x32_bf16 v[100:103], v[180:183], v[156:159], v[96:99]
	v_mfma_f32_16x16x32_bf16 v[28:31], v[218:221], v[156:159], v[28:31]
	v_mfma_f32_16x16x32_bf16 v[80:83], v[180:183], v[164:167], v[80:83]
	v_mfma_f32_16x16x32_bf16 v[92:95], v[218:221], v[164:167], v[92:95]
	v_mfma_f32_16x16x32_bf16 v[84:87], v[180:183], v[172:175], v[84:87]
	v_mfma_f32_16x16x32_bf16 v[88:91], v[218:221], v[172:175], v[88:91]
	s_mov_b32 m0, s49
	v_lshl_add_u64 v[120:121], v[226:227], 0, s[18:19]
	s_barrier
	ds_read_b128 v[96:99], v213 offset:49152
	ds_read_b128 v[152:155], v213 offset:50176
	ds_read_b128 v[156:159], v213 offset:51200
	ds_read_b128 v[160:163], v213 offset:52224
	ds_read_b128 v[164:167], v213 offset:53248
	ds_read_b128 v[168:171], v213 offset:54272
	ds_read_b128 v[172:175], v213 offset:55296
	ds_read_b128 v[222:225], v213 offset:56320
	global_load_lds_dwordx4 v[120:121], off
	v_lshl_add_u64 v[120:121], v[228:229], 0, s[18:19]
	s_mov_b32 m0, s50
	s_nop 0
	global_load_lds_dwordx4 v[120:121], off
	s_barrier
	s_waitcnt lgkmcnt(0)
	s_waitcnt lgkmcnt(0)
	v_mfma_f32_16x16x32_bf16 v[120:123], v[64:67], v[164:167], v[128:131]
	v_mfma_f32_16x16x32_bf16 v[128:131], v[68:71], v[168:171], v[120:123]
	v_mfma_f32_16x16x32_bf16 v[120:123], v[116:119], v[164:167], v[124:127]
	v_mfma_f32_16x16x32_bf16 v[16:19], v[64:67], v[172:175], v[16:19]
	v_mfma_f32_16x16x32_bf16 v[76:79], v[64:67], v[96:99], v[76:79]
	v_mfma_f32_16x16x32_bf16 v[12:15], v[116:119], v[96:99], v[12:15]
	v_mfma_f32_16x16x32_bf16 v[72:75], v[64:67], v[156:159], v[72:75]
	v_mfma_f32_16x16x32_bf16 v[8:11], v[116:119], v[156:159], v[8:11]
	v_mfma_f32_16x16x32_bf16 v[124:127], v[148:151], v[168:171], v[120:123]
	v_mfma_f32_16x16x32_bf16 v[120:123], v[68:71], v[222:225], v[16:19]
	v_mfma_f32_16x16x32_bf16 v[16:19], v[116:119], v[172:175], v[20:23]
	v_mfma_f32_16x16x32_bf16 v[76:79], v[68:71], v[152:155], v[76:79]
	v_mfma_f32_16x16x32_bf16 v[12:15], v[148:151], v[152:155], v[12:15]
	v_mfma_f32_16x16x32_bf16 v[72:75], v[68:71], v[160:163], v[72:75]
	v_mfma_f32_16x16x32_bf16 v[8:11], v[148:151], v[160:163], v[8:11]
	v_mfma_f32_16x16x32_bf16 v[116:119], v[148:151], v[222:225], v[16:19]
	s_barrier
	s_add_u32 s8, s30, 0x40080
	s_addc_u32 s9, s31, 0
	s_add_i32 s30, s34, s41
	v_lshl_add_u64 v[16:17], s[8:9], 0, v[192:193]
	s_mov_b32 m0, s30
	s_nop 0
	global_load_lds_dwordx4 v[16:17], off
	v_lshl_add_u64 v[16:17], s[8:9], 0, v[198:199]
	s_add_i32 m0, s30, 0x2000
	s_nop 0
	global_load_lds_dwordx4 v[16:17], off
	s_waitcnt vmcnt(6)
	s_barrier
	v_mfma_f32_16x16x32_bf16 v[16:19], v[176:179], v[96:99], v[24:27]
	v_mfma_f32_16x16x32_bf16 v[64:67], v[180:183], v[152:155], v[16:19]
	v_mfma_f32_16x16x32_bf16 v[16:19], v[176:179], v[156:159], v[60:63]
	v_mfma_f32_16x16x32_bf16 v[60:63], v[180:183], v[160:163], v[16:19]
	v_mfma_f32_16x16x32_bf16 v[16:19], v[176:179], v[164:167], v[44:47]
	v_mfma_f32_16x16x32_bf16 v[44:47], v[180:183], v[168:171], v[16:19]
	v_mfma_f32_16x16x32_bf16 v[16:19], v[184:187], v[164:167], v[48:51]
	v_mfma_f32_16x16x32_bf16 v[48:51], v[218:221], v[168:171], v[16:19]
	v_mfma_f32_16x16x32_bf16 v[16:19], v[176:179], v[172:175], v[52:55]
	v_mfma_f32_16x16x32_bf16 v[4:7], v[184:187], v[96:99], v[4:7]
	v_mfma_f32_16x16x32_bf16 v[0:3], v[184:187], v[156:159], v[0:3]
	v_mfma_f32_16x16x32_bf16 v[52:55], v[180:183], v[222:225], v[16:19]
	v_mfma_f32_16x16x32_bf16 v[16:19], v[184:187], v[172:175], v[56:59]
	v_mfma_f32_16x16x32_bf16 v[4:7], v[218:221], v[152:155], v[4:7]
	v_mfma_f32_16x16x32_bf16 v[0:3], v[218:221], v[160:163], v[0:3]
	v_mfma_f32_16x16x32_bf16 v[56:59], v[218:221], v[222:225], v[16:19]
	s_add_i32 s67, s67, 2
	s_add_u32 s62, s62, 0x100
	s_addc_u32 s63, s63, 0
	s_cmp_gt_u32 s67, 13
	s_mov_b64 s[8:9], s[28:29]
	s_barrier
	s_cbranch_scc0 .LBB0_1639
	v_cndmask_b32_e64 v16, 0, 1, s[26:27]
	v_cmp_ne_u32_e64 s[8:9], 1, v16
	s_andn2_b64 vcc, exec, s[26:27]
	s_cbranch_vccnz .LBB0_1644
	v_mov_b32_e32 v16, 0
	v_mov_b32_e32 v17, 0
	v_mov_b32_e32 v18, 0
	v_mov_b32_e32 v19, 0
	s_and_saveexec_b64 s[26:27], s[2:3]
	s_cbranch_execz .LBB0_1643
	s_lshl_b32 s28, s10, 7
	s_ashr_i32 s29, s28, 31
	v_lshl_add_u64 v[16:17], s[28:29], 2, v[202:203]
	global_load_dwordx4 v[16:19], v[16:17], off

.LBB0_1741:
	ds_read_b128 v[128:131], v190
	ds_read_b128 v[132:135], v190 offset:1024
	ds_read_b128 v[136:139], v190 offset:2048
	ds_read_b128 v[140:143], v190 offset:3072
	s_add_u32 s16, s14, 0x100
	s_addc_u32 s17, s15, 0
	s_cmp_eq_u32 s47, 40
	s_cselect_b32 s21, s1, s17
	s_cselect_b32 s20, s0, s16
	s_cselect_b32 s19, s7, s46
	s_cselect_b32 s18, s6, s45
	v_lshl_add_u64 v[184:185], s[14:15], 0, v[160:161]
	s_add_i32 m0, s28, 0xc000
	ds_read_b128 v[144:147], v191
	ds_read_b128 v[148:151], v191 offset:1024
	ds_read_b128 v[168:171], v191 offset:2048
	ds_read_b128 v[172:175], v191 offset:3072
	ds_read_b128 v[176:179], v191 offset:4096
	ds_read_b128 v[180:183], v191 offset:5120
	ds_read_b128 v[194:197], v191 offset:6144
	ds_read_b128 v[198:201], v191 offset:7168
	global_load_lds_dwordx4 v[184:185], off
	v_lshl_add_u64 v[184:185], s[14:15], 0, v[162:163]
	s_add_i32 m0, s28, 0xe000
	s_nop 0
	global_load_lds_dwordx4 v[184:185], off
	s_waitcnt lgkmcnt(8)
	s_barrier
	s_waitcnt lgkmcnt(0)
	s_waitcnt lgkmcnt(0)
	v_mfma_f32_16x16x32_bf16 v[124:127], v[128:131], v[144:147], v[124:127]
	v_mfma_f32_16x16x32_bf16 v[120:123], v[136:139], v[144:147], v[120:123]
	v_mfma_f32_16x16x32_bf16 v[108:111], v[128:131], v[168:171], v[108:111]
	v_mfma_f32_16x16x32_bf16 v[104:107], v[136:139], v[168:171], v[104:107]
	v_mfma_f32_16x16x32_bf16 v[92:95], v[128:131], v[176:179], v[92:95]
	v_mfma_f32_16x16x32_bf16 v[88:91], v[136:139], v[176:179], v[88:91]
	v_mfma_f32_16x16x32_bf16 v[76:79], v[128:131], v[194:197], v[76:79]
	v_mfma_f32_16x16x32_bf16 v[72:75], v[136:139], v[194:197], v[72:75]
	v_mfma_f32_16x16x32_bf16 v[124:127], v[132:135], v[148:151], v[124:127]
	v_mfma_f32_16x16x32_bf16 v[120:123], v[140:143], v[148:151], v[120:123]
	v_mfma_f32_16x16x32_bf16 v[108:111], v[132:135], v[172:175], v[108:111]
	v_mfma_f32_16x16x32_bf16 v[104:107], v[140:143], v[172:175], v[104:107]
	v_mfma_f32_16x16x32_bf16 v[92:95], v[132:135], v[180:183], v[92:95]
	v_mfma_f32_16x16x32_bf16 v[88:91], v[140:143], v[180:183], v[88:91]
	v_mfma_f32_16x16x32_bf16 v[76:79], v[132:135], v[198:201], v[76:79]
	v_mfma_f32_16x16x32_bf16 v[72:75], v[140:143], v[198:201], v[72:75]
	s_barrier
	s_add_i32 s14, s39, s27
	v_lshl_add_u64 v[184:185], s[18:19], 0, v[154:155]
	s_mov_b32 m0, s14
	ds_read_b128 v[202:205], v192
	ds_read_b128 v[206:209], v192 offset:1024
	ds_read_b128 v[210:213], v192 offset:2048
	ds_read_b128 v[214:217], v192 offset:3072
	global_load_lds_dwordx4 v[184:185], off
	v_lshl_add_u64 v[218:219], s[18:19], 0, v[158:159]
	s_add_i32 m0, s14, 0x2000
	s_nop 0
	global_load_lds_dwordx4 v[218:219], off
	s_barrier
	s_waitcnt lgkmcnt(0)
	s_waitcnt lgkmcnt(0)
	v_mfma_f32_16x16x32_bf16 v[116:119], v[202:205], v[144:147], v[116:119]
	v_mfma_f32_16x16x32_bf16 v[112:115], v[210:213], v[144:147], v[112:115]
	v_mfma_f32_16x16x32_bf16 v[100:103], v[202:205], v[168:171], v[100:103]
	v_mfma_f32_16x16x32_bf16 v[96:99], v[210:213], v[168:171], v[96:99]
	v_mfma_f32_16x16x32_bf16 v[84:87], v[202:205], v[176:179], v[84:87]
	v_mfma_f32_16x16x32_bf16 v[80:83], v[210:213], v[176:179], v[80:83]
	v_mfma_f32_16x16x32_bf16 v[68:71], v[202:205], v[194:197], v[68:71]
	v_mfma_f32_16x16x32_bf16 v[64:67], v[210:213], v[194:197], v[64:67]
	v_mfma_f32_16x16x32_bf16 v[116:119], v[206:209], v[148:151], v[116:119]
	v_mfma_f32_16x16x32_bf16 v[112:115], v[214:217], v[148:151], v[112:115]
	v_mfma_f32_16x16x32_bf16 v[100:103], v[206:209], v[172:175], v[100:103]
	v_mfma_f32_16x16x32_bf16 v[96:99], v[214:217], v[172:175], v[96:99]
	v_mfma_f32_16x16x32_bf16 v[84:87], v[206:209], v[180:183], v[84:87]
	v_mfma_f32_16x16x32_bf16 v[80:83], v[214:217], v[180:183], v[80:83]
	v_mfma_f32_16x16x32_bf16 v[68:71], v[206:209], v[198:201], v[68:71]
	v_mfma_f32_16x16x32_bf16 v[64:67], v[214:217], v[198:201], v[64:67]
	s_mov_b32 m0, s28
	v_lshl_add_u64 v[220:221], s[20:21], 0, v[152:153]
	s_barrier
	ds_read_b128 v[144:147], v191 offset:16384
	ds_read_b128 v[148:151], v191 offset:17408
	ds_read_b128 v[168:171], v191 offset:18432
	ds_read_b128 v[172:175], v191 offset:19456
	ds_read_b128 v[176:179], v191 offset:20480
	ds_read_b128 v[180:183], v191 offset:21504
	ds_read_b128 v[194:197], v191 offset:22528
	ds_read_b128 v[198:201], v191 offset:23552
	global_load_lds_dwordx4 v[220:221], off
	v_lshl_add_u64 v[222:223], s[20:21], 0, v[156:157]
	s_mov_b32 m0, s29
	s_nop 0
	global_load_lds_dwordx4 v[222:223], off
	s_barrier
	s_waitcnt lgkmcnt(0)
	s_waitcnt lgkmcnt(0)
	v_mfma_f32_16x16x32_bf16 v[60:63], v[128:131], v[144:147], v[60:63]
	v_mfma_f32_16x16x32_bf16 v[56:59], v[136:139], v[144:147], v[56:59]
	v_mfma_f32_16x16x32_bf16 v[44:47], v[128:131], v[168:171], v[44:47]
	v_mfma_f32_16x16x32_bf16 v[40:43], v[136:139], v[168:171], v[40:43]
	v_mfma_f32_16x16x32_bf16 v[28:31], v[128:131], v[176:179], v[28:31]
	v_mfma_f32_16x16x32_bf16 v[24:27], v[136:139], v[176:179], v[24:27]
	v_mfma_f32_16x16x32_bf16 v[12:15], v[128:131], v[194:197], v[12:15]
	v_mfma_f32_16x16x32_bf16 v[8:11], v[136:139], v[194:197], v[8:11]
	v_mfma_f32_16x16x32_bf16 v[60:63], v[132:135], v[148:151], v[60:63]
	v_mfma_f32_16x16x32_bf16 v[56:59], v[140:143], v[148:151], v[56:59]
	v_mfma_f32_16x16x32_bf16 v[44:47], v[132:135], v[172:175], v[44:47]
	v_mfma_f32_16x16x32_bf16 v[40:43], v[140:143], v[172:175], v[40:43]
	v_mfma_f32_16x16x32_bf16 v[28:31], v[132:135], v[180:183], v[28:31]
	v_mfma_f32_16x16x32_bf16 v[24:27], v[140:143], v[180:183], v[24:27]
	v_mfma_f32_16x16x32_bf16 v[12:15], v[132:135], v[198:201], v[12:15]
	v_mfma_f32_16x16x32_bf16 v[8:11], v[140:143], v[198:201], v[8:11]
	s_barrier
	s_add_u32 s14, s18, 0xb0000
	s_addc_u32 s15, s19, 0
	s_add_i32 s48, s40, s27
	v_lshl_add_u64 v[128:129], s[14:15], 0, v[154:155]
	s_mov_b32 m0, s48
	s_nop 0
	global_load_lds_dwordx4 v[128:129], off
	v_lshl_add_u64 v[128:129], s[14:15], 0, v[158:159]
	s_add_i32 m0, s48, 0x2000
	s_nop 0
	global_load_lds_dwordx4 v[128:129], off
	s_waitcnt vmcnt(6)
	s_barrier
	v_mfma_f32_16x16x32_bf16 v[52:55], v[202:205], v[144:147], v[52:55]
	v_mfma_f32_16x16x32_bf16 v[48:51], v[210:213], v[144:147], v[48:51]
	v_mfma_f32_16x16x32_bf16 v[36:39], v[202:205], v[168:171], v[36:39]
	v_mfma_f32_16x16x32_bf16 v[32:35], v[210:213], v[168:171], v[32:35]
	v_mfma_f32_16x16x32_bf16 v[20:23], v[202:205], v[176:179], v[20:23]
	v_mfma_f32_16x16x32_bf16 v[16:19], v[210:213], v[176:179], v[16:19]
	v_mfma_f32_16x16x32_bf16 v[4:7], v[202:205], v[194:197], v[4:7]
	v_mfma_f32_16x16x32_bf16 v[0:3], v[210:213], v[194:197], v[0:3]
	v_mfma_f32_16x16x32_bf16 v[52:55], v[206:209], v[148:151], v[52:55]
	v_mfma_f32_16x16x32_bf16 v[48:51], v[214:217], v[148:151], v[48:51]
	v_mfma_f32_16x16x32_bf16 v[36:39], v[206:209], v[172:175], v[36:39]
	v_mfma_f32_16x16x32_bf16 v[32:35], v[214:217], v[172:175], v[32:35]
	v_mfma_f32_16x16x32_bf16 v[20:23], v[206:209], v[180:183], v[20:23]
	v_mfma_f32_16x16x32_bf16 v[16:19], v[214:217], v[180:183], v[16:19]
	v_mfma_f32_16x16x32_bf16 v[4:7], v[206:209], v[198:201], v[4:7]
	v_mfma_f32_16x16x32_bf16 v[0:3], v[214:217], v[198:201], v[0:3]
	s_add_i32 s48, 0, 0x18000
	v_add_u32_e32 v140, s48, v187
	s_barrier
	ds_read_b128 v[128:131], v140
	ds_read_b128 v[132:135], v140 offset:1024
	ds_read_b128 v[136:139], v140 offset:2048
	ds_read_b128 v[140:143], v140 offset:3072
	s_add_u32 s14, s20, 0xb0000
	s_addc_u32 s15, s21, 0
	s_mov_b32 m0, s30
	v_lshl_add_u64 v[202:203], s[14:15], 0, v[152:153]
	ds_read_b128 v[144:147], v191 offset:32768
	ds_read_b128 v[148:151], v191 offset:33792
	ds_read_b128 v[168:171], v191 offset:34816
	ds_read_b128 v[172:175], v191 offset:35840
	ds_read_b128 v[176:179], v191 offset:36864
	ds_read_b128 v[180:183], v191 offset:37888
	ds_read_b128 v[194:197], v191 offset:38912
	ds_read_b128 v[198:201], v191 offset:39936
	global_load_lds_dwordx4 v[202:203], off
	v_lshl_add_u64 v[202:203], s[14:15], 0, v[156:157]
	s_mov_b32 m0, s31
	s_nop 0
	global_load_lds_dwordx4 v[202:203], off
	s_waitcnt lgkmcnt(8)
	s_barrier
	s_waitcnt lgkmcnt(0)
	s_waitcnt lgkmcnt(0)
	v_mfma_f32_16x16x32_bf16 v[124:127], v[128:131], v[144:147], v[124:127]
	v_mfma_f32_16x16x32_bf16 v[120:123], v[136:139], v[144:147], v[120:123]
	v_mfma_f32_16x16x32_bf16 v[108:111], v[128:131], v[168:171], v[108:111]
	v_mfma_f32_16x16x32_bf16 v[104:107], v[136:139], v[168:171], v[104:107]
	v_mfma_f32_16x16x32_bf16 v[92:95], v[128:131], v[176:179], v[92:95]
	v_mfma_f32_16x16x32_bf16 v[88:91], v[136:139], v[176:179], v[88:91]
	v_mfma_f32_16x16x32_bf16 v[76:79], v[128:131], v[194:197], v[76:79]
	v_mfma_f32_16x16x32_bf16 v[72:75], v[136:139], v[194:197], v[72:75]
	v_mfma_f32_16x16x32_bf16 v[124:127], v[132:135], v[148:151], v[124:127]
	v_mfma_f32_16x16x32_bf16 v[120:123], v[140:143], v[148:151], v[120:123]
	v_mfma_f32_16x16x32_bf16 v[108:111], v[132:135], v[172:175], v[108:111]
	v_mfma_f32_16x16x32_bf16 v[104:107], v[140:143], v[172:175], v[104:107]
	v_mfma_f32_16x16x32_bf16 v[92:95], v[132:135], v[180:183], v[92:95]
	v_mfma_f32_16x16x32_bf16 v[88:91], v[140:143], v[180:183], v[88:91]
	v_mfma_f32_16x16x32_bf16 v[76:79], v[132:135], v[198:201], v[76:79]
	v_mfma_f32_16x16x32_bf16 v[72:75], v[140:143], v[198:201], v[72:75]
	s_barrier
	s_add_i32 s20, 0, 0x1c000
	s_add_i32 s14, s48, s27
	v_add_u32_e32 v214, s20, v187
	v_lshl_add_u64 v[184:185], v[184:185], 0, s[12:13]
	s_mov_b32 m0, s14
	ds_read_b128 v[202:205], v214
	ds_read_b128 v[206:209], v214 offset:1024
	ds_read_b128 v[210:213], v214 offset:2048
	ds_read_b128 v[214:217], v214 offset:3072
	global_load_lds_dwordx4 v[184:185], off
	v_lshl_add_u64 v[184:185], v[218:219], 0, s[12:13]
	s_add_i32 m0, s14, 0x2000
	s_nop 0
	global_load_lds_dwordx4 v[184:185], off
	s_barrier
	s_waitcnt lgkmcnt(0)
	s_waitcnt lgkmcnt(0)
	v_mfma_f32_16x16x32_bf16 v[116:119], v[202:205], v[144:147], v[116:119]
	v_mfma_f32_16x16x32_bf16 v[112:115], v[210:213], v[144:147], v[112:115]
	v_mfma_f32_16x16x32_bf16 v[100:103], v[202:205], v[168:171], v[100:103]
	v_mfma_f32_16x16x32_bf16 v[96:99], v[210:213], v[168:171], v[96:99]
	v_mfma_f32_16x16x32_bf16 v[84:87], v[202:205], v[176:179], v[84:87]
	v_mfma_f32_16x16x32_bf16 v[80:83], v[210:213], v[176:179], v[80:83]
	v_mfma_f32_16x16x32_bf16 v[68:71], v[202:205], v[194:197], v[68:71]
	v_mfma_f32_16x16x32_bf16 v[64:67], v[210:213], v[194:197], v[64:67]
	v_mfma_f32_16x16x32_bf16 v[116:119], v[206:209], v[148:151], v[116:119]
	v_mfma_f32_16x16x32_bf16 v[112:115], v[214:217], v[148:151], v[112:115]
	v_mfma_f32_16x16x32_bf16 v[100:103], v[206:209], v[172:175], v[100:103]
	v_mfma_f32_16x16x32_bf16 v[96:99], v[214:217], v[172:175], v[96:99]
	v_mfma_f32_16x16x32_bf16 v[84:87], v[206:209], v[180:183], v[84:87]
	v_mfma_f32_16x16x32_bf16 v[80:83], v[214:217], v[180:183], v[80:83]
	v_mfma_f32_16x16x32_bf16 v[68:71], v[206:209], v[198:201], v[68:71]
	v_mfma_f32_16x16x32_bf16 v[64:67], v[214:217], v[198:201], v[64:67]
	s_mov_b32 m0, s35
	v_lshl_add_u64 v[184:185], v[220:221], 0, s[12:13]
	s_barrier
	ds_read_b128 v[144:147], v191 offset:49152
	ds_read_b128 v[148:151], v191 offset:50176
	ds_read_b128 v[168:171], v191 offset:51200
	ds_read_b128 v[172:175], v191 offset:52224
	ds_read_b128 v[176:179], v191 offset:53248
	ds_read_b128 v[180:183], v191 offset:54272
	ds_read_b128 v[194:197], v191 offset:55296
	ds_read_b128 v[198:201], v191 offset:56320
	global_load_lds_dwordx4 v[184:185], off
	v_lshl_add_u64 v[184:185], v[222:223], 0, s[12:13]
	s_mov_b32 m0, s36
	s_nop 0
	global_load_lds_dwordx4 v[184:185], off
	s_barrier
	s_waitcnt lgkmcnt(0)
	s_waitcnt lgkmcnt(0)
	v_mfma_f32_16x16x32_bf16 v[60:63], v[128:131], v[144:147], v[60:63]
	v_mfma_f32_16x16x32_bf16 v[56:59], v[136:139], v[144:147], v[56:59]
	v_mfma_f32_16x16x32_bf16 v[44:47], v[128:131], v[168:171], v[44:47]
	v_mfma_f32_16x16x32_bf16 v[40:43], v[136:139], v[168:171], v[40:43]
	v_mfma_f32_16x16x32_bf16 v[28:31], v[128:131], v[176:179], v[28:31]
	v_mfma_f32_16x16x32_bf16 v[24:27], v[136:139], v[176:179], v[24:27]
	v_mfma_f32_16x16x32_bf16 v[12:15], v[128:131], v[194:197], v[12:15]
	v_mfma_f32_16x16x32_bf16 v[8:11], v[136:139], v[194:197], v[8:11]
	v_mfma_f32_16x16x32_bf16 v[60:63], v[132:135], v[148:151], v[60:63]
	v_mfma_f32_16x16x32_bf16 v[56:59], v[140:143], v[148:151], v[56:59]
	v_mfma_f32_16x16x32_bf16 v[44:47], v[132:135], v[172:175], v[44:47]
	v_mfma_f32_16x16x32_bf16 v[40:43], v[140:143], v[172:175], v[40:43]
	v_mfma_f32_16x16x32_bf16 v[28:31], v[132:135], v[180:183], v[28:31]
	v_mfma_f32_16x16x32_bf16 v[24:27], v[140:143], v[180:183], v[24:27]
	v_mfma_f32_16x16x32_bf16 v[12:15], v[132:135], v[198:201], v[12:15]
	v_mfma_f32_16x16x32_bf16 v[8:11], v[140:143], v[198:201], v[8:11]
	s_barrier
	s_add_u32 s14, s18, 0xb0080
	s_addc_u32 s15, s19, 0
	s_add_i32 s18, s20, s27
	v_lshl_add_u64 v[128:129], s[14:15], 0, v[154:155]
	s_mov_b32 m0, s18
	s_nop 0
	global_load_lds_dwordx4 v[128:129], off
	v_lshl_add_u64 v[128:129], s[14:15], 0, v[158:159]
	s_add_i32 m0, s18, 0x2000
	s_nop 0
	global_load_lds_dwordx4 v[128:129], off
	s_waitcnt vmcnt(6)
	s_barrier
	v_mfma_f32_16x16x32_bf16 v[52:55], v[202:205], v[144:147], v[52:55]
	v_mfma_f32_16x16x32_bf16 v[48:51], v[210:213], v[144:147], v[48:51]
	v_mfma_f32_16x16x32_bf16 v[36:39], v[202:205], v[168:171], v[36:39]
	v_mfma_f32_16x16x32_bf16 v[32:35], v[210:213], v[168:171], v[32:35]
	v_mfma_f32_16x16x32_bf16 v[20:23], v[202:205], v[176:179], v[20:23]
	v_mfma_f32_16x16x32_bf16 v[16:19], v[210:213], v[176:179], v[16:19]
	v_mfma_f32_16x16x32_bf16 v[4:7], v[202:205], v[194:197], v[4:7]
	v_mfma_f32_16x16x32_bf16 v[0:3], v[210:213], v[194:197], v[0:3]
	v_mfma_f32_16x16x32_bf16 v[52:55], v[206:209], v[148:151], v[52:55]
	v_mfma_f32_16x16x32_bf16 v[48:51], v[214:217], v[148:151], v[48:51]
	v_mfma_f32_16x16x32_bf16 v[36:39], v[206:209], v[172:175], v[36:39]
	v_mfma_f32_16x16x32_bf16 v[32:35], v[214:217], v[172:175], v[32:35]
	v_mfma_f32_16x16x32_bf16 v[20:23], v[206:209], v[180:183], v[20:23]
	v_mfma_f32_16x16x32_bf16 v[16:19], v[214:217], v[180:183], v[16:19]
	v_mfma_f32_16x16x32_bf16 v[4:7], v[206:209], v[198:201], v[4:7]
	v_mfma_f32_16x16x32_bf16 v[0:3], v[214:217], v[198:201], v[0:3]
	s_add_i32 s47, s47, 2
	s_add_u32 s45, s45, 0x100
	s_addc_u32 s46, s46, 0
	s_cmp_gt_u32 s47, 41
	s_mov_b64 s[14:15], s[16:17]
	s_barrier
	s_cbranch_scc0 .LBB0_1741
	v_lshl_or_b32 v168, s10, 8, v189
	v_lshl_add_u32 v170, s44, 8, v186
	v_ashrrev_i32_e32 v169, 31, v168
	v_lshlrev_b64 v[202:203], 1, v[168:169]
	v_ashrrev_i32_e32 v171, 31, v170
	v_or_b32_e32 v182, 16, v170
	v_lshl_add_u64 v[172:173], s[64:65], 0, v[202:203]
	v_lshlrev_b64 v[204:205], 11, v[170:171]
	v_ashrrev_i32_e32 v183, 31, v182
	v_or_b32_e32 v178, 32, v170
	v_lshl_add_u64 v[128:129], v[172:173], 0, v[204:205]
	v_lshlrev_b64 v[184:185], 11, v[182:183]
	v_ashrrev_i32_e32 v179, 31, v178
	v_or_b32_e32 v174, 48, v170
	global_load_dwordx4 v[194:197], v[128:129], off
	global_load_dwordx4 v[198:201], v[128:129], off offset:256
	v_lshl_add_u64 v[128:129], v[172:173], 0, v[184:185]
	v_lshlrev_b64 v[180:181], 11, v[178:179]
	v_ashrrev_i32_e32 v175, 31, v174
	global_load_dwordx4 v[148:151], v[128:129], off
	global_load_dwordx4 v[144:147], v[128:129], off offset:256
	v_lshl_add_u64 v[128:129], v[172:173], 0, v[180:181]
	v_lshlrev_b64 v[176:177], 11, v[174:175]
	global_load_dwordx4 v[140:143], v[128:129], off
	global_load_dwordx4 v[136:139], v[128:129], off offset:256
	v_lshl_add_u64 v[128:129], v[172:173], 0, v[176:177]
	global_load_dwordx4 v[132:135], v[128:129], off
	s_nop 0
	global_load_dwordx4 v[128:131], v[128:129], off offset:256
	s_lshl_b32 s14, s10, 2
	s_ashr_i32 s15, s14, 31
	v_add_u32_e32 v252, 0x80, v170
	v_ashrrev_i32_e32 v253, 31, v252
	v_lshlrev_b64 v[252:253], 11, v[252:253]
	v_lshl_add_u64 v[252:253], v[172:173], 0, v[252:253]
	global_load_dwordx4 v[236:239], v[252:253], off
	global_load_dwordx4 v[240:243], v[252:253], off offset:256
	v_add_u32_e32 v252, 0x90, v170
	v_ashrrev_i32_e32 v253, 31, v252
	v_lshlrev_b64 v[252:253], 11, v[252:253]
	v_lshl_add_u64 v[252:253], v[172:173], 0, v[252:253]
	global_load_dwordx4 v[244:247], v[252:253], off
	global_load_dwordx4 v[248:251], v[252:253], off offset:256
	v_add_u32_e32 v252, 0xa0, v170
	v_ashrrev_i32_e32 v253, 31, v252
	v_lshlrev_b64 v[252:253], 11, v[252:253]
	v_lshl_add_u64 v[252:253], v[172:173], 0, v[252:253]
	global_load_dwordx4 v[210:213], v[252:253], off
	global_load_dwordx4 v[214:217], v[252:253], off offset:256
	s_waitcnt vmcnt(6)
	v_lshlrev_b32_e32 v206, 16, v194
	v_and_b32_e32 v207, 0xffff0000, v194
	v_lshlrev_b32_e32 v194, 16, v195
	v_and_b32_e32 v195, 0xffff0000, v195
	v_lshlrev_b32_e32 v208, 16, v196
	v_and_b32_e32 v209, 0xffff0000, v196
	v_lshlrev_b32_e32 v196, 16, v197
	v_and_b32_e32 v197, 0xffff0000, v197
	v_pk_add_f32 v[126:127], v[126:127], v[194:195]
	v_pk_add_f32 v[124:125], v[124:125], v[206:207]
	v_pk_add_f32 v[194:195], v[122:123], v[196:197]
	v_pk_add_f32 v[122:123], v[120:121], v[208:209]
	v_mul_f32_e32 v120, v125, v125
	v_mul_f32_e32 v121, v127, v127
	v_fmac_f32_e32 v120, v124, v124
	v_fmac_f32_e32 v121, v126, v126
	v_add_f32_e32 v120, v120, v121
	v_mul_f32_e32 v121, v123, v123
	v_mul_f32_e32 v196, v195, v195
	v_fmac_f32_e32 v121, v122, v122
	v_fmac_f32_e32 v196, v194, v194
	v_add_f32_e32 v121, v121, v196
	v_add_f32_e32 v206, v120, v121
	v_cvt_pk_bf16_f32 v120, v124, v125
	v_cvt_pk_bf16_f32 v121, v126, v127
	v_lshlrev_b32_e32 v124, 16, v198
	v_and_b32_e32 v125, 0xffff0000, v198
	v_lshlrev_b32_e32 v126, 16, v199
	v_and_b32_e32 v127, 0xffff0000, v199
	v_cvt_pk_bf16_f32 v122, v122, v123
	v_cvt_pk_bf16_f32 v123, v194, v195
	v_lshlrev_b32_e32 v194, 16, v200
	v_and_b32_e32 v195, 0xffff0000, v200
	v_pk_add_f32 v[118:119], v[118:119], v[126:127]
	v_pk_add_f32 v[116:117], v[116:117], v[124:125]
	v_lshlrev_b32_e32 v196, 16, v201
	v_and_b32_e32 v197, 0xffff0000, v201
	v_pk_add_f32 v[126:127], v[112:113], v[194:195]
	v_mul_f32_e32 v112, v117, v117
	v_mul_f32_e32 v113, v119, v119
	v_pk_add_f32 v[124:125], v[114:115], v[196:197]
	v_fmac_f32_e32 v112, v116, v116
	v_fmac_f32_e32 v113, v118, v118
	v_add_f32_e32 v112, v112, v113
	v_mul_f32_e32 v113, v127, v127
	v_mul_f32_e32 v114, v125, v125
	v_fmac_f32_e32 v113, v126, v126
	v_fmac_f32_e32 v114, v124, v124
	v_add_f32_e32 v113, v113, v114
	v_add_f32_e32 v112, v112, v113
	v_and_b32_e32 v114, 64, v193
	v_add_f32_e32 v113, v206, v112
	v_xor_b32_e32 v112, 16, v193
	v_add_u32_e32 v196, 64, v114
	v_cmp_lt_i32_e32 vcc, v112, v196
	v_lshl_add_u64 v[114:115], s[64:65], 0, v[204:205]
	v_lshl_add_u64 v[194:195], v[114:115], 0, v[202:203]
	v_cndmask_b32_e32 v112, v193, v112, vcc
	v_lshlrev_b32_e32 v112, 2, v112
	ds_bpermute_b32 v197, v112, v113
	global_store_dwordx4 v[194:195], v[120:123], off
	v_cvt_pk_bf16_f32 v116, v116, v117
	v_cvt_pk_bf16_f32 v117, v118, v119
	v_cvt_pk_bf16_f32 v118, v126, v127
	s_waitcnt lgkmcnt(0)
	v_add_f32_e32 v114, v113, v197
	v_xor_b32_e32 v113, 32, v193
	v_cmp_lt_i32_e32 vcc, v113, v196
	v_cvt_pk_bf16_f32 v119, v124, v125
	global_store_dwordx4 v[194:195], v[116:119], off offset:256
	s_nop 0
	v_cndmask_b32_e32 v113, v193, v113, vcc
	v_lshlrev_b32_e32 v113, 2, v113
	ds_bpermute_b32 v115, v113, v114
	s_and_saveexec_b64 s[16:17], s[2:3]
	s_cbranch_execz .LBB0_1744
	s_waitcnt lgkmcnt(0)
	v_add_f32_e32 v116, v114, v115
	v_lshlrev_b64 v[114:115], 6, v[170:171]
	v_lshl_add_u64 v[114:115], s[74:75], 0, v[114:115]
	v_lshl_add_u64 v[114:115], s[14:15], 2, v[114:115]
	s_lshl_b32 s10, s34, 2
	v_lshl_add_u64 v[114:115], v[114:115], 0, s[10:11]
	global_store_dword v[114:115], v116, off
